# v52 plus residual epilogue of the w_out and down phases: second half's loads issued together with the first half's
# baseline (speedup 1.0000x reference)
; __device__ __forceinline__ float sq4(f32x4 v) { return (v[0] * v[0] + v[1] * v[1]) + (v[2] * v[2] + v[3] * v[3]); }
; __device__ __forceinline__ u32x4 pack8(f32x4 a, f32x4 b) { u32x4 w; w.x = cvt_pk_bf16(a[0], a[1]); w.y = cvt_pk_bf16(a[2], a[3]); w.z = cvt_pk_bf16(b[0], b[1]); w.w = cvt_pk_bf16(b[2], b[3]); return w; }
;     __device__ __forceinline__ void operator()(const f32x4 (&acc)[2][2][4][2], const Unit& u, int wr, int wc, int fr, int fq) const {
;         const int col0 = u.pn * 256 + 32 * wc + 8 * fq;
; #pragma unroll
;         for (int ai = 0; ai < 2; ++ai) {
;             u32x4 bs[4][2];
; #pragma unroll
;             for (int m = 0; m < 4; ++m)
; #pragma unroll
;                 for (int bj = 0; bj < 2; ++bj) bs[m][bj] = *(const u32x4*)(xb + (size_t)(u.pm * BM + ai * HALF + wr * 64 + m * 16 + fr) * 1024 + col0 + 128 * bj);
; #pragma unroll
;             for (int m = 0; m < 4; ++m) {
;                 const int row = u.pm * BM + ai * HALF + wr * 64 + m * 16 + fr;
;                 float q = 0.f;
; #pragma unroll
;                 for (int bj = 0; bj < 2; ++bj) {
;                     const size_t off = (size_t)row * 1024 + col0 + 128 * bj; const u32x4 w = bs[m][bj];
;                     const f32x4 b0 = (f32x4){__builtin_bit_cast(float, w.x << 16), __builtin_bit_cast(float, w.x & 0xffff0000u), __builtin_bit_cast(float, w.y << 16), __builtin_bit_cast(float, w.y & 0xffff0000u)};
;                     const f32x4 b1 = (f32x4){__builtin_bit_cast(float, w.z << 16), __builtin_bit_cast(float, w.z & 0xffff0000u), __builtin_bit_cast(float, w.w << 16), __builtin_bit_cast(float, w.w & 0xffff0000u)};
;                     const f32x4 v0 = acc[ai][bj][m][0] + b0, v1 = acc[ai][bj][m][1] + b1;
;                     if (last) { __builtin_nontemporal_store(v0, (f32x4*)(out + off)); __builtin_nontemporal_store(v1, (f32x4*)(out + off + 4)); }
;                     else { q += sq4(v0) + sq4(v1); *(u32x4*)(xb + off) = pack8(v0, v1); }
;                 }
;                 if (!last) { q += shx(q, 16); q += shx(q, 32); if (fq == 0) ss[(size_t)row * 16 + u.pn * 4 + wc] = q; }
.LBB0_439:
	v_lshl_or_b32 v168, s14, 8, v188
	v_lshl_add_u32 v172, s42, 8, v186
	v_ashrrev_i32_e32 v169, 31, v168
	v_lshlrev_b64 v[202:203], 1, v[168:169]
	v_ashrrev_i32_e32 v173, 31, v172
	v_lshl_add_u64 v[170:171], s[18:19], 0, v[202:203]
	v_lshlrev_b64 v[204:205], 11, v[172:173]
	v_lshl_add_u64 v[128:129], v[170:171], 0, v[204:205]
	global_load_dwordx4 v[192:195], v[128:129], off
	global_load_dwordx4 v[196:199], v[128:129], off offset:256
	v_or_b32_e32 v182, 16, v172
	v_or_b32_e32 v178, 32, v172
	v_or_b32_e32 v174, 48, v172
	v_ashrrev_i32_e32 v183, 31, v182
	v_ashrrev_i32_e32 v179, 31, v178
	v_ashrrev_i32_e32 v175, 31, v174
	v_lshlrev_b64 v[184:185], 11, v[182:183]
	v_lshlrev_b64 v[180:181], 11, v[178:179]
	v_lshlrev_b64 v[176:177], 11, v[174:175]
	v_lshl_add_u64 v[128:129], v[170:171], 0, v[184:185]
	v_lshl_add_u64 v[130:131], v[170:171], 0, v[180:181]
	v_lshl_add_u64 v[206:207], v[170:171], 0, v[176:177]
	global_load_dwordx4 v[148:151], v[128:129], off
	global_load_dwordx4 v[144:147], v[128:129], off offset:256
	global_load_dwordx4 v[140:143], v[130:131], off
	global_load_dwordx4 v[136:139], v[130:131], off offset:256
	global_load_dwordx4 v[132:135], v[206:207], off
	s_nop 0
	global_load_dwordx4 v[128:131], v[206:207], off offset:256
	v_add_u32_e32 v244, 0x80, v172
	v_ashrrev_i32_e32 v245, 31, v244
	v_lshlrev_b64 v[244:245], 11, v[244:245]
	v_lshl_add_u64 v[244:245], v[170:171], 0, v[244:245]
	global_load_dwordx4 v[212:215], v[244:245], off
	global_load_dwordx4 v[216:219], v[244:245], off offset:256
	v_add_u32_e32 v244, 0x90, v172
	v_ashrrev_i32_e32 v245, 31, v244
	v_lshlrev_b64 v[244:245], 11, v[244:245]
	v_lshl_add_u64 v[244:245], v[170:171], 0, v[244:245]
	global_load_dwordx4 v[220:223], v[244:245], off
	global_load_dwordx4 v[224:227], v[244:245], off offset:256
	v_add_u32_e32 v244, 0xa0, v172
	v_ashrrev_i32_e32 v245, 31, v244
	v_lshlrev_b64 v[244:245], 11, v[244:245]
	v_lshl_add_u64 v[244:245], v[170:171], 0, v[244:245]
	global_load_dwordx4 v[228:231], v[244:245], off
	global_load_dwordx4 v[232:235], v[244:245], off offset:256
	v_add_u32_e32 v244, 0xb0, v172
	v_ashrrev_i32_e32 v245, 31, v244
	v_lshlrev_b64 v[244:245], 11, v[244:245]
	v_lshl_add_u64 v[244:245], v[170:171], 0, v[244:245]
	global_load_dwordx4 v[236:239], v[244:245], off
	global_load_dwordx4 v[240:243], v[244:245], off offset:256
	v_lshl_add_u64 v[204:205], s[18:19], 0, v[204:205]
	v_lshl_add_u64 v[202:203], v[204:205], 0, v[202:203]
	v_mov_b32_e32 v200, v201
	s_lshl_b32 s42, s14, 2
	s_ashr_i32 s43, s42, 31
	s_waitcnt vmcnt(8)
	v_lshlrev_b32_e32 v204, 16, v192
	v_and_b32_e32 v205, 0xffff0000, v192
	v_lshlrev_b32_e32 v192, 16, v193
	v_and_b32_e32 v193, 0xffff0000, v193
	v_lshlrev_b32_e32 v206, 16, v194
	v_and_b32_e32 v207, 0xffff0000, v194
	v_lshlrev_b32_e32 v194, 16, v195
	v_and_b32_e32 v195, 0xffff0000, v195
	v_lshlrev_b32_e32 v208, 16, v196
	v_and_b32_e32 v209, 0xffff0000, v196
	v_lshlrev_b32_e32 v196, 16, v197
	v_and_b32_e32 v197, 0xffff0000, v197
	v_lshlrev_b32_e32 v210, 16, v198
	v_and_b32_e32 v211, 0xffff0000, v198
	v_lshlrev_b32_e32 v198, 16, v199
	v_and_b32_e32 v199, 0xffff0000, v199
	v_pk_add_f32 v[126:127], v[126:127], v[192:193]
	v_pk_add_f32 v[124:125], v[124:125], v[204:205]
	v_pk_add_f32 v[122:123], v[122:123], v[194:195]
	v_pk_add_f32 v[120:121], v[120:121], v[206:207]
	v_pk_add_f32 v[118:119], v[118:119], v[196:197]
	v_pk_add_f32 v[116:117], v[116:117], v[208:209]
	v_pk_add_f32 v[192:193], v[114:115], v[198:199]
	v_pk_add_f32 v[194:195], v[112:113], v[210:211]
	v_mul_f32_e32 v196, v125, v125
	v_mul_f32_e32 v197, v127, v127
	v_mul_f32_e32 v198, v121, v121
	v_mul_f32_e32 v199, v123, v123
	v_cvt_pk_bf16_f32 v112, v124, v125
	v_cvt_pk_bf16_f32 v113, v126, v127
	v_cvt_pk_bf16_f32 v114, v120, v121
	v_cvt_pk_bf16_f32 v115, v122, v123
	v_mul_f32_e32 v121, v117, v117
	v_mul_f32_e32 v123, v119, v119
	v_mul_f32_e32 v125, v195, v195
	v_mul_f32_e32 v127, v193, v193
	v_fmac_f32_e32 v196, v124, v124
	v_fmac_f32_e32 v197, v126, v126
	v_fmac_f32_e32 v198, v120, v120
	v_fmac_f32_e32 v199, v122, v122
	v_fmac_f32_e32 v121, v116, v116
	v_fmac_f32_e32 v123, v118, v118
	v_fmac_f32_e32 v125, v194, v194
	v_fmac_f32_e32 v127, v192, v192
	global_store_dwordx4 v[202:203], v[112:115], off
	s_nop 1
	v_cvt_pk_bf16_f32 v112, v116, v117
	v_cvt_pk_bf16_f32 v113, v118, v119
	v_cvt_pk_bf16_f32 v114, v194, v195
	v_add_f32_e32 v116, v196, v197
	v_add_f32_e32 v117, v198, v199
	v_add_f32_e32 v118, v121, v123
	v_add_f32_e32 v119, v125, v127
	v_cvt_pk_bf16_f32 v115, v192, v193
	global_store_dwordx4 v[202:203], v[112:115], off offset:256
	s_nop 1
	v_add_f32_e32 v112, v116, v117
	v_add_f32_e32 v113, v118, v119
	v_lshlrev_b32_e32 v114, 2, v200
	v_add_f32_e32 v112, v112, v113
	v_xor_b32_e32 v113, 64, v114
	v_mov_b32_e32 v113, v112
	s_nop 1
	v_permlane16_swap_b32_e32 v113, v112
	v_mov_b32_e32 v114, v201
	s_waitcnt lgkmcnt(0)
	v_add_f32_e32 v112, v112, v113
	v_lshlrev_b32_e32 v114, 2, v114
	v_xor_b32_e32 v113, 0x80, v114
	v_mov_b32_e32 v113, v112
	s_nop 1
	v_permlane32_swap_b32_e32 v113, v112
	s_and_saveexec_b64 s[44:45], s[10:11]
	s_cbranch_execz .LBB0_441
	s_waitcnt lgkmcnt(0)
	v_add_f32_e32 v114, v112, v113
	v_lshlrev_b64 v[112:113], 6, v[172:173]
	v_lshl_add_u64 v[112:113], s[22:23], 0, v[112:113]
	v_lshl_add_u64 v[112:113], s[42:43], 2, v[112:113]
	s_lshl_b32 s14, s52, 2
	v_lshl_add_u64 v[112:113], v[112:113], 0, s[14:15]
	global_store_dword v[112:113], v114, off

; __device__ __forceinline__ float sq4(f32x4 v) { return (v[0] * v[0] + v[1] * v[1]) + (v[2] * v[2] + v[3] * v[3]); }
; __device__ __forceinline__ u32x4 pack8(f32x4 a, f32x4 b) { u32x4 w; w.x = cvt_pk_bf16(a[0], a[1]); w.y = cvt_pk_bf16(a[2], a[3]); w.z = cvt_pk_bf16(b[0], b[1]); w.w = cvt_pk_bf16(b[2], b[3]); return w; }
;     __device__ __forceinline__ void operator()(const f32x4 (&acc)[2][2][4][2], const Unit& u, int wr, int wc, int fr, int fq) const {
;     ...
;         for (int ai = 0; ai < 2; ++ai) {
;             u32x4 bs[4][2];
; #pragma unroll
;             for (int m = 0; m < 4; ++m)
; #pragma unroll
;                 for (int bj = 0; bj < 2; ++bj) bs[m][bj] = *(const u32x4*)(xb + (size_t)(u.pm * BM + ai * HALF + wr * 64 + m * 16 + fr) * 1024 + col0 + 128 * bj);
; #pragma unroll
;             for (int m = 0; m < 4; ++m) {
;                 const int row = u.pm * BM + ai * HALF + wr * 64 + m * 16 + fr;
;                 float q = 0.f;
; #pragma unroll
;                 for (int bj = 0; bj < 2; ++bj) {
;                     const size_t off = (size_t)row * 1024 + col0 + 128 * bj; const u32x4 w = bs[m][bj];
;                     const f32x4 b0 = (f32x4){__builtin_bit_cast(float, w.x << 16), __builtin_bit_cast(float, w.x & 0xffff0000u), __builtin_bit_cast(float, w.y << 16), __builtin_bit_cast(float, w.y & 0xffff0000u)};
;                     const f32x4 b1 = (f32x4){__builtin_bit_cast(float, w.z << 16), __builtin_bit_cast(float, w.z & 0xffff0000u), __builtin_bit_cast(float, w.w << 16), __builtin_bit_cast(float, w.w & 0xffff0000u)};
;                     const f32x4 v0 = acc[ai][bj][m][0] + b0, v1 = acc[ai][bj][m][1] + b1;
;                     if (last) { __builtin_nontemporal_store(v0, (f32x4*)(out + off)); __builtin_nontemporal_store(v1, (f32x4*)(out + off + 4)); }
;                     else { q += sq4(v0) + sq4(v1); *(u32x4*)(xb + off) = pack8(v0, v1); }
;                 }
;                 if (!last) { q += shx(q, 16); q += shx(q, 32); if (fq == 0) ss[(size_t)row * 16 + u.pn * 4 + wc] = q; }
.LBB0_447:
	s_or_b64 exec, exec, s[44:45]
	v_add_u32_e32 v100, 0x80, v172
	v_ashrrev_i32_e32 v101, 31, v100
	v_lshlrev_b64 v[110:111], 11, v[100:101]
	s_waitcnt lgkmcnt(0)
	v_lshl_add_u64 v[64:65], v[170:171], 0, v[110:111]
	s_nop 0
	s_nop 0
	v_add_u32_e32 v96, 0x90, v172
	v_add_u32_e32 v92, 0xa0, v172
	v_add_u32_e32 v88, 0xb0, v172
	v_ashrrev_i32_e32 v97, 31, v96
	v_ashrrev_i32_e32 v93, 31, v92
	v_ashrrev_i32_e32 v89, 31, v88
	v_lshlrev_b64 v[98:99], 11, v[96:97]
	v_lshlrev_b64 v[94:95], 11, v[92:93]
	v_lshlrev_b64 v[90:91], 11, v[88:89]
	v_lshl_add_u64 v[64:65], v[170:171], 0, v[98:99]
	v_lshl_add_u64 v[66:67], v[170:171], 0, v[94:95]
	v_lshl_add_u64 v[112:113], v[170:171], 0, v[90:91]
	s_nop 0
	s_nop 0
	s_nop 0
	s_nop 0
	s_nop 0
	s_nop 0
	s_nop 0
	v_lshl_add_u64 v[110:111], s[18:19], 0, v[110:111]
	v_lshl_add_u64 v[110:111], v[168:169], 1, v[110:111]
	v_mov_b32_e32 v120, v201
	s_waitcnt vmcnt(7)
	v_lshlrev_b32_e32 v112, 16, v212
	v_and_b32_e32 v113, 0xffff0000, v212
	v_lshlrev_b32_e32 v102, 16, v213
	v_and_b32_e32 v103, 0xffff0000, v213
	v_lshlrev_b32_e32 v114, 16, v214
	v_and_b32_e32 v115, 0xffff0000, v214
	v_lshlrev_b32_e32 v104, 16, v215
	v_and_b32_e32 v105, 0xffff0000, v215
	s_waitcnt vmcnt(6)
	v_lshlrev_b32_e32 v116, 16, v216
	v_and_b32_e32 v117, 0xffff0000, v216
	v_lshlrev_b32_e32 v106, 16, v217
	v_and_b32_e32 v107, 0xffff0000, v217
	v_lshlrev_b32_e32 v118, 16, v218
	v_and_b32_e32 v119, 0xffff0000, v218
	v_lshlrev_b32_e32 v108, 16, v219
	v_and_b32_e32 v109, 0xffff0000, v219
	v_pk_add_f32 v[62:63], v[62:63], v[102:103]
	v_pk_add_f32 v[60:61], v[60:61], v[112:113]
	v_pk_add_f32 v[58:59], v[58:59], v[104:105]
	v_pk_add_f32 v[56:57], v[56:57], v[114:115]
	v_pk_add_f32 v[54:55], v[54:55], v[106:107]
	v_pk_add_f32 v[52:53], v[52:53], v[116:117]
	v_pk_add_f32 v[102:103], v[50:51], v[108:109]
	v_pk_add_f32 v[104:105], v[48:49], v[118:119]
	v_mul_f32_e32 v106, v61, v61
	v_mul_f32_e32 v107, v63, v63
	v_mul_f32_e32 v108, v57, v57
	v_mul_f32_e32 v109, v59, v59
	v_cvt_pk_bf16_f32 v48, v60, v61
	v_cvt_pk_bf16_f32 v49, v62, v63
	v_cvt_pk_bf16_f32 v50, v56, v57
	v_cvt_pk_bf16_f32 v51, v58, v59
	v_mul_f32_e32 v57, v53, v53
	v_mul_f32_e32 v59, v55, v55
	v_mul_f32_e32 v61, v105, v105
	v_mul_f32_e32 v63, v103, v103
	v_fmac_f32_e32 v106, v60, v60
	v_fmac_f32_e32 v107, v62, v62
	v_fmac_f32_e32 v108, v56, v56
	v_fmac_f32_e32 v109, v58, v58
	v_fmac_f32_e32 v57, v52, v52
	v_fmac_f32_e32 v59, v54, v54
	v_fmac_f32_e32 v61, v104, v104
	v_fmac_f32_e32 v63, v102, v102
	global_store_dwordx4 v[110:111], v[48:51], off
	s_nop 1
	v_cvt_pk_bf16_f32 v48, v52, v53
	v_cvt_pk_bf16_f32 v49, v54, v55
	v_cvt_pk_bf16_f32 v50, v104, v105
	v_add_f32_e32 v52, v106, v107
	v_add_f32_e32 v53, v108, v109
	v_add_f32_e32 v54, v57, v59
	v_add_f32_e32 v55, v61, v63
	v_cvt_pk_bf16_f32 v51, v102, v103
	global_store_dwordx4 v[110:111], v[48:51], off offset:256
	s_nop 1
	v_add_f32_e32 v48, v52, v53
	v_add_f32_e32 v49, v54, v55
	v_lshlrev_b32_e32 v50, 2, v120
	v_add_f32_e32 v48, v48, v49
	v_xor_b32_e32 v49, 64, v50
	v_mov_b32_e32 v49, v48
	s_nop 1
	v_permlane16_swap_b32_e32 v49, v48
	v_mov_b32_e32 v50, v201
	s_waitcnt lgkmcnt(0)
	v_add_f32_e32 v48, v48, v49
	v_lshlrev_b32_e32 v50, 2, v50
	v_xor_b32_e32 v49, 0x80, v50
	v_mov_b32_e32 v49, v48
	s_nop 1
	v_permlane32_swap_b32_e32 v49, v48
	s_and_saveexec_b64 s[44:45], s[10:11]
	s_cbranch_execz .LBB0_449
	s_waitcnt lgkmcnt(0)
	v_add_f32_e32 v50, v48, v49
	v_lshlrev_b64 v[48:49], 6, v[100:101]
	v_lshl_add_u64 v[48:49], s[22:23], 0, v[48:49]
	v_lshl_add_u64 v[48:49], s[42:43], 2, v[48:49]
	s_lshl_b32 s14, s52, 2
	v_lshl_add_u64 v[48:49], v[48:49], 0, s[14:15]
	global_store_dword v[48:49], v50, off
.LBB0_449:
	s_or_b64 exec, exec, s[44:45]
	s_waitcnt vmcnt(7)
	v_lshlrev_b32_e32 v48, 16, v220
	s_waitcnt lgkmcnt(0)
	v_and_b32_e32 v49, 0xffff0000, v220
	v_lshlrev_b32_e32 v50, 16, v221
	v_and_b32_e32 v51, 0xffff0000, v221
	v_lshlrev_b32_e32 v52, 16, v222
	v_and_b32_e32 v53, 0xffff0000, v222
	v_lshlrev_b32_e32 v54, 16, v223
	v_and_b32_e32 v55, 0xffff0000, v223
	v_pk_add_f32 v[46:47], v[46:47], v[50:51]
	v_pk_add_f32 v[44:45], v[44:45], v[48:49]
	v_pk_add_f32 v[48:49], v[42:43], v[54:55]
	v_pk_add_f32 v[42:43], v[40:41], v[52:53]
	v_mul_f32_e32 v40, v45, v45
	v_mul_f32_e32 v41, v47, v47
	v_fmac_f32_e32 v40, v44, v44
	v_fmac_f32_e32 v41, v46, v46
	v_add_f32_e32 v40, v40, v41
	v_mul_f32_e32 v41, v43, v43
	v_mul_f32_e32 v50, v49, v49
	v_fmac_f32_e32 v41, v42, v42
	v_fmac_f32_e32 v50, v48, v48
	v_add_f32_e32 v41, v41, v50
	v_add_f32_e32 v50, v40, v41
	v_cvt_pk_bf16_f32 v40, v44, v45
	v_lshl_add_u64 v[44:45], s[18:19], 0, v[98:99]
	v_cvt_pk_bf16_f32 v41, v46, v47
	v_cvt_pk_bf16_f32 v42, v42, v43
	v_cvt_pk_bf16_f32 v43, v48, v49
	v_lshl_add_u64 v[44:45], v[168:169], 1, v[44:45]
	global_store_dwordx4 v[44:45], v[40:43], off
	s_waitcnt vmcnt(7)
	v_lshlrev_b32_e32 v46, 16, v226
	v_and_b32_e32 v47, 0xffff0000, v226
	v_lshlrev_b32_e32 v40, 16, v224
	v_and_b32_e32 v41, 0xffff0000, v224
	v_lshlrev_b32_e32 v42, 16, v225
	v_and_b32_e32 v43, 0xffff0000, v225
	v_lshlrev_b32_e32 v48, 16, v227
	v_and_b32_e32 v49, 0xffff0000, v227
	v_pk_add_f32 v[38:39], v[38:39], v[42:43]
	v_pk_add_f32 v[36:37], v[36:37], v[40:41]
	v_pk_add_f32 v[40:41], v[34:35], v[48:49]
	v_pk_add_f32 v[34:35], v[32:33], v[46:47]
	v_mul_f32_e32 v32, v37, v37
	v_mul_f32_e32 v33, v39, v39
	v_fmac_f32_e32 v32, v36, v36
	v_fmac_f32_e32 v33, v38, v38
	v_add_f32_e32 v32, v32, v33
	v_mul_f32_e32 v33, v35, v35
	v_mul_f32_e32 v42, v41, v41
	v_fmac_f32_e32 v33, v34, v34
	v_fmac_f32_e32 v42, v40, v40
	v_add_f32_e32 v33, v33, v42
	v_add_f32_e32 v32, v32, v33
	v_add_f32_e32 v42, v50, v32
	v_cvt_pk_bf16_f32 v32, v36, v37
	v_cvt_pk_bf16_f32 v33, v38, v39
	v_cvt_pk_bf16_f32 v34, v34, v35
	v_cvt_pk_bf16_f32 v35, v40, v41
	global_store_dwordx4 v[44:45], v[32:35], off offset:256
	s_nop 1
	v_mov_b32_e32 v32, v201
	v_mov_b32_e32 v33, v201
	v_lshlrev_b32_e32 v32, 2, v32
	v_xor_b32_e32 v32, 64, v32
	v_mov_b32_e32 v32, v42
	s_nop 1
	v_permlane16_swap_b32_e32 v32, v42
	s_waitcnt lgkmcnt(0)
	v_add_f32_e32 v32, v42, v32
	v_lshlrev_b32_e32 v33, 2, v33
	v_xor_b32_e32 v33, 0x80, v33
	v_mov_b32_e32 v33, v32
	s_nop 1
	v_permlane32_swap_b32_e32 v33, v32
	s_and_saveexec_b64 s[44:45], s[10:11]
	s_cbranch_execz .LBB0_451
	s_waitcnt lgkmcnt(0)
	v_add_f32_e32 v34, v32, v33
	v_lshlrev_b64 v[32:33], 6, v[96:97]
	v_lshl_add_u64 v[32:33], s[22:23], 0, v[32:33]
	v_lshl_add_u64 v[32:33], s[42:43], 2, v[32:33]
	s_lshl_b32 s14, s52, 2
	v_lshl_add_u64 v[32:33], v[32:33], 0, s[14:15]
	global_store_dword v[32:33], v34, off
; __device__ __forceinline__ float sq4(f32x4 v) { return (v[0] * v[0] + v[1] * v[1]) + (v[2] * v[2] + v[3] * v[3]); }
; __device__ __forceinline__ u32x4 pack8(f32x4 a, f32x4 b) { u32x4 w; w.x = cvt_pk_bf16(a[0], a[1]); w.y = cvt_pk_bf16(a[2], a[3]); w.z = cvt_pk_bf16(b[0], b[1]); w.w = cvt_pk_bf16(b[2], b[3]); return w; }
;     __device__ __forceinline__ void operator()(const f32x4 (&acc)[2][2][4][2], const Unit& u, int wr, int wc, int fr, int fq) const {
;     ...
;             for (int m = 0; m < 4; ++m) {
;                 const int row = u.pm * BM + ai * HALF + wr * 64 + m * 16 + fr;
;                 float q = 0.f;
; #pragma unroll
;                 for (int bj = 0; bj < 2; ++bj) {
;                     const size_t off = (size_t)row * 1024 + col0 + 128 * bj; const u32x4 w = bs[m][bj];
;                     const f32x4 b0 = (f32x4){__builtin_bit_cast(float, w.x << 16), __builtin_bit_cast(float, w.x & 0xffff0000u), __builtin_bit_cast(float, w.y << 16), __builtin_bit_cast(float, w.y & 0xffff0000u)};
;                     const f32x4 b1 = (f32x4){__builtin_bit_cast(float, w.z << 16), __builtin_bit_cast(float, w.z & 0xffff0000u), __builtin_bit_cast(float, w.w << 16), __builtin_bit_cast(float, w.w & 0xffff0000u)};
;                     const f32x4 v0 = acc[ai][bj][m][0] + b0, v1 = acc[ai][bj][m][1] + b1;
;                     if (last) { __builtin_nontemporal_store(v0, (f32x4*)(out + off)); __builtin_nontemporal_store(v1, (f32x4*)(out + off + 4)); }
;                     else { q += sq4(v0) + sq4(v1); *(u32x4*)(xb + off) = pack8(v0, v1); }
;                 }
;                 if (!last) { q += shx(q, 16); q += shx(q, 32); if (fq == 0) ss[(size_t)row * 16 + u.pn * 4 + wc] = q; }
.LBB0_451:
	s_or_b64 exec, exec, s[44:45]
	s_waitcnt vmcnt(7)
	v_lshlrev_b32_e32 v32, 16, v228
	s_waitcnt lgkmcnt(0)
	v_and_b32_e32 v33, 0xffff0000, v228
	v_lshlrev_b32_e32 v34, 16, v229
	v_and_b32_e32 v35, 0xffff0000, v229
	v_lshlrev_b32_e32 v36, 16, v230
	v_and_b32_e32 v37, 0xffff0000, v230
	v_lshlrev_b32_e32 v38, 16, v231
	v_and_b32_e32 v39, 0xffff0000, v231
	v_pk_add_f32 v[30:31], v[30:31], v[34:35]
	v_pk_add_f32 v[28:29], v[28:29], v[32:33]
	v_pk_add_f32 v[32:33], v[26:27], v[38:39]
	v_pk_add_f32 v[26:27], v[24:25], v[36:37]
	v_mul_f32_e32 v24, v29, v29
	v_mul_f32_e32 v25, v31, v31
	v_fmac_f32_e32 v24, v28, v28
	v_fmac_f32_e32 v25, v30, v30
	v_add_f32_e32 v24, v24, v25
	v_mul_f32_e32 v25, v27, v27
	v_mul_f32_e32 v34, v33, v33
	v_fmac_f32_e32 v25, v26, v26
	v_fmac_f32_e32 v34, v32, v32
	v_add_f32_e32 v25, v25, v34
	v_add_f32_e32 v34, v24, v25
	v_cvt_pk_bf16_f32 v24, v28, v29
	v_lshl_add_u64 v[28:29], s[18:19], 0, v[94:95]
	v_cvt_pk_bf16_f32 v25, v30, v31
	v_cvt_pk_bf16_f32 v26, v26, v27
	v_cvt_pk_bf16_f32 v27, v32, v33
	v_lshl_add_u64 v[28:29], v[168:169], 1, v[28:29]
	global_store_dwordx4 v[28:29], v[24:27], off
	s_waitcnt vmcnt(7)
	v_lshlrev_b32_e32 v30, 16, v234
	v_and_b32_e32 v31, 0xffff0000, v234
	v_lshlrev_b32_e32 v24, 16, v232
	v_and_b32_e32 v25, 0xffff0000, v232
	v_lshlrev_b32_e32 v26, 16, v233
	v_and_b32_e32 v27, 0xffff0000, v233
	v_lshlrev_b32_e32 v32, 16, v235
	v_and_b32_e32 v33, 0xffff0000, v235
	v_pk_add_f32 v[22:23], v[22:23], v[26:27]
	v_pk_add_f32 v[20:21], v[20:21], v[24:25]
	v_pk_add_f32 v[24:25], v[18:19], v[32:33]
	v_pk_add_f32 v[18:19], v[16:17], v[30:31]
	v_mul_f32_e32 v16, v21, v21
	v_mul_f32_e32 v17, v23, v23
	v_fmac_f32_e32 v16, v20, v20
	v_fmac_f32_e32 v17, v22, v22
	v_add_f32_e32 v16, v16, v17
	v_mul_f32_e32 v17, v19, v19
	v_mul_f32_e32 v26, v25, v25
	v_fmac_f32_e32 v17, v18, v18
	v_fmac_f32_e32 v26, v24, v24
	v_add_f32_e32 v17, v17, v26
	v_add_f32_e32 v16, v16, v17
	v_add_f32_e32 v26, v34, v16
	v_cvt_pk_bf16_f32 v16, v20, v21
	v_cvt_pk_bf16_f32 v17, v22, v23
	v_cvt_pk_bf16_f32 v18, v18, v19
	v_cvt_pk_bf16_f32 v19, v24, v25
	global_store_dwordx4 v[28:29], v[16:19], off offset:256
	s_nop 1
	v_mov_b32_e32 v16, v201
	v_mov_b32_e32 v17, v201
	v_lshlrev_b32_e32 v16, 2, v16
	v_xor_b32_e32 v16, 64, v16
	v_mov_b32_e32 v16, v26
	s_nop 1
	v_permlane16_swap_b32_e32 v16, v26
	s_waitcnt lgkmcnt(0)
	v_add_f32_e32 v16, v26, v16
	v_lshlrev_b32_e32 v17, 2, v17
	v_xor_b32_e32 v17, 0x80, v17
	v_mov_b32_e32 v17, v16
	s_nop 1
	v_permlane32_swap_b32_e32 v17, v16
	s_and_saveexec_b64 s[44:45], s[10:11]
	s_cbranch_execz .LBB0_453
	s_waitcnt lgkmcnt(0)
	v_add_f32_e32 v18, v16, v17
	v_lshlrev_b64 v[16:17], 6, v[92:93]
	v_lshl_add_u64 v[16:17], s[22:23], 0, v[16:17]
	v_lshl_add_u64 v[16:17], s[42:43], 2, v[16:17]
	s_lshl_b32 s14, s52, 2
	v_lshl_add_u64 v[16:17], v[16:17], 0, s[14:15]
	global_store_dword v[16:17], v18, off
.LBB0_453:
	s_or_b64 exec, exec, s[44:45]
	s_waitcnt vmcnt(7)
	v_lshlrev_b32_e32 v16, 16, v236
	s_waitcnt lgkmcnt(0)
	v_and_b32_e32 v17, 0xffff0000, v236
	v_lshlrev_b32_e32 v18, 16, v237
	v_and_b32_e32 v19, 0xffff0000, v237
	v_lshlrev_b32_e32 v20, 16, v238
	v_and_b32_e32 v21, 0xffff0000, v238
	v_lshlrev_b32_e32 v22, 16, v239
	v_and_b32_e32 v23, 0xffff0000, v239
	v_pk_add_f32 v[14:15], v[14:15], v[18:19]
	v_pk_add_f32 v[12:13], v[12:13], v[16:17]
	v_pk_add_f32 v[16:17], v[10:11], v[22:23]
	v_pk_add_f32 v[10:11], v[8:9], v[20:21]
	v_mul_f32_e32 v8, v13, v13
	v_mul_f32_e32 v9, v15, v15
	v_fmac_f32_e32 v8, v12, v12
	v_fmac_f32_e32 v9, v14, v14
	v_add_f32_e32 v8, v8, v9
	v_mul_f32_e32 v9, v11, v11
	v_mul_f32_e32 v18, v17, v17
	v_fmac_f32_e32 v9, v10, v10
	v_fmac_f32_e32 v18, v16, v16
	v_add_f32_e32 v9, v9, v18
	v_add_f32_e32 v18, v8, v9
	v_cvt_pk_bf16_f32 v8, v12, v13
	v_lshl_add_u64 v[12:13], s[18:19], 0, v[90:91]
	v_cvt_pk_bf16_f32 v9, v14, v15
	v_cvt_pk_bf16_f32 v10, v10, v11
	v_cvt_pk_bf16_f32 v11, v16, v17
	v_lshl_add_u64 v[12:13], v[168:169], 1, v[12:13]
	global_store_dwordx4 v[12:13], v[8:11], off
	s_waitcnt vmcnt(7)
	v_lshlrev_b32_e32 v14, 16, v242
	v_and_b32_e32 v15, 0xffff0000, v242
	v_lshlrev_b32_e32 v8, 16, v240
	v_and_b32_e32 v9, 0xffff0000, v240
	v_lshlrev_b32_e32 v10, 16, v241
	v_and_b32_e32 v11, 0xffff0000, v241
	v_lshlrev_b32_e32 v16, 16, v243
	v_and_b32_e32 v17, 0xffff0000, v243
	v_pk_add_f32 v[6:7], v[6:7], v[10:11]
	v_pk_add_f32 v[4:5], v[4:5], v[8:9]
	v_pk_add_f32 v[8:9], v[2:3], v[16:17]
	v_pk_add_f32 v[2:3], v[0:1], v[14:15]
	v_mul_f32_e32 v0, v5, v5
	v_mul_f32_e32 v1, v7, v7
	v_fmac_f32_e32 v0, v4, v4
	v_fmac_f32_e32 v1, v6, v6
	v_add_f32_e32 v0, v0, v1
	v_mul_f32_e32 v1, v3, v3
	v_mul_f32_e32 v10, v9, v9
	v_fmac_f32_e32 v1, v2, v2
	v_fmac_f32_e32 v10, v8, v8
	v_add_f32_e32 v1, v1, v10
	v_add_f32_e32 v0, v0, v1
	v_add_f32_e32 v10, v18, v0
	v_cvt_pk_bf16_f32 v0, v4, v5
	v_cvt_pk_bf16_f32 v1, v6, v7
	v_cvt_pk_bf16_f32 v2, v2, v3
	v_cvt_pk_bf16_f32 v3, v8, v9
	global_store_dwordx4 v[12:13], v[0:3], off offset:256
	s_nop 1
	v_mov_b32_e32 v0, v201
	v_mov_b32_e32 v1, v201
	v_lshlrev_b32_e32 v0, 2, v0
	v_xor_b32_e32 v0, 64, v0
	v_mov_b32_e32 v0, v10
	s_nop 1
	v_permlane16_swap_b32_e32 v0, v10
	s_waitcnt lgkmcnt(0)
	v_add_f32_e32 v0, v10, v0
	v_lshlrev_b32_e32 v1, 2, v1
	v_xor_b32_e32 v1, 0x80, v1
	v_mov_b32_e32 v1, v0
	s_nop 1
	v_permlane32_swap_b32_e32 v1, v0
	s_and_saveexec_b64 s[44:45], s[10:11]
	s_cbranch_execz .LBB0_455
	s_waitcnt lgkmcnt(0)
	v_add_f32_e32 v2, v0, v1
	v_lshlrev_b64 v[0:1], 6, v[88:89]
	v_lshl_add_u64 v[0:1], s[22:23], 0, v[0:1]
	v_lshl_add_u64 v[0:1], s[42:43], 2, v[0:1]
	s_lshl_b32 s14, s52, 2
	v_lshl_add_u64 v[0:1], v[0:1], 0, s[14:15]
	global_store_dword v[0:1], v2, off

; __device__ __forceinline__ float sq4(f32x4 v) { return (v[0] * v[0] + v[1] * v[1]) + (v[2] * v[2] + v[3] * v[3]); }
; __device__ __forceinline__ u32x4 pack8(f32x4 a, f32x4 b) { u32x4 w; w.x = cvt_pk_bf16(a[0], a[1]); w.y = cvt_pk_bf16(a[2], a[3]); w.z = cvt_pk_bf16(b[0], b[1]); w.w = cvt_pk_bf16(b[2], b[3]); return w; }
;     __device__ __forceinline__ void operator()(const f32x4 (&acc)[2][2][4][2], const Unit& u, int wr, int wc, int fr, int fq) const {
;         const int col0 = u.pn * 256 + 32 * wc + 8 * fq;
; #pragma unroll
;         for (int ai = 0; ai < 2; ++ai) {
;             u32x4 bs[4][2];
; #pragma unroll
;             for (int m = 0; m < 4; ++m)
; #pragma unroll
;                 for (int bj = 0; bj < 2; ++bj) bs[m][bj] = *(const u32x4*)(xb + (size_t)(u.pm * BM + ai * HALF + wr * 64 + m * 16 + fr) * 1024 + col0 + 128 * bj);
; #pragma unroll
;             for (int m = 0; m < 4; ++m) {
;                 const int row = u.pm * BM + ai * HALF + wr * 64 + m * 16 + fr;
;                 float q = 0.f;
; #pragma unroll
;                 for (int bj = 0; bj < 2; ++bj) {
;                     const size_t off = (size_t)row * 1024 + col0 + 128 * bj; const u32x4 w = bs[m][bj];
;                     const f32x4 b0 = (f32x4){__builtin_bit_cast(float, w.x << 16), __builtin_bit_cast(float, w.x & 0xffff0000u), __builtin_bit_cast(float, w.y << 16), __builtin_bit_cast(float, w.y & 0xffff0000u)};
;                     const f32x4 b1 = (f32x4){__builtin_bit_cast(float, w.z << 16), __builtin_bit_cast(float, w.z & 0xffff0000u), __builtin_bit_cast(float, w.w << 16), __builtin_bit_cast(float, w.w & 0xffff0000u)};
;                     const f32x4 v0 = acc[ai][bj][m][0] + b0, v1 = acc[ai][bj][m][1] + b1;
;                     if (last) { __builtin_nontemporal_store(v0, (f32x4*)(out + off)); __builtin_nontemporal_store(v1, (f32x4*)(out + off + 4)); }
;                     else { q += sq4(v0) + sq4(v1); *(u32x4*)(xb + off) = pack8(v0, v1); }
;                 }
;                 if (!last) { q += shx(q, 16); q += shx(q, 32); if (fq == 0) ss[(size_t)row * 16 + u.pn * 4 + wc] = q; }
.LBB0_605:
	v_lshl_or_b32 v168, s16, 8, v188
	v_lshl_add_u32 v172, s61, 8, v186
	v_ashrrev_i32_e32 v169, 31, v168
	v_lshlrev_b64 v[202:203], 1, v[168:169]
	v_ashrrev_i32_e32 v173, 31, v172
	v_lshl_add_u64 v[170:171], s[22:23], 0, v[202:203]
	v_lshlrev_b64 v[204:205], 11, v[172:173]
	v_lshl_add_u64 v[128:129], v[170:171], 0, v[204:205]
	global_load_dwordx4 v[192:195], v[128:129], off
	global_load_dwordx4 v[196:199], v[128:129], off offset:256
	v_or_b32_e32 v182, 16, v172
	v_or_b32_e32 v178, 32, v172
	v_or_b32_e32 v174, 48, v172
	v_ashrrev_i32_e32 v183, 31, v182
	v_ashrrev_i32_e32 v179, 31, v178
	v_ashrrev_i32_e32 v175, 31, v174
	v_lshlrev_b64 v[184:185], 11, v[182:183]
	v_lshlrev_b64 v[180:181], 11, v[178:179]
	v_lshlrev_b64 v[176:177], 11, v[174:175]
	v_lshl_add_u64 v[128:129], v[170:171], 0, v[184:185]
	v_lshl_add_u64 v[130:131], v[170:171], 0, v[180:181]
	v_lshl_add_u64 v[206:207], v[170:171], 0, v[176:177]
	global_load_dwordx4 v[148:151], v[128:129], off
	global_load_dwordx4 v[144:147], v[128:129], off offset:256
	global_load_dwordx4 v[140:143], v[130:131], off
	global_load_dwordx4 v[136:139], v[130:131], off offset:256
	global_load_dwordx4 v[132:135], v[206:207], off
	s_nop 0
	global_load_dwordx4 v[128:131], v[206:207], off offset:256
	v_add_u32_e32 v244, 0x80, v172
	v_ashrrev_i32_e32 v245, 31, v244
	v_lshlrev_b64 v[244:245], 11, v[244:245]
	v_lshl_add_u64 v[244:245], v[170:171], 0, v[244:245]
	global_load_dwordx4 v[212:215], v[244:245], off
	global_load_dwordx4 v[216:219], v[244:245], off offset:256
	v_add_u32_e32 v244, 0x90, v172
	v_ashrrev_i32_e32 v245, 31, v244
	v_lshlrev_b64 v[244:245], 11, v[244:245]
	v_lshl_add_u64 v[244:245], v[170:171], 0, v[244:245]
	global_load_dwordx4 v[220:223], v[244:245], off
	global_load_dwordx4 v[224:227], v[244:245], off offset:256
	v_add_u32_e32 v244, 0xa0, v172
	v_ashrrev_i32_e32 v245, 31, v244
	v_lshlrev_b64 v[244:245], 11, v[244:245]
	v_lshl_add_u64 v[244:245], v[170:171], 0, v[244:245]
	global_load_dwordx4 v[228:231], v[244:245], off
	global_load_dwordx4 v[232:235], v[244:245], off offset:256
	v_add_u32_e32 v244, 0xb0, v172
	v_ashrrev_i32_e32 v245, 31, v244
	v_lshlrev_b64 v[244:245], 11, v[244:245]
	v_lshl_add_u64 v[244:245], v[170:171], 0, v[244:245]
	global_load_dwordx4 v[236:239], v[244:245], off
	global_load_dwordx4 v[240:243], v[244:245], off offset:256
	v_lshl_add_u64 v[204:205], s[22:23], 0, v[204:205]
	v_lshl_add_u64 v[202:203], v[204:205], 0, v[202:203]
	v_mov_b32_e32 v200, v201
	s_lshl_b32 s38, s16, 2
	s_ashr_i32 s39, s38, 31
	s_waitcnt vmcnt(8)
	v_lshlrev_b32_e32 v204, 16, v192
	v_and_b32_e32 v205, 0xffff0000, v192
	v_lshlrev_b32_e32 v192, 16, v193
	v_and_b32_e32 v193, 0xffff0000, v193
	v_lshlrev_b32_e32 v206, 16, v194
	v_and_b32_e32 v207, 0xffff0000, v194
	v_lshlrev_b32_e32 v194, 16, v195
	v_and_b32_e32 v195, 0xffff0000, v195
	v_lshlrev_b32_e32 v208, 16, v196
	v_and_b32_e32 v209, 0xffff0000, v196
	v_lshlrev_b32_e32 v196, 16, v197
	v_and_b32_e32 v197, 0xffff0000, v197
	v_lshlrev_b32_e32 v210, 16, v198
	v_and_b32_e32 v211, 0xffff0000, v198
	v_lshlrev_b32_e32 v198, 16, v199
	v_and_b32_e32 v199, 0xffff0000, v199
	v_pk_add_f32 v[126:127], v[126:127], v[192:193]
	v_pk_add_f32 v[124:125], v[124:125], v[204:205]
	v_pk_add_f32 v[122:123], v[122:123], v[194:195]
	v_pk_add_f32 v[120:121], v[120:121], v[206:207]
	v_pk_add_f32 v[118:119], v[118:119], v[196:197]
	v_pk_add_f32 v[116:117], v[116:117], v[208:209]
	v_pk_add_f32 v[192:193], v[114:115], v[198:199]
	v_pk_add_f32 v[194:195], v[112:113], v[210:211]
	v_mul_f32_e32 v196, v125, v125
	v_mul_f32_e32 v197, v127, v127
	v_mul_f32_e32 v198, v121, v121
	v_mul_f32_e32 v199, v123, v123
	v_cvt_pk_bf16_f32 v112, v124, v125
	v_cvt_pk_bf16_f32 v113, v126, v127
	v_cvt_pk_bf16_f32 v114, v120, v121
	v_cvt_pk_bf16_f32 v115, v122, v123
	v_mul_f32_e32 v121, v117, v117
	v_mul_f32_e32 v123, v119, v119
	v_mul_f32_e32 v125, v195, v195
	v_mul_f32_e32 v127, v193, v193
	v_fmac_f32_e32 v196, v124, v124
	v_fmac_f32_e32 v197, v126, v126
	v_fmac_f32_e32 v198, v120, v120
	v_fmac_f32_e32 v199, v122, v122
	v_fmac_f32_e32 v121, v116, v116
	v_fmac_f32_e32 v123, v118, v118
	v_fmac_f32_e32 v125, v194, v194
	v_fmac_f32_e32 v127, v192, v192
	global_store_dwordx4 v[202:203], v[112:115], off
	s_nop 1
	v_cvt_pk_bf16_f32 v112, v116, v117
	v_cvt_pk_bf16_f32 v113, v118, v119
	v_cvt_pk_bf16_f32 v114, v194, v195
	v_add_f32_e32 v116, v196, v197
	v_add_f32_e32 v117, v198, v199
	v_add_f32_e32 v118, v121, v123
	v_add_f32_e32 v119, v125, v127
	v_cvt_pk_bf16_f32 v115, v192, v193
	global_store_dwordx4 v[202:203], v[112:115], off offset:256
	s_nop 1
	v_add_f32_e32 v112, v116, v117
	v_add_f32_e32 v113, v118, v119
	v_lshlrev_b32_e32 v114, 2, v200
	v_add_f32_e32 v112, v112, v113
	v_xor_b32_e32 v113, 64, v114
	v_mov_b32_e32 v113, v112
	s_nop 1
	v_permlane16_swap_b32_e32 v113, v112
	v_mov_b32_e32 v114, v201
	s_waitcnt lgkmcnt(0)
	v_add_f32_e32 v112, v112, v113
	v_lshlrev_b32_e32 v114, 2, v114
	v_xor_b32_e32 v113, 0x80, v114
	v_mov_b32_e32 v113, v112
	s_nop 1
	v_permlane32_swap_b32_e32 v113, v112
	s_and_saveexec_b64 s[40:41], s[10:11]
	s_cbranch_execz .LBB0_607
	s_waitcnt lgkmcnt(0)
	v_add_f32_e32 v114, v112, v113
	v_lshlrev_b64 v[112:113], 6, v[172:173]
	v_lshl_add_u64 v[112:113], s[24:25], 0, v[112:113]
	v_lshl_add_u64 v[112:113], s[38:39], 2, v[112:113]
	s_lshl_b32 s16, s50, 2
	v_lshl_add_u64 v[112:113], v[112:113], 0, s[16:17]
	global_store_dword v[112:113], v114, off

; __device__ __forceinline__ float sq4(f32x4 v) { return (v[0] * v[0] + v[1] * v[1]) + (v[2] * v[2] + v[3] * v[3]); }
; __device__ __forceinline__ u32x4 pack8(f32x4 a, f32x4 b) { u32x4 w; w.x = cvt_pk_bf16(a[0], a[1]); w.y = cvt_pk_bf16(a[2], a[3]); w.z = cvt_pk_bf16(b[0], b[1]); w.w = cvt_pk_bf16(b[2], b[3]); return w; }
;     __device__ __forceinline__ void operator()(const f32x4 (&acc)[2][2][4][2], const Unit& u, int wr, int wc, int fr, int fq) const {
;     ...
;         for (int ai = 0; ai < 2; ++ai) {
;             u32x4 bs[4][2];
; #pragma unroll
;             for (int m = 0; m < 4; ++m)
; #pragma unroll
;                 for (int bj = 0; bj < 2; ++bj) bs[m][bj] = *(const u32x4*)(xb + (size_t)(u.pm * BM + ai * HALF + wr * 64 + m * 16 + fr) * 1024 + col0 + 128 * bj);
; #pragma unroll
;             for (int m = 0; m < 4; ++m) {
;                 const int row = u.pm * BM + ai * HALF + wr * 64 + m * 16 + fr;
;                 float q = 0.f;
; #pragma unroll
;                 for (int bj = 0; bj < 2; ++bj) {
;                     const size_t off = (size_t)row * 1024 + col0 + 128 * bj; const u32x4 w = bs[m][bj];
;                     const f32x4 b0 = (f32x4){__builtin_bit_cast(float, w.x << 16), __builtin_bit_cast(float, w.x & 0xffff0000u), __builtin_bit_cast(float, w.y << 16), __builtin_bit_cast(float, w.y & 0xffff0000u)};
;                     const f32x4 b1 = (f32x4){__builtin_bit_cast(float, w.z << 16), __builtin_bit_cast(float, w.z & 0xffff0000u), __builtin_bit_cast(float, w.w << 16), __builtin_bit_cast(float, w.w & 0xffff0000u)};
;                     const f32x4 v0 = acc[ai][bj][m][0] + b0, v1 = acc[ai][bj][m][1] + b1;
;                     if (last) { __builtin_nontemporal_store(v0, (f32x4*)(out + off)); __builtin_nontemporal_store(v1, (f32x4*)(out + off + 4)); }
;                     else { q += sq4(v0) + sq4(v1); *(u32x4*)(xb + off) = pack8(v0, v1); }
;                 }
;                 if (!last) { q += shx(q, 16); q += shx(q, 32); if (fq == 0) ss[(size_t)row * 16 + u.pn * 4 + wc] = q; }
.LBB0_613:
	s_or_b64 exec, exec, s[40:41]
	v_add_u32_e32 v100, 0x80, v172
	v_ashrrev_i32_e32 v101, 31, v100
	v_lshlrev_b64 v[110:111], 11, v[100:101]
	s_waitcnt lgkmcnt(0)
	v_lshl_add_u64 v[64:65], v[170:171], 0, v[110:111]
	s_nop 0
	s_nop 0
	v_add_u32_e32 v96, 0x90, v172
	v_add_u32_e32 v92, 0xa0, v172
	v_add_u32_e32 v88, 0xb0, v172
	v_ashrrev_i32_e32 v97, 31, v96
	v_ashrrev_i32_e32 v93, 31, v92
	v_ashrrev_i32_e32 v89, 31, v88
	v_lshlrev_b64 v[98:99], 11, v[96:97]
	v_lshlrev_b64 v[94:95], 11, v[92:93]
	v_lshlrev_b64 v[90:91], 11, v[88:89]
	v_lshl_add_u64 v[64:65], v[170:171], 0, v[98:99]
	v_lshl_add_u64 v[66:67], v[170:171], 0, v[94:95]
	v_lshl_add_u64 v[112:113], v[170:171], 0, v[90:91]
	s_nop 0
	s_nop 0
	s_nop 0
	s_nop 0
	s_nop 0
	s_nop 0
	s_nop 0
	v_lshl_add_u64 v[110:111], s[22:23], 0, v[110:111]
	v_lshl_add_u64 v[110:111], v[168:169], 1, v[110:111]
	v_mov_b32_e32 v120, v201
	s_waitcnt vmcnt(7)
	v_lshlrev_b32_e32 v112, 16, v212
	v_and_b32_e32 v113, 0xffff0000, v212
	v_lshlrev_b32_e32 v102, 16, v213
	v_and_b32_e32 v103, 0xffff0000, v213
	v_lshlrev_b32_e32 v114, 16, v214
	v_and_b32_e32 v115, 0xffff0000, v214
	v_lshlrev_b32_e32 v104, 16, v215
	v_and_b32_e32 v105, 0xffff0000, v215
	s_waitcnt vmcnt(6)
	v_lshlrev_b32_e32 v116, 16, v216
	v_and_b32_e32 v117, 0xffff0000, v216
	v_lshlrev_b32_e32 v106, 16, v217
	v_and_b32_e32 v107, 0xffff0000, v217
	v_lshlrev_b32_e32 v118, 16, v218
	v_and_b32_e32 v119, 0xffff0000, v218
	v_lshlrev_b32_e32 v108, 16, v219
	v_and_b32_e32 v109, 0xffff0000, v219
	v_pk_add_f32 v[62:63], v[62:63], v[102:103]
	v_pk_add_f32 v[60:61], v[60:61], v[112:113]
	v_pk_add_f32 v[58:59], v[58:59], v[104:105]
	v_pk_add_f32 v[56:57], v[56:57], v[114:115]
	v_pk_add_f32 v[54:55], v[54:55], v[106:107]
	v_pk_add_f32 v[52:53], v[52:53], v[116:117]
	v_pk_add_f32 v[102:103], v[50:51], v[108:109]
	v_pk_add_f32 v[104:105], v[48:49], v[118:119]
	v_mul_f32_e32 v106, v61, v61
	v_mul_f32_e32 v107, v63, v63
	v_mul_f32_e32 v108, v57, v57
	v_mul_f32_e32 v109, v59, v59
	v_cvt_pk_bf16_f32 v48, v60, v61
	v_cvt_pk_bf16_f32 v49, v62, v63
	v_cvt_pk_bf16_f32 v50, v56, v57
	v_cvt_pk_bf16_f32 v51, v58, v59
	v_mul_f32_e32 v57, v53, v53
	v_mul_f32_e32 v59, v55, v55
	v_mul_f32_e32 v61, v105, v105
	v_mul_f32_e32 v63, v103, v103
	v_fmac_f32_e32 v106, v60, v60
	v_fmac_f32_e32 v107, v62, v62
	v_fmac_f32_e32 v108, v56, v56
	v_fmac_f32_e32 v109, v58, v58
	v_fmac_f32_e32 v57, v52, v52
	v_fmac_f32_e32 v59, v54, v54
	v_fmac_f32_e32 v61, v104, v104
	v_fmac_f32_e32 v63, v102, v102
	global_store_dwordx4 v[110:111], v[48:51], off
	s_nop 1
	v_cvt_pk_bf16_f32 v48, v52, v53
	v_cvt_pk_bf16_f32 v49, v54, v55
	v_cvt_pk_bf16_f32 v50, v104, v105
	v_add_f32_e32 v52, v106, v107
	v_add_f32_e32 v53, v108, v109
	v_add_f32_e32 v54, v57, v59
	v_add_f32_e32 v55, v61, v63
	v_cvt_pk_bf16_f32 v51, v102, v103
	global_store_dwordx4 v[110:111], v[48:51], off offset:256
	s_nop 1
	v_add_f32_e32 v48, v52, v53
	v_add_f32_e32 v49, v54, v55
	v_lshlrev_b32_e32 v50, 2, v120
	v_add_f32_e32 v48, v48, v49
	v_xor_b32_e32 v49, 64, v50
	v_mov_b32_e32 v49, v48
	s_nop 1
	v_permlane16_swap_b32_e32 v49, v48
	v_mov_b32_e32 v50, v201
	s_waitcnt lgkmcnt(0)
	v_add_f32_e32 v48, v48, v49
	v_lshlrev_b32_e32 v50, 2, v50
	v_xor_b32_e32 v49, 0x80, v50
	v_mov_b32_e32 v49, v48
	s_nop 1
	v_permlane32_swap_b32_e32 v49, v48
	s_and_saveexec_b64 s[40:41], s[10:11]
	s_cbranch_execz .LBB0_615
	s_waitcnt lgkmcnt(0)
	v_add_f32_e32 v50, v48, v49
	v_lshlrev_b64 v[48:49], 6, v[100:101]
	v_lshl_add_u64 v[48:49], s[24:25], 0, v[48:49]
	v_lshl_add_u64 v[48:49], s[38:39], 2, v[48:49]
	s_lshl_b32 s16, s50, 2
	v_lshl_add_u64 v[48:49], v[48:49], 0, s[16:17]
	global_store_dword v[48:49], v50, off
.LBB0_615:
	s_or_b64 exec, exec, s[40:41]
	s_waitcnt vmcnt(7)
	v_lshlrev_b32_e32 v48, 16, v220
	s_waitcnt lgkmcnt(0)
	v_and_b32_e32 v49, 0xffff0000, v220
	v_lshlrev_b32_e32 v50, 16, v221
	v_and_b32_e32 v51, 0xffff0000, v221
	v_lshlrev_b32_e32 v52, 16, v222
	v_and_b32_e32 v53, 0xffff0000, v222
	v_lshlrev_b32_e32 v54, 16, v223
	v_and_b32_e32 v55, 0xffff0000, v223
	v_pk_add_f32 v[46:47], v[46:47], v[50:51]
	v_pk_add_f32 v[44:45], v[44:45], v[48:49]
	v_pk_add_f32 v[48:49], v[42:43], v[54:55]
	v_pk_add_f32 v[42:43], v[40:41], v[52:53]
	v_mul_f32_e32 v40, v45, v45
	v_mul_f32_e32 v41, v47, v47
	v_fmac_f32_e32 v40, v44, v44
	v_fmac_f32_e32 v41, v46, v46
	v_add_f32_e32 v40, v40, v41
	v_mul_f32_e32 v41, v43, v43
	v_mul_f32_e32 v50, v49, v49
	v_fmac_f32_e32 v41, v42, v42
	v_fmac_f32_e32 v50, v48, v48
	v_add_f32_e32 v41, v41, v50
	v_add_f32_e32 v50, v40, v41
	v_cvt_pk_bf16_f32 v40, v44, v45
	v_lshl_add_u64 v[44:45], s[22:23], 0, v[98:99]
	v_cvt_pk_bf16_f32 v41, v46, v47
	v_cvt_pk_bf16_f32 v42, v42, v43
	v_cvt_pk_bf16_f32 v43, v48, v49
	v_lshl_add_u64 v[44:45], v[168:169], 1, v[44:45]
	global_store_dwordx4 v[44:45], v[40:43], off
	s_waitcnt vmcnt(7)
	v_lshlrev_b32_e32 v46, 16, v226
	v_and_b32_e32 v47, 0xffff0000, v226
	v_lshlrev_b32_e32 v40, 16, v224
	v_and_b32_e32 v41, 0xffff0000, v224
	v_lshlrev_b32_e32 v42, 16, v225
	v_and_b32_e32 v43, 0xffff0000, v225
	v_lshlrev_b32_e32 v48, 16, v227
	v_and_b32_e32 v49, 0xffff0000, v227
	v_pk_add_f32 v[38:39], v[38:39], v[42:43]
	v_pk_add_f32 v[36:37], v[36:37], v[40:41]
	v_pk_add_f32 v[40:41], v[34:35], v[48:49]
	v_pk_add_f32 v[34:35], v[32:33], v[46:47]
	v_mul_f32_e32 v32, v37, v37
	v_mul_f32_e32 v33, v39, v39
	v_fmac_f32_e32 v32, v36, v36
	v_fmac_f32_e32 v33, v38, v38
	v_add_f32_e32 v32, v32, v33
	v_mul_f32_e32 v33, v35, v35
	v_mul_f32_e32 v42, v41, v41
	v_fmac_f32_e32 v33, v34, v34
	v_fmac_f32_e32 v42, v40, v40
	v_add_f32_e32 v33, v33, v42
	v_add_f32_e32 v32, v32, v33
	v_add_f32_e32 v42, v50, v32
	v_cvt_pk_bf16_f32 v32, v36, v37
	v_cvt_pk_bf16_f32 v33, v38, v39
	v_cvt_pk_bf16_f32 v34, v34, v35
	v_cvt_pk_bf16_f32 v35, v40, v41
	global_store_dwordx4 v[44:45], v[32:35], off offset:256
	s_nop 1
	v_mov_b32_e32 v32, v201
	v_mov_b32_e32 v33, v201
	v_lshlrev_b32_e32 v32, 2, v32
	v_xor_b32_e32 v32, 64, v32
	v_mov_b32_e32 v32, v42
	s_nop 1
	v_permlane16_swap_b32_e32 v32, v42
	s_waitcnt lgkmcnt(0)
	v_add_f32_e32 v32, v42, v32
	v_lshlrev_b32_e32 v33, 2, v33
	v_xor_b32_e32 v33, 0x80, v33
	v_mov_b32_e32 v33, v32
	s_nop 1
	v_permlane32_swap_b32_e32 v33, v32
	s_and_saveexec_b64 s[40:41], s[10:11]
	s_cbranch_execz .LBB0_617
	s_waitcnt lgkmcnt(0)
	v_add_f32_e32 v34, v32, v33
	v_lshlrev_b64 v[32:33], 6, v[96:97]
	v_lshl_add_u64 v[32:33], s[24:25], 0, v[32:33]
	v_lshl_add_u64 v[32:33], s[38:39], 2, v[32:33]
	s_lshl_b32 s16, s50, 2
	v_lshl_add_u64 v[32:33], v[32:33], 0, s[16:17]
	global_store_dword v[32:33], v34, off
; __device__ __forceinline__ float sq4(f32x4 v) { return (v[0] * v[0] + v[1] * v[1]) + (v[2] * v[2] + v[3] * v[3]); }
; __device__ __forceinline__ u32x4 pack8(f32x4 a, f32x4 b) { u32x4 w; w.x = cvt_pk_bf16(a[0], a[1]); w.y = cvt_pk_bf16(a[2], a[3]); w.z = cvt_pk_bf16(b[0], b[1]); w.w = cvt_pk_bf16(b[2], b[3]); return w; }
;     __device__ __forceinline__ void operator()(const f32x4 (&acc)[2][2][4][2], const Unit& u, int wr, int wc, int fr, int fq) const {
;     ...
;             for (int m = 0; m < 4; ++m) {
;                 const int row = u.pm * BM + ai * HALF + wr * 64 + m * 16 + fr;
;                 float q = 0.f;
; #pragma unroll
;                 for (int bj = 0; bj < 2; ++bj) {
;                     const size_t off = (size_t)row * 1024 + col0 + 128 * bj; const u32x4 w = bs[m][bj];
;                     const f32x4 b0 = (f32x4){__builtin_bit_cast(float, w.x << 16), __builtin_bit_cast(float, w.x & 0xffff0000u), __builtin_bit_cast(float, w.y << 16), __builtin_bit_cast(float, w.y & 0xffff0000u)};
;                     const f32x4 b1 = (f32x4){__builtin_bit_cast(float, w.z << 16), __builtin_bit_cast(float, w.z & 0xffff0000u), __builtin_bit_cast(float, w.w << 16), __builtin_bit_cast(float, w.w & 0xffff0000u)};
;                     const f32x4 v0 = acc[ai][bj][m][0] + b0, v1 = acc[ai][bj][m][1] + b1;
;                     if (last) { __builtin_nontemporal_store(v0, (f32x4*)(out + off)); __builtin_nontemporal_store(v1, (f32x4*)(out + off + 4)); }
;                     else { q += sq4(v0) + sq4(v1); *(u32x4*)(xb + off) = pack8(v0, v1); }
;                 }
;                 if (!last) { q += shx(q, 16); q += shx(q, 32); if (fq == 0) ss[(size_t)row * 16 + u.pn * 4 + wc] = q; }
.LBB0_617:
	s_or_b64 exec, exec, s[40:41]
	s_waitcnt vmcnt(7)
	v_lshlrev_b32_e32 v32, 16, v228
	s_waitcnt lgkmcnt(0)
	v_and_b32_e32 v33, 0xffff0000, v228
	v_lshlrev_b32_e32 v34, 16, v229
	v_and_b32_e32 v35, 0xffff0000, v229
	v_lshlrev_b32_e32 v36, 16, v230
	v_and_b32_e32 v37, 0xffff0000, v230
	v_lshlrev_b32_e32 v38, 16, v231
	v_and_b32_e32 v39, 0xffff0000, v231
	v_pk_add_f32 v[30:31], v[30:31], v[34:35]
	v_pk_add_f32 v[28:29], v[28:29], v[32:33]
	v_pk_add_f32 v[32:33], v[26:27], v[38:39]
	v_pk_add_f32 v[26:27], v[24:25], v[36:37]
	v_mul_f32_e32 v24, v29, v29
	v_mul_f32_e32 v25, v31, v31
	v_fmac_f32_e32 v24, v28, v28
	v_fmac_f32_e32 v25, v30, v30
	v_add_f32_e32 v24, v24, v25
	v_mul_f32_e32 v25, v27, v27
	v_mul_f32_e32 v34, v33, v33
	v_fmac_f32_e32 v25, v26, v26
	v_fmac_f32_e32 v34, v32, v32
	v_add_f32_e32 v25, v25, v34
	v_add_f32_e32 v34, v24, v25
	v_cvt_pk_bf16_f32 v24, v28, v29
	v_lshl_add_u64 v[28:29], s[22:23], 0, v[94:95]
	v_cvt_pk_bf16_f32 v25, v30, v31
	v_cvt_pk_bf16_f32 v26, v26, v27
	v_cvt_pk_bf16_f32 v27, v32, v33
	v_lshl_add_u64 v[28:29], v[168:169], 1, v[28:29]
	global_store_dwordx4 v[28:29], v[24:27], off
	s_waitcnt vmcnt(7)
	v_lshlrev_b32_e32 v30, 16, v234
	v_and_b32_e32 v31, 0xffff0000, v234
	v_lshlrev_b32_e32 v24, 16, v232
	v_and_b32_e32 v25, 0xffff0000, v232
	v_lshlrev_b32_e32 v26, 16, v233
	v_and_b32_e32 v27, 0xffff0000, v233
	v_lshlrev_b32_e32 v32, 16, v235
	v_and_b32_e32 v33, 0xffff0000, v235
	v_pk_add_f32 v[22:23], v[22:23], v[26:27]
	v_pk_add_f32 v[20:21], v[20:21], v[24:25]
	v_pk_add_f32 v[24:25], v[18:19], v[32:33]
	v_pk_add_f32 v[18:19], v[16:17], v[30:31]
	v_mul_f32_e32 v16, v21, v21
	v_mul_f32_e32 v17, v23, v23
	v_fmac_f32_e32 v16, v20, v20
	v_fmac_f32_e32 v17, v22, v22
	v_add_f32_e32 v16, v16, v17
	v_mul_f32_e32 v17, v19, v19
	v_mul_f32_e32 v26, v25, v25
	v_fmac_f32_e32 v17, v18, v18
	v_fmac_f32_e32 v26, v24, v24
	v_add_f32_e32 v17, v17, v26
	v_add_f32_e32 v16, v16, v17
	v_add_f32_e32 v26, v34, v16
	v_cvt_pk_bf16_f32 v16, v20, v21
	v_cvt_pk_bf16_f32 v17, v22, v23
	v_cvt_pk_bf16_f32 v18, v18, v19
	v_cvt_pk_bf16_f32 v19, v24, v25
	global_store_dwordx4 v[28:29], v[16:19], off offset:256
	s_nop 1
	v_mov_b32_e32 v16, v201
	v_mov_b32_e32 v17, v201
	v_lshlrev_b32_e32 v16, 2, v16
	v_xor_b32_e32 v16, 64, v16
	v_mov_b32_e32 v16, v26
	s_nop 1
	v_permlane16_swap_b32_e32 v16, v26
	s_waitcnt lgkmcnt(0)
	v_add_f32_e32 v16, v26, v16
	v_lshlrev_b32_e32 v17, 2, v17
	v_xor_b32_e32 v17, 0x80, v17
	v_mov_b32_e32 v17, v16
	s_nop 1
	v_permlane32_swap_b32_e32 v17, v16
	s_and_saveexec_b64 s[40:41], s[10:11]
	s_cbranch_execz .LBB0_619
	s_waitcnt lgkmcnt(0)
	v_add_f32_e32 v18, v16, v17
	v_lshlrev_b64 v[16:17], 6, v[92:93]
	v_lshl_add_u64 v[16:17], s[24:25], 0, v[16:17]
	v_lshl_add_u64 v[16:17], s[38:39], 2, v[16:17]
	s_lshl_b32 s16, s50, 2
	v_lshl_add_u64 v[16:17], v[16:17], 0, s[16:17]
	global_store_dword v[16:17], v18, off
.LBB0_619:
	s_or_b64 exec, exec, s[40:41]
	s_waitcnt vmcnt(7)
	v_lshlrev_b32_e32 v16, 16, v236
	s_waitcnt lgkmcnt(0)
	v_and_b32_e32 v17, 0xffff0000, v236
	v_lshlrev_b32_e32 v18, 16, v237
	v_and_b32_e32 v19, 0xffff0000, v237
	v_lshlrev_b32_e32 v20, 16, v238
	v_and_b32_e32 v21, 0xffff0000, v238
	v_lshlrev_b32_e32 v22, 16, v239
	v_and_b32_e32 v23, 0xffff0000, v239
	v_pk_add_f32 v[14:15], v[14:15], v[18:19]
	v_pk_add_f32 v[12:13], v[12:13], v[16:17]
	v_pk_add_f32 v[16:17], v[10:11], v[22:23]
	v_pk_add_f32 v[10:11], v[8:9], v[20:21]
	v_mul_f32_e32 v8, v13, v13
	v_mul_f32_e32 v9, v15, v15
	v_fmac_f32_e32 v8, v12, v12
	v_fmac_f32_e32 v9, v14, v14
	v_add_f32_e32 v8, v8, v9
	v_mul_f32_e32 v9, v11, v11
	v_mul_f32_e32 v18, v17, v17
	v_fmac_f32_e32 v9, v10, v10
	v_fmac_f32_e32 v18, v16, v16
	v_add_f32_e32 v9, v9, v18
	v_add_f32_e32 v18, v8, v9
	v_cvt_pk_bf16_f32 v8, v12, v13
	v_lshl_add_u64 v[12:13], s[22:23], 0, v[90:91]
	v_cvt_pk_bf16_f32 v9, v14, v15
	v_cvt_pk_bf16_f32 v10, v10, v11
	v_cvt_pk_bf16_f32 v11, v16, v17
	v_lshl_add_u64 v[12:13], v[168:169], 1, v[12:13]
	global_store_dwordx4 v[12:13], v[8:11], off
	s_waitcnt vmcnt(7)
	v_lshlrev_b32_e32 v14, 16, v242
	v_and_b32_e32 v15, 0xffff0000, v242
	v_lshlrev_b32_e32 v8, 16, v240
	v_and_b32_e32 v9, 0xffff0000, v240
	v_lshlrev_b32_e32 v10, 16, v241
	v_and_b32_e32 v11, 0xffff0000, v241
	v_lshlrev_b32_e32 v16, 16, v243
	v_and_b32_e32 v17, 0xffff0000, v243
	v_pk_add_f32 v[6:7], v[6:7], v[10:11]
	v_pk_add_f32 v[4:5], v[4:5], v[8:9]
	v_pk_add_f32 v[8:9], v[2:3], v[16:17]
	v_pk_add_f32 v[2:3], v[0:1], v[14:15]
	v_mul_f32_e32 v0, v5, v5
	v_mul_f32_e32 v1, v7, v7
	v_fmac_f32_e32 v0, v4, v4
	v_fmac_f32_e32 v1, v6, v6
	v_add_f32_e32 v0, v0, v1
	v_mul_f32_e32 v1, v3, v3
	v_mul_f32_e32 v10, v9, v9
	v_fmac_f32_e32 v1, v2, v2
	v_fmac_f32_e32 v10, v8, v8
	v_add_f32_e32 v1, v1, v10
	v_add_f32_e32 v0, v0, v1
	v_add_f32_e32 v10, v18, v0
	v_cvt_pk_bf16_f32 v0, v4, v5
	v_cvt_pk_bf16_f32 v1, v6, v7
	v_cvt_pk_bf16_f32 v2, v2, v3
	v_cvt_pk_bf16_f32 v3, v8, v9
	global_store_dwordx4 v[12:13], v[0:3], off offset:256
	s_nop 1
	v_mov_b32_e32 v0, v201
	v_mov_b32_e32 v1, v201
	v_lshlrev_b32_e32 v0, 2, v0
	v_xor_b32_e32 v0, 64, v0
	v_mov_b32_e32 v0, v10
	s_nop 1
	v_permlane16_swap_b32_e32 v0, v10
	s_waitcnt lgkmcnt(0)
	v_add_f32_e32 v0, v10, v0
	v_lshlrev_b32_e32 v1, 2, v1
	v_xor_b32_e32 v1, 0x80, v1
	v_mov_b32_e32 v1, v0
	s_nop 1
	v_permlane32_swap_b32_e32 v1, v0
	s_and_saveexec_b64 s[40:41], s[10:11]
	s_cbranch_execz .LBB0_621
	s_waitcnt lgkmcnt(0)
	v_add_f32_e32 v2, v0, v1
	v_lshlrev_b64 v[0:1], 6, v[88:89]
	v_lshl_add_u64 v[0:1], s[24:25], 0, v[0:1]
	v_lshl_add_u64 v[0:1], s[38:39], 2, v[0:1]
	s_lshl_b32 s16, s50, 2
	v_lshl_add_u64 v[0:1], v[0:1], 0, s[16:17]
	global_store_dword v[0:1], v2, off

; __device__ __forceinline__ float sq4(f32x4 v) { return (v[0] * v[0] + v[1] * v[1]) + (v[2] * v[2] + v[3] * v[3]); }
; __device__ __forceinline__ u32x4 pack8(f32x4 a, f32x4 b) { u32x4 w; w.x = cvt_pk_bf16(a[0], a[1]); w.y = cvt_pk_bf16(a[2], a[3]); w.z = cvt_pk_bf16(b[0], b[1]); w.w = cvt_pk_bf16(b[2], b[3]); return w; }
;     __device__ __forceinline__ void operator()(const f32x4 (&acc)[2][2][4][2], const Unit& u, int wr, int wc, int fr, int fq) const {
;         const int col0 = u.pn * 256 + 32 * wc + 8 * fq;
; #pragma unroll
;         for (int ai = 0; ai < 2; ++ai) {
;             u32x4 bs[4][2];
; #pragma unroll
;             for (int m = 0; m < 4; ++m)
; #pragma unroll
;                 for (int bj = 0; bj < 2; ++bj) bs[m][bj] = *(const u32x4*)(xb + (size_t)(u.pm * BM + ai * HALF + wr * 64 + m * 16 + fr) * 1024 + col0 + 128 * bj);
; #pragma unroll
;             for (int m = 0; m < 4; ++m) {
;                 const int row = u.pm * BM + ai * HALF + wr * 64 + m * 16 + fr;
;                 float q = 0.f;
; #pragma unroll
;                 for (int bj = 0; bj < 2; ++bj) {
;                     const size_t off = (size_t)row * 1024 + col0 + 128 * bj; const u32x4 w = bs[m][bj];
;                     const f32x4 b0 = (f32x4){__builtin_bit_cast(float, w.x << 16), __builtin_bit_cast(float, w.x & 0xffff0000u), __builtin_bit_cast(float, w.y << 16), __builtin_bit_cast(float, w.y & 0xffff0000u)};
;                     const f32x4 b1 = (f32x4){__builtin_bit_cast(float, w.z << 16), __builtin_bit_cast(float, w.z & 0xffff0000u), __builtin_bit_cast(float, w.w << 16), __builtin_bit_cast(float, w.w & 0xffff0000u)};
;                     const f32x4 v0 = acc[ai][bj][m][0] + b0, v1 = acc[ai][bj][m][1] + b1;
;                     if (last) { __builtin_nontemporal_store(v0, (f32x4*)(out + off)); __builtin_nontemporal_store(v1, (f32x4*)(out + off + 4)); }
;                     else { q += sq4(v0) + sq4(v1); *(u32x4*)(xb + off) = pack8(v0, v1); }
;                 }
;                 if (!last) { q += shx(q, 16); q += shx(q, 32); if (fq == 0) ss[(size_t)row * 16 + u.pn * 4 + wc] = q; }
.LBB0_915:
	v_lshl_or_b32 v168, s18, 8, v188
	v_lshl_add_u32 v172, s54, 8, v186
	v_ashrrev_i32_e32 v169, 31, v168
	v_lshlrev_b64 v[202:203], 1, v[168:169]
	v_ashrrev_i32_e32 v173, 31, v172
	v_lshl_add_u64 v[170:171], s[22:23], 0, v[202:203]
	v_lshlrev_b64 v[204:205], 11, v[172:173]
	v_lshl_add_u64 v[120:121], v[170:171], 0, v[204:205]
	global_load_dwordx4 v[192:195], v[120:121], off
	global_load_dwordx4 v[196:199], v[120:121], off offset:256
	v_or_b32_e32 v182, 16, v172
	v_ashrrev_i32_e32 v183, 31, v182
	v_or_b32_e32 v178, 32, v172
	v_lshlrev_b64 v[184:185], 11, v[182:183]
	v_ashrrev_i32_e32 v179, 31, v178
	v_or_b32_e32 v174, 48, v172
	v_lshl_add_u64 v[120:121], v[170:171], 0, v[184:185]
	v_lshlrev_b64 v[180:181], 11, v[178:179]
	v_ashrrev_i32_e32 v175, 31, v174
	global_load_dwordx4 v[148:151], v[120:121], off
	global_load_dwordx4 v[144:147], v[120:121], off offset:256
	v_lshl_add_u64 v[120:121], v[170:171], 0, v[180:181]
	v_lshlrev_b64 v[176:177], 11, v[174:175]
	global_load_dwordx4 v[140:143], v[120:121], off
	global_load_dwordx4 v[136:139], v[120:121], off offset:256
	v_lshl_add_u64 v[120:121], v[170:171], 0, v[176:177]
	global_load_dwordx4 v[132:135], v[120:121], off
	s_nop 0
	global_load_dwordx4 v[120:123], v[120:121], off offset:256
	v_add_u32_e32 v210, 0x80, v172
	v_ashrrev_i32_e32 v211, 31, v210
	v_lshlrev_b64 v[210:211], 11, v[210:211]
	v_lshl_add_u64 v[210:211], v[170:171], 0, v[210:211]
	global_load_dwordx4 v[212:215], v[210:211], off
	global_load_dwordx4 v[216:219], v[210:211], off offset:256
	v_add_u32_e32 v210, 0x90, v172
	v_ashrrev_i32_e32 v211, 31, v210
	v_lshlrev_b64 v[210:211], 11, v[210:211]
	v_lshl_add_u64 v[210:211], v[170:171], 0, v[210:211]
	global_load_dwordx4 v[220:223], v[210:211], off
	global_load_dwordx4 v[224:227], v[210:211], off offset:256
	v_add_u32_e32 v210, 0xa0, v172
	v_ashrrev_i32_e32 v211, 31, v210
	v_lshlrev_b64 v[210:211], 11, v[210:211]
	v_lshl_add_u64 v[210:211], v[170:171], 0, v[210:211]
	global_load_dwordx4 v[228:231], v[210:211], off
	global_load_dwordx4 v[232:235], v[210:211], off offset:256
	v_add_u32_e32 v210, 0xb0, v172
	v_ashrrev_i32_e32 v211, 31, v210
	v_lshlrev_b64 v[210:211], 11, v[210:211]
	v_lshl_add_u64 v[210:211], v[170:171], 0, v[210:211]
	global_load_dwordx4 v[236:239], v[210:211], off
	global_load_dwordx4 v[240:243], v[210:211], off offset:256
	s_lshl_b32 s54, s18, 2
	s_ashr_i32 s55, s54, 31
	s_waitcnt vmcnt(8)
	v_lshlrev_b32_e32 v206, 16, v192
	v_and_b32_e32 v207, 0xffff0000, v192
	v_lshlrev_b32_e32 v192, 16, v193
	v_and_b32_e32 v193, 0xffff0000, v193
	v_lshlrev_b32_e32 v208, 16, v194
	v_and_b32_e32 v209, 0xffff0000, v194
	v_lshlrev_b32_e32 v194, 16, v195
	v_and_b32_e32 v195, 0xffff0000, v195
	v_pk_add_f32 v[130:131], v[130:131], v[192:193]
	v_pk_add_f32 v[128:129], v[128:129], v[206:207]
	v_pk_add_f32 v[192:193], v[126:127], v[194:195]
	v_pk_add_f32 v[126:127], v[124:125], v[208:209]
	v_mul_f32_e32 v124, v129, v129
	v_mul_f32_e32 v125, v131, v131
	v_fmac_f32_e32 v124, v128, v128
	v_fmac_f32_e32 v125, v130, v130
	v_add_f32_e32 v124, v124, v125
	v_mul_f32_e32 v125, v127, v127
	v_mul_f32_e32 v194, v193, v193
	v_fmac_f32_e32 v125, v126, v126
	v_fmac_f32_e32 v194, v192, v192
	v_add_f32_e32 v125, v125, v194
	v_add_f32_e32 v194, v124, v125
	v_cvt_pk_bf16_f32 v124, v128, v129
	v_lshl_add_u64 v[128:129], s[22:23], 0, v[204:205]
	v_cvt_pk_bf16_f32 v125, v130, v131
	v_cvt_pk_bf16_f32 v126, v126, v127
	v_cvt_pk_bf16_f32 v127, v192, v193
	v_lshl_add_u64 v[128:129], v[128:129], 0, v[202:203]
	global_store_dwordx4 v[128:129], v[124:127], off
	v_lshlrev_b32_e32 v130, 16, v198
	v_and_b32_e32 v131, 0xffff0000, v198
	v_lshlrev_b32_e32 v124, 16, v196
	v_and_b32_e32 v125, 0xffff0000, v196
	v_lshlrev_b32_e32 v126, 16, v197
	v_and_b32_e32 v127, 0xffff0000, v197
	v_lshlrev_b32_e32 v192, 16, v199
	v_and_b32_e32 v193, 0xffff0000, v199
	v_pk_add_f32 v[118:119], v[118:119], v[126:127]
	v_pk_add_f32 v[116:117], v[116:117], v[124:125]
	v_pk_add_f32 v[124:125], v[114:115], v[192:193]
	v_pk_add_f32 v[114:115], v[112:113], v[130:131]
	v_mul_f32_e32 v112, v117, v117
	v_mul_f32_e32 v113, v119, v119
	v_fmac_f32_e32 v112, v116, v116
	v_fmac_f32_e32 v113, v118, v118
	v_add_f32_e32 v112, v112, v113
	v_mul_f32_e32 v113, v115, v115
	v_mul_f32_e32 v126, v125, v125
	v_fmac_f32_e32 v113, v114, v114
	v_fmac_f32_e32 v126, v124, v124
	v_add_f32_e32 v113, v113, v126
	v_add_f32_e32 v112, v112, v113
	v_add_f32_e32 v126, v194, v112
	v_cvt_pk_bf16_f32 v112, v116, v117
	v_cvt_pk_bf16_f32 v113, v118, v119
	v_cvt_pk_bf16_f32 v114, v114, v115
	v_cvt_pk_bf16_f32 v115, v124, v125
	global_store_dwordx4 v[128:129], v[112:115], off offset:256
	s_nop 1
	v_mov_b32_e32 v112, v201
	v_mov_b32_e32 v113, v201
	v_lshlrev_b32_e32 v112, 2, v112
	v_xor_b32_e32 v112, 64, v112
	v_mov_b32_e32 v112, v126
	s_nop 1
	v_permlane16_swap_b32_e32 v112, v126
	s_waitcnt lgkmcnt(0)
	v_add_f32_e32 v112, v126, v112
	v_lshlrev_b32_e32 v113, 2, v113
	v_xor_b32_e32 v113, 0x80, v113
	v_mov_b32_e32 v113, v112
	s_nop 1
	v_permlane32_swap_b32_e32 v113, v112
	s_and_saveexec_b64 s[56:57], s[12:13]
	s_cbranch_execz .LBB0_917
	s_waitcnt lgkmcnt(0)
	v_add_f32_e32 v114, v112, v113
	v_lshlrev_b64 v[112:113], 6, v[172:173]
	v_lshl_add_u64 v[112:113], s[24:25], 0, v[112:113]
	v_lshl_add_u64 v[112:113], s[54:55], 2, v[112:113]
	s_lshl_b32 s18, s67, 2
	v_lshl_add_u64 v[112:113], v[112:113], 0, s[18:19]
	global_store_dword v[112:113], v114, off

; __device__ __forceinline__ float sq4(f32x4 v) { return (v[0] * v[0] + v[1] * v[1]) + (v[2] * v[2] + v[3] * v[3]); }
; __device__ __forceinline__ u32x4 pack8(f32x4 a, f32x4 b) { u32x4 w; w.x = cvt_pk_bf16(a[0], a[1]); w.y = cvt_pk_bf16(a[2], a[3]); w.z = cvt_pk_bf16(b[0], b[1]); w.w = cvt_pk_bf16(b[2], b[3]); return w; }
;     __device__ __forceinline__ void operator()(const f32x4 (&acc)[2][2][4][2], const Unit& u, int wr, int wc, int fr, int fq) const {
;     ...
;         for (int ai = 0; ai < 2; ++ai) {
;             u32x4 bs[4][2];
; #pragma unroll
;             for (int m = 0; m < 4; ++m)
; #pragma unroll
;                 for (int bj = 0; bj < 2; ++bj) bs[m][bj] = *(const u32x4*)(xb + (size_t)(u.pm * BM + ai * HALF + wr * 64 + m * 16 + fr) * 1024 + col0 + 128 * bj);
; #pragma unroll
;             for (int m = 0; m < 4; ++m) {
;                 const int row = u.pm * BM + ai * HALF + wr * 64 + m * 16 + fr;
;                 float q = 0.f;
; #pragma unroll
;                 for (int bj = 0; bj < 2; ++bj) {
;                     const size_t off = (size_t)row * 1024 + col0 + 128 * bj; const u32x4 w = bs[m][bj];
;                     const f32x4 b0 = (f32x4){__builtin_bit_cast(float, w.x << 16), __builtin_bit_cast(float, w.x & 0xffff0000u), __builtin_bit_cast(float, w.y << 16), __builtin_bit_cast(float, w.y & 0xffff0000u)};
;                     const f32x4 b1 = (f32x4){__builtin_bit_cast(float, w.z << 16), __builtin_bit_cast(float, w.z & 0xffff0000u), __builtin_bit_cast(float, w.w << 16), __builtin_bit_cast(float, w.w & 0xffff0000u)};
;                     const f32x4 v0 = acc[ai][bj][m][0] + b0, v1 = acc[ai][bj][m][1] + b1;
;                     if (last) { __builtin_nontemporal_store(v0, (f32x4*)(out + off)); __builtin_nontemporal_store(v1, (f32x4*)(out + off + 4)); }
;                     else { q += sq4(v0) + sq4(v1); *(u32x4*)(xb + off) = pack8(v0, v1); }
;                 }
;                 if (!last) { q += shx(q, 16); q += shx(q, 32); if (fq == 0) ss[(size_t)row * 16 + u.pn * 4 + wc] = q; }
.LBB0_923:
	s_or_b64 exec, exec, s[56:57]
	v_add_u32_e32 v100, 0x80, v172
	v_ashrrev_i32_e32 v101, 31, v100
	v_lshlrev_b64 v[110:111], 11, v[100:101]
	s_waitcnt lgkmcnt(0)
	v_lshl_add_u64 v[64:65], v[170:171], 0, v[110:111]
	s_nop 0
	s_nop 0
	v_add_u32_e32 v96, 0x90, v172
	v_ashrrev_i32_e32 v97, 31, v96
	v_add_u32_e32 v92, 0xa0, v172
	v_lshlrev_b64 v[98:99], 11, v[96:97]
	v_ashrrev_i32_e32 v93, 31, v92
	v_add_u32_e32 v88, 0xb0, v172
	v_lshl_add_u64 v[64:65], v[170:171], 0, v[98:99]
	v_lshlrev_b64 v[94:95], 11, v[92:93]
	v_ashrrev_i32_e32 v89, 31, v88
	s_nop 0
	s_nop 0
	v_lshl_add_u64 v[64:65], v[170:171], 0, v[94:95]
	v_lshlrev_b64 v[90:91], 11, v[88:89]
	s_nop 0
	s_nop 0
	v_lshl_add_u64 v[64:65], v[170:171], 0, v[90:91]
	s_nop 0
	s_nop 0
	s_nop 0
	s_waitcnt vmcnt(7)
	v_lshlrev_b32_e32 v112, 16, v212
	v_and_b32_e32 v113, 0xffff0000, v212
	v_lshlrev_b32_e32 v102, 16, v213
	v_and_b32_e32 v103, 0xffff0000, v213
	v_lshlrev_b32_e32 v114, 16, v214
	v_and_b32_e32 v115, 0xffff0000, v214
	v_lshlrev_b32_e32 v104, 16, v215
	v_and_b32_e32 v105, 0xffff0000, v215
	v_pk_add_f32 v[62:63], v[62:63], v[102:103]
	v_pk_add_f32 v[60:61], v[60:61], v[112:113]
	v_pk_add_f32 v[102:103], v[58:59], v[104:105]
	v_pk_add_f32 v[58:59], v[56:57], v[114:115]
	v_mul_f32_e32 v56, v61, v61
	v_mul_f32_e32 v57, v63, v63
	v_fmac_f32_e32 v56, v60, v60
	v_fmac_f32_e32 v57, v62, v62
	v_add_f32_e32 v56, v56, v57
	v_mul_f32_e32 v57, v59, v59
	v_mul_f32_e32 v104, v103, v103
	v_fmac_f32_e32 v57, v58, v58
	v_fmac_f32_e32 v104, v102, v102
	v_add_f32_e32 v57, v57, v104
	v_add_f32_e32 v104, v56, v57
	v_cvt_pk_bf16_f32 v56, v60, v61
	v_lshl_add_u64 v[60:61], s[22:23], 0, v[110:111]
	v_cvt_pk_bf16_f32 v57, v62, v63
	v_cvt_pk_bf16_f32 v58, v58, v59
	v_cvt_pk_bf16_f32 v59, v102, v103
	v_lshl_add_u64 v[60:61], v[168:169], 1, v[60:61]
	global_store_dwordx4 v[60:61], v[56:59], off
	s_waitcnt vmcnt(7)
	v_lshlrev_b32_e32 v62, 16, v218
	v_and_b32_e32 v63, 0xffff0000, v218
	v_lshlrev_b32_e32 v56, 16, v216
	v_and_b32_e32 v57, 0xffff0000, v216
	v_lshlrev_b32_e32 v58, 16, v217
	v_and_b32_e32 v59, 0xffff0000, v217
	v_lshlrev_b32_e32 v102, 16, v219
	v_and_b32_e32 v103, 0xffff0000, v219
	v_pk_add_f32 v[54:55], v[54:55], v[58:59]
	v_pk_add_f32 v[52:53], v[52:53], v[56:57]
	v_pk_add_f32 v[56:57], v[50:51], v[102:103]
	v_pk_add_f32 v[50:51], v[48:49], v[62:63]
	v_mul_f32_e32 v48, v53, v53
	v_mul_f32_e32 v49, v55, v55
	v_fmac_f32_e32 v48, v52, v52
	v_fmac_f32_e32 v49, v54, v54
	v_add_f32_e32 v48, v48, v49
	v_mul_f32_e32 v49, v51, v51
	v_mul_f32_e32 v58, v57, v57
	v_fmac_f32_e32 v49, v50, v50
	v_fmac_f32_e32 v58, v56, v56
	v_add_f32_e32 v49, v49, v58
	v_add_f32_e32 v48, v48, v49
	v_add_f32_e32 v58, v104, v48
	v_cvt_pk_bf16_f32 v48, v52, v53
	v_cvt_pk_bf16_f32 v49, v54, v55
	v_cvt_pk_bf16_f32 v50, v50, v51
	v_cvt_pk_bf16_f32 v51, v56, v57
	global_store_dwordx4 v[60:61], v[48:51], off offset:256
	s_nop 1
	v_mov_b32_e32 v48, v201
	v_mov_b32_e32 v49, v201
	v_lshlrev_b32_e32 v48, 2, v48
	v_xor_b32_e32 v48, 64, v48
	v_mov_b32_e32 v48, v58
	s_nop 1
	v_permlane16_swap_b32_e32 v48, v58
	s_waitcnt lgkmcnt(0)
	v_add_f32_e32 v48, v58, v48
	v_lshlrev_b32_e32 v49, 2, v49
	v_xor_b32_e32 v49, 0x80, v49
	v_mov_b32_e32 v49, v48
	s_nop 1
	v_permlane32_swap_b32_e32 v49, v48
	s_and_saveexec_b64 s[56:57], s[12:13]
	s_cbranch_execz .LBB0_925
	s_waitcnt lgkmcnt(0)
	v_add_f32_e32 v50, v48, v49
	v_lshlrev_b64 v[48:49], 6, v[100:101]
	v_lshl_add_u64 v[48:49], s[24:25], 0, v[48:49]
	v_lshl_add_u64 v[48:49], s[54:55], 2, v[48:49]
	s_lshl_b32 s18, s67, 2
	v_lshl_add_u64 v[48:49], v[48:49], 0, s[18:19]
	global_store_dword v[48:49], v50, off
.LBB0_925:
	s_or_b64 exec, exec, s[56:57]
	s_waitcnt vmcnt(7)
	v_lshlrev_b32_e32 v48, 16, v220
	s_waitcnt lgkmcnt(0)
	v_and_b32_e32 v49, 0xffff0000, v220
	v_lshlrev_b32_e32 v50, 16, v221
	v_and_b32_e32 v51, 0xffff0000, v221
	v_lshlrev_b32_e32 v52, 16, v222
	v_and_b32_e32 v53, 0xffff0000, v222
	v_lshlrev_b32_e32 v54, 16, v223
	v_and_b32_e32 v55, 0xffff0000, v223
	v_pk_add_f32 v[46:47], v[46:47], v[50:51]
	v_pk_add_f32 v[44:45], v[44:45], v[48:49]
	v_pk_add_f32 v[48:49], v[42:43], v[54:55]
	v_pk_add_f32 v[42:43], v[40:41], v[52:53]
	v_mul_f32_e32 v40, v45, v45
	v_mul_f32_e32 v41, v47, v47
	v_fmac_f32_e32 v40, v44, v44
	v_fmac_f32_e32 v41, v46, v46
	v_add_f32_e32 v40, v40, v41
	v_mul_f32_e32 v41, v43, v43
	v_mul_f32_e32 v50, v49, v49
	v_fmac_f32_e32 v41, v42, v42
	v_fmac_f32_e32 v50, v48, v48
	v_add_f32_e32 v41, v41, v50
	v_add_f32_e32 v50, v40, v41
	v_cvt_pk_bf16_f32 v40, v44, v45
	v_lshl_add_u64 v[44:45], s[22:23], 0, v[98:99]
	v_cvt_pk_bf16_f32 v41, v46, v47
	v_cvt_pk_bf16_f32 v42, v42, v43
	v_cvt_pk_bf16_f32 v43, v48, v49
	v_lshl_add_u64 v[44:45], v[168:169], 1, v[44:45]
	global_store_dwordx4 v[44:45], v[40:43], off
	s_waitcnt vmcnt(7)
	v_lshlrev_b32_e32 v46, 16, v226
	v_and_b32_e32 v47, 0xffff0000, v226
	v_lshlrev_b32_e32 v40, 16, v224
	v_and_b32_e32 v41, 0xffff0000, v224
	v_lshlrev_b32_e32 v42, 16, v225
	v_and_b32_e32 v43, 0xffff0000, v225
	v_lshlrev_b32_e32 v48, 16, v227
	v_and_b32_e32 v49, 0xffff0000, v227
	v_pk_add_f32 v[38:39], v[38:39], v[42:43]
	v_pk_add_f32 v[36:37], v[36:37], v[40:41]
	v_pk_add_f32 v[40:41], v[34:35], v[48:49]
	v_pk_add_f32 v[34:35], v[32:33], v[46:47]
	v_mul_f32_e32 v32, v37, v37
	v_mul_f32_e32 v33, v39, v39
	v_fmac_f32_e32 v32, v36, v36
	v_fmac_f32_e32 v33, v38, v38
	v_add_f32_e32 v32, v32, v33
	v_mul_f32_e32 v33, v35, v35
	v_mul_f32_e32 v42, v41, v41
	v_fmac_f32_e32 v33, v34, v34
	v_fmac_f32_e32 v42, v40, v40
	v_add_f32_e32 v33, v33, v42
	v_add_f32_e32 v32, v32, v33
	v_add_f32_e32 v42, v50, v32
	v_cvt_pk_bf16_f32 v32, v36, v37
	v_cvt_pk_bf16_f32 v33, v38, v39
	v_cvt_pk_bf16_f32 v34, v34, v35
	v_cvt_pk_bf16_f32 v35, v40, v41
	global_store_dwordx4 v[44:45], v[32:35], off offset:256
	s_nop 1
	v_mov_b32_e32 v32, v201
	v_mov_b32_e32 v33, v201
	v_lshlrev_b32_e32 v32, 2, v32
	v_xor_b32_e32 v32, 64, v32
	v_mov_b32_e32 v32, v42
	s_nop 1
	v_permlane16_swap_b32_e32 v32, v42
	s_waitcnt lgkmcnt(0)
	v_add_f32_e32 v32, v42, v32
	v_lshlrev_b32_e32 v33, 2, v33
	v_xor_b32_e32 v33, 0x80, v33
	v_mov_b32_e32 v33, v32
	s_nop 1
	v_permlane32_swap_b32_e32 v33, v32
	s_and_saveexec_b64 s[56:57], s[12:13]
	s_cbranch_execz .LBB0_927
	s_waitcnt lgkmcnt(0)
	v_add_f32_e32 v34, v32, v33
	v_lshlrev_b64 v[32:33], 6, v[96:97]
	v_lshl_add_u64 v[32:33], s[24:25], 0, v[32:33]
	v_lshl_add_u64 v[32:33], s[54:55], 2, v[32:33]
	s_lshl_b32 s18, s67, 2
	v_lshl_add_u64 v[32:33], v[32:33], 0, s[18:19]
	global_store_dword v[32:33], v34, off
; __device__ __forceinline__ float sq4(f32x4 v) { return (v[0] * v[0] + v[1] * v[1]) + (v[2] * v[2] + v[3] * v[3]); }
; __device__ __forceinline__ u32x4 pack8(f32x4 a, f32x4 b) { u32x4 w; w.x = cvt_pk_bf16(a[0], a[1]); w.y = cvt_pk_bf16(a[2], a[3]); w.z = cvt_pk_bf16(b[0], b[1]); w.w = cvt_pk_bf16(b[2], b[3]); return w; }
;     __device__ __forceinline__ void operator()(const f32x4 (&acc)[2][2][4][2], const Unit& u, int wr, int wc, int fr, int fq) const {
;     ...
;         for (int ai = 0; ai < 2; ++ai) {
;             u32x4 bs[4][2];
; #pragma unroll
;             for (int m = 0; m < 4; ++m)
; #pragma unroll
;                 for (int bj = 0; bj < 2; ++bj) bs[m][bj] = *(const u32x4*)(xb + (size_t)(u.pm * BM + ai * HALF + wr * 64 + m * 16 + fr) * 1024 + col0 + 128 * bj);
; #pragma unroll
;             for (int m = 0; m < 4; ++m) {
;                 const int row = u.pm * BM + ai * HALF + wr * 64 + m * 16 + fr;
;                 float q = 0.f;
; #pragma unroll
;                 for (int bj = 0; bj < 2; ++bj) {
;                     const size_t off = (size_t)row * 1024 + col0 + 128 * bj; const u32x4 w = bs[m][bj];
;                     const f32x4 b0 = (f32x4){__builtin_bit_cast(float, w.x << 16), __builtin_bit_cast(float, w.x & 0xffff0000u), __builtin_bit_cast(float, w.y << 16), __builtin_bit_cast(float, w.y & 0xffff0000u)};
;                     const f32x4 b1 = (f32x4){__builtin_bit_cast(float, w.z << 16), __builtin_bit_cast(float, w.z & 0xffff0000u), __builtin_bit_cast(float, w.w << 16), __builtin_bit_cast(float, w.w & 0xffff0000u)};
;                     const f32x4 v0 = acc[ai][bj][m][0] + b0, v1 = acc[ai][bj][m][1] + b1;
;                     if (last) { __builtin_nontemporal_store(v0, (f32x4*)(out + off)); __builtin_nontemporal_store(v1, (f32x4*)(out + off + 4)); }
;                     else { q += sq4(v0) + sq4(v1); *(u32x4*)(xb + off) = pack8(v0, v1); }
;                 }
;                 if (!last) { q += shx(q, 16); q += shx(q, 32); if (fq == 0) ss[(size_t)row * 16 + u.pn * 4 + wc] = q; }
.LBB0_927:
	s_or_b64 exec, exec, s[56:57]
	s_waitcnt vmcnt(7)
	v_lshlrev_b32_e32 v32, 16, v228
	s_waitcnt lgkmcnt(0)
	v_and_b32_e32 v33, 0xffff0000, v228
	v_lshlrev_b32_e32 v34, 16, v229
	v_and_b32_e32 v35, 0xffff0000, v229
	v_lshlrev_b32_e32 v36, 16, v230
	v_and_b32_e32 v37, 0xffff0000, v230
	v_lshlrev_b32_e32 v38, 16, v231
	v_and_b32_e32 v39, 0xffff0000, v231
	v_pk_add_f32 v[30:31], v[30:31], v[34:35]
	v_pk_add_f32 v[28:29], v[28:29], v[32:33]
	v_pk_add_f32 v[32:33], v[26:27], v[38:39]
	v_pk_add_f32 v[26:27], v[24:25], v[36:37]
	v_mul_f32_e32 v24, v29, v29
	v_mul_f32_e32 v25, v31, v31
	v_fmac_f32_e32 v24, v28, v28
	v_fmac_f32_e32 v25, v30, v30
	v_add_f32_e32 v24, v24, v25
	v_mul_f32_e32 v25, v27, v27
	v_mul_f32_e32 v34, v33, v33
	v_fmac_f32_e32 v25, v26, v26
	v_fmac_f32_e32 v34, v32, v32
	v_add_f32_e32 v25, v25, v34
	v_add_f32_e32 v34, v24, v25
	v_cvt_pk_bf16_f32 v24, v28, v29
	v_lshl_add_u64 v[28:29], s[22:23], 0, v[94:95]
	v_cvt_pk_bf16_f32 v25, v30, v31
	v_cvt_pk_bf16_f32 v26, v26, v27
	v_cvt_pk_bf16_f32 v27, v32, v33
	v_lshl_add_u64 v[28:29], v[168:169], 1, v[28:29]
	global_store_dwordx4 v[28:29], v[24:27], off
	s_waitcnt vmcnt(7)
	v_lshlrev_b32_e32 v30, 16, v234
	v_and_b32_e32 v31, 0xffff0000, v234
	v_lshlrev_b32_e32 v24, 16, v232
	v_and_b32_e32 v25, 0xffff0000, v232
	v_lshlrev_b32_e32 v26, 16, v233
	v_and_b32_e32 v27, 0xffff0000, v233
	v_lshlrev_b32_e32 v32, 16, v235
	v_and_b32_e32 v33, 0xffff0000, v235
	v_pk_add_f32 v[22:23], v[22:23], v[26:27]
	v_pk_add_f32 v[20:21], v[20:21], v[24:25]
	v_pk_add_f32 v[24:25], v[18:19], v[32:33]
	v_pk_add_f32 v[18:19], v[16:17], v[30:31]
	v_mul_f32_e32 v16, v21, v21
	v_mul_f32_e32 v17, v23, v23
	v_fmac_f32_e32 v16, v20, v20
	v_fmac_f32_e32 v17, v22, v22
	v_add_f32_e32 v16, v16, v17
	v_mul_f32_e32 v17, v19, v19
	v_mul_f32_e32 v26, v25, v25
	v_fmac_f32_e32 v17, v18, v18
	v_fmac_f32_e32 v26, v24, v24
	v_add_f32_e32 v17, v17, v26
	v_add_f32_e32 v16, v16, v17
	v_add_f32_e32 v26, v34, v16
	v_cvt_pk_bf16_f32 v16, v20, v21
	v_cvt_pk_bf16_f32 v17, v22, v23
	v_cvt_pk_bf16_f32 v18, v18, v19
	v_cvt_pk_bf16_f32 v19, v24, v25
	global_store_dwordx4 v[28:29], v[16:19], off offset:256
	s_nop 1
	v_mov_b32_e32 v16, v201
	v_mov_b32_e32 v17, v201
	v_lshlrev_b32_e32 v16, 2, v16
	v_xor_b32_e32 v16, 64, v16
	v_mov_b32_e32 v16, v26
	s_nop 1
	v_permlane16_swap_b32_e32 v16, v26
	s_waitcnt lgkmcnt(0)
	v_add_f32_e32 v16, v26, v16
	v_lshlrev_b32_e32 v17, 2, v17
	v_xor_b32_e32 v17, 0x80, v17
	v_mov_b32_e32 v17, v16
	s_nop 1
	v_permlane32_swap_b32_e32 v17, v16
	s_and_saveexec_b64 s[56:57], s[12:13]
	s_cbranch_execz .LBB0_929
	s_waitcnt lgkmcnt(0)
	v_add_f32_e32 v18, v16, v17
	v_lshlrev_b64 v[16:17], 6, v[92:93]
	v_lshl_add_u64 v[16:17], s[24:25], 0, v[16:17]
	v_lshl_add_u64 v[16:17], s[54:55], 2, v[16:17]
	s_lshl_b32 s18, s67, 2
	v_lshl_add_u64 v[16:17], v[16:17], 0, s[18:19]
	global_store_dword v[16:17], v18, off
.LBB0_929:
	s_or_b64 exec, exec, s[56:57]
	s_waitcnt vmcnt(7)
	v_lshlrev_b32_e32 v16, 16, v236
	s_waitcnt lgkmcnt(0)
	v_and_b32_e32 v17, 0xffff0000, v236
	v_lshlrev_b32_e32 v18, 16, v237
	v_and_b32_e32 v19, 0xffff0000, v237
	v_lshlrev_b32_e32 v20, 16, v238
	v_and_b32_e32 v21, 0xffff0000, v238
	v_lshlrev_b32_e32 v22, 16, v239
	v_and_b32_e32 v23, 0xffff0000, v239
	v_pk_add_f32 v[14:15], v[14:15], v[18:19]
	v_pk_add_f32 v[12:13], v[12:13], v[16:17]
	v_pk_add_f32 v[16:17], v[10:11], v[22:23]
	v_pk_add_f32 v[10:11], v[8:9], v[20:21]
	v_mul_f32_e32 v8, v13, v13
	v_mul_f32_e32 v9, v15, v15
	v_fmac_f32_e32 v8, v12, v12
	v_fmac_f32_e32 v9, v14, v14
	v_add_f32_e32 v8, v8, v9
	v_mul_f32_e32 v9, v11, v11
	v_mul_f32_e32 v18, v17, v17
	v_fmac_f32_e32 v9, v10, v10
	v_fmac_f32_e32 v18, v16, v16
	v_add_f32_e32 v9, v9, v18
	v_add_f32_e32 v18, v8, v9
	v_cvt_pk_bf16_f32 v8, v12, v13
	v_lshl_add_u64 v[12:13], s[22:23], 0, v[90:91]
	v_cvt_pk_bf16_f32 v9, v14, v15
	v_cvt_pk_bf16_f32 v10, v10, v11
	v_cvt_pk_bf16_f32 v11, v16, v17
	v_lshl_add_u64 v[12:13], v[168:169], 1, v[12:13]
	global_store_dwordx4 v[12:13], v[8:11], off
	s_waitcnt vmcnt(7)
	v_lshlrev_b32_e32 v14, 16, v242
	v_and_b32_e32 v15, 0xffff0000, v242
	v_lshlrev_b32_e32 v8, 16, v240
	v_and_b32_e32 v9, 0xffff0000, v240
	v_lshlrev_b32_e32 v10, 16, v241
	v_and_b32_e32 v11, 0xffff0000, v241
	v_lshlrev_b32_e32 v16, 16, v243
	v_and_b32_e32 v17, 0xffff0000, v243
	v_pk_add_f32 v[6:7], v[6:7], v[10:11]
	v_pk_add_f32 v[4:5], v[4:5], v[8:9]
	v_pk_add_f32 v[8:9], v[2:3], v[16:17]
	v_pk_add_f32 v[2:3], v[0:1], v[14:15]
	v_mul_f32_e32 v0, v5, v5
	v_mul_f32_e32 v1, v7, v7
	v_fmac_f32_e32 v0, v4, v4
	v_fmac_f32_e32 v1, v6, v6
	v_add_f32_e32 v0, v0, v1
	v_mul_f32_e32 v1, v3, v3
	v_mul_f32_e32 v10, v9, v9
	v_fmac_f32_e32 v1, v2, v2
	v_fmac_f32_e32 v10, v8, v8
	v_add_f32_e32 v1, v1, v10
	v_add_f32_e32 v0, v0, v1
	v_add_f32_e32 v10, v18, v0
	v_cvt_pk_bf16_f32 v0, v4, v5
	v_cvt_pk_bf16_f32 v1, v6, v7
	v_cvt_pk_bf16_f32 v2, v2, v3
	v_cvt_pk_bf16_f32 v3, v8, v9
	global_store_dwordx4 v[12:13], v[0:3], off offset:256
	s_nop 1
	v_mov_b32_e32 v0, v201
	v_mov_b32_e32 v1, v201
	v_lshlrev_b32_e32 v0, 2, v0
	v_xor_b32_e32 v0, 64, v0
	v_mov_b32_e32 v0, v10
	s_nop 1
	v_permlane16_swap_b32_e32 v0, v10
	s_waitcnt lgkmcnt(0)
	v_add_f32_e32 v0, v10, v0
	v_lshlrev_b32_e32 v1, 2, v1
	v_xor_b32_e32 v1, 0x80, v1
	v_mov_b32_e32 v1, v0
	s_nop 1
	v_permlane32_swap_b32_e32 v1, v0
	s_and_saveexec_b64 s[56:57], s[12:13]
	s_cbranch_execz .LBB0_931
	s_waitcnt lgkmcnt(0)
	v_add_f32_e32 v2, v0, v1
	v_lshlrev_b64 v[0:1], 6, v[88:89]
	v_lshl_add_u64 v[0:1], s[24:25], 0, v[0:1]
	v_lshl_add_u64 v[0:1], s[54:55], 2, v[0:1]
	s_lshl_b32 s18, s67, 2
	v_lshl_add_u64 v[0:1], v[0:1], 0, s[18:19]
	global_store_dword v[0:1], v2, off

; __device__ __forceinline__ float sq4(f32x4 v) { return (v[0] * v[0] + v[1] * v[1]) + (v[2] * v[2] + v[3] * v[3]); }
; __device__ __forceinline__ u32x4 pack8(f32x4 a, f32x4 b) { u32x4 w; w.x = cvt_pk_bf16(a[0], a[1]); w.y = cvt_pk_bf16(a[2], a[3]); w.z = cvt_pk_bf16(b[0], b[1]); w.w = cvt_pk_bf16(b[2], b[3]); return w; }
;     __device__ __forceinline__ void operator()(const f32x4 (&acc)[2][2][4][2], const Unit& u, int wr, int wc, int fr, int fq) const {
;         const int col0 = u.pn * 256 + 32 * wc + 8 * fq;
; #pragma unroll
;         for (int ai = 0; ai < 2; ++ai) {
;             u32x4 bs[4][2];
; #pragma unroll
;             for (int m = 0; m < 4; ++m)
; #pragma unroll
;                 for (int bj = 0; bj < 2; ++bj) bs[m][bj] = *(const u32x4*)(xb + (size_t)(u.pm * BM + ai * HALF + wr * 64 + m * 16 + fr) * 1024 + col0 + 128 * bj);
; #pragma unroll
;             for (int m = 0; m < 4; ++m) {
;                 const int row = u.pm * BM + ai * HALF + wr * 64 + m * 16 + fr;
;                 float q = 0.f;
; #pragma unroll
;                 for (int bj = 0; bj < 2; ++bj) {
;                     const size_t off = (size_t)row * 1024 + col0 + 128 * bj; const u32x4 w = bs[m][bj];
;                     const f32x4 b0 = (f32x4){__builtin_bit_cast(float, w.x << 16), __builtin_bit_cast(float, w.x & 0xffff0000u), __builtin_bit_cast(float, w.y << 16), __builtin_bit_cast(float, w.y & 0xffff0000u)};
;                     const f32x4 b1 = (f32x4){__builtin_bit_cast(float, w.z << 16), __builtin_bit_cast(float, w.z & 0xffff0000u), __builtin_bit_cast(float, w.w << 16), __builtin_bit_cast(float, w.w & 0xffff0000u)};
;                     const f32x4 v0 = acc[ai][bj][m][0] + b0, v1 = acc[ai][bj][m][1] + b1;
;                     if (last) { __builtin_nontemporal_store(v0, (f32x4*)(out + off)); __builtin_nontemporal_store(v1, (f32x4*)(out + off + 4)); }
;                     else { q += sq4(v0) + sq4(v1); *(u32x4*)(xb + off) = pack8(v0, v1); }
;                 }
;                 if (!last) { q += shx(q, 16); q += shx(q, 32); if (fq == 0) ss[(size_t)row * 16 + u.pn * 4 + wc] = q; }
.LBB0_1081:
	v_lshl_or_b32 v168, s22, 8, v188
	v_lshl_add_u32 v172, s72, 8, v186
	v_ashrrev_i32_e32 v169, 31, v168
	v_lshlrev_b64 v[202:203], 1, v[168:169]
	v_ashrrev_i32_e32 v173, 31, v172
	v_lshl_add_u64 v[170:171], s[26:27], 0, v[202:203]
	v_lshlrev_b64 v[204:205], 11, v[172:173]
	v_lshl_add_u64 v[120:121], v[170:171], 0, v[204:205]
	global_load_dwordx4 v[192:195], v[120:121], off
	global_load_dwordx4 v[196:199], v[120:121], off offset:256
	v_or_b32_e32 v182, 16, v172
	v_ashrrev_i32_e32 v183, 31, v182
	v_or_b32_e32 v178, 32, v172
	v_lshlrev_b64 v[184:185], 11, v[182:183]
	v_ashrrev_i32_e32 v179, 31, v178
	v_or_b32_e32 v174, 48, v172
	v_lshl_add_u64 v[120:121], v[170:171], 0, v[184:185]
	v_lshlrev_b64 v[180:181], 11, v[178:179]
	v_ashrrev_i32_e32 v175, 31, v174
	global_load_dwordx4 v[148:151], v[120:121], off
	global_load_dwordx4 v[144:147], v[120:121], off offset:256
	v_lshl_add_u64 v[120:121], v[170:171], 0, v[180:181]
	v_lshlrev_b64 v[176:177], 11, v[174:175]
	global_load_dwordx4 v[140:143], v[120:121], off
	global_load_dwordx4 v[136:139], v[120:121], off offset:256
	v_lshl_add_u64 v[120:121], v[170:171], 0, v[176:177]
	global_load_dwordx4 v[132:135], v[120:121], off
	s_nop 0
	global_load_dwordx4 v[120:123], v[120:121], off offset:256
	v_add_u32_e32 v210, 0x80, v172
	v_ashrrev_i32_e32 v211, 31, v210
	v_lshlrev_b64 v[210:211], 11, v[210:211]
	v_lshl_add_u64 v[210:211], v[170:171], 0, v[210:211]
	global_load_dwordx4 v[212:215], v[210:211], off
	global_load_dwordx4 v[216:219], v[210:211], off offset:256
	v_add_u32_e32 v210, 0x90, v172
	v_ashrrev_i32_e32 v211, 31, v210
	v_lshlrev_b64 v[210:211], 11, v[210:211]
	v_lshl_add_u64 v[210:211], v[170:171], 0, v[210:211]
	global_load_dwordx4 v[220:223], v[210:211], off
	global_load_dwordx4 v[224:227], v[210:211], off offset:256
	v_add_u32_e32 v210, 0xa0, v172
	v_ashrrev_i32_e32 v211, 31, v210
	v_lshlrev_b64 v[210:211], 11, v[210:211]
	v_lshl_add_u64 v[210:211], v[170:171], 0, v[210:211]
	global_load_dwordx4 v[228:231], v[210:211], off
	global_load_dwordx4 v[232:235], v[210:211], off offset:256
	v_add_u32_e32 v210, 0xb0, v172
	v_ashrrev_i32_e32 v211, 31, v210
	v_lshlrev_b64 v[210:211], 11, v[210:211]
	v_lshl_add_u64 v[210:211], v[170:171], 0, v[210:211]
	global_load_dwordx4 v[236:239], v[210:211], off
	global_load_dwordx4 v[240:243], v[210:211], off offset:256
	s_lshl_b32 s50, s22, 2
	s_ashr_i32 s51, s50, 31
	s_waitcnt vmcnt(8)
	v_lshlrev_b32_e32 v206, 16, v192
	v_and_b32_e32 v207, 0xffff0000, v192
	v_lshlrev_b32_e32 v192, 16, v193
	v_and_b32_e32 v193, 0xffff0000, v193
	v_lshlrev_b32_e32 v208, 16, v194
	v_and_b32_e32 v209, 0xffff0000, v194
	v_lshlrev_b32_e32 v194, 16, v195
	v_and_b32_e32 v195, 0xffff0000, v195
	v_pk_add_f32 v[130:131], v[130:131], v[192:193]
	v_pk_add_f32 v[128:129], v[128:129], v[206:207]
	v_pk_add_f32 v[192:193], v[126:127], v[194:195]
	v_pk_add_f32 v[126:127], v[124:125], v[208:209]
	v_mul_f32_e32 v124, v129, v129
	v_mul_f32_e32 v125, v131, v131
	v_fmac_f32_e32 v124, v128, v128
	v_fmac_f32_e32 v125, v130, v130
	v_add_f32_e32 v124, v124, v125
	v_mul_f32_e32 v125, v127, v127
	v_mul_f32_e32 v194, v193, v193
	v_fmac_f32_e32 v125, v126, v126
	v_fmac_f32_e32 v194, v192, v192
	v_add_f32_e32 v125, v125, v194
	v_add_f32_e32 v194, v124, v125
	v_cvt_pk_bf16_f32 v124, v128, v129
	v_lshl_add_u64 v[128:129], s[26:27], 0, v[204:205]
	v_cvt_pk_bf16_f32 v125, v130, v131
	v_cvt_pk_bf16_f32 v126, v126, v127
	v_cvt_pk_bf16_f32 v127, v192, v193
	v_lshl_add_u64 v[128:129], v[128:129], 0, v[202:203]
	global_store_dwordx4 v[128:129], v[124:127], off
	v_lshlrev_b32_e32 v130, 16, v198
	v_and_b32_e32 v131, 0xffff0000, v198
	v_lshlrev_b32_e32 v124, 16, v196
	v_and_b32_e32 v125, 0xffff0000, v196
	v_lshlrev_b32_e32 v126, 16, v197
	v_and_b32_e32 v127, 0xffff0000, v197
	v_lshlrev_b32_e32 v192, 16, v199
	v_and_b32_e32 v193, 0xffff0000, v199
	v_pk_add_f32 v[118:119], v[118:119], v[126:127]
	v_pk_add_f32 v[116:117], v[116:117], v[124:125]
	v_pk_add_f32 v[124:125], v[114:115], v[192:193]
	v_pk_add_f32 v[114:115], v[112:113], v[130:131]
	v_mul_f32_e32 v112, v117, v117
	v_mul_f32_e32 v113, v119, v119
	v_fmac_f32_e32 v112, v116, v116
	v_fmac_f32_e32 v113, v118, v118
	v_add_f32_e32 v112, v112, v113
	v_mul_f32_e32 v113, v115, v115
	v_mul_f32_e32 v126, v125, v125
	v_fmac_f32_e32 v113, v114, v114
	v_fmac_f32_e32 v126, v124, v124
	v_add_f32_e32 v113, v113, v126
	v_add_f32_e32 v112, v112, v113
	v_add_f32_e32 v126, v194, v112
	v_cvt_pk_bf16_f32 v112, v116, v117
	v_cvt_pk_bf16_f32 v113, v118, v119
	v_cvt_pk_bf16_f32 v114, v114, v115
	v_cvt_pk_bf16_f32 v115, v124, v125
	global_store_dwordx4 v[128:129], v[112:115], off offset:256
	s_nop 1
	v_mov_b32_e32 v112, v201
	v_mov_b32_e32 v113, v201
	v_lshlrev_b32_e32 v112, 2, v112
	v_xor_b32_e32 v112, 64, v112
	v_mov_b32_e32 v112, v126
	s_nop 1
	v_permlane16_swap_b32_e32 v112, v126
	s_waitcnt lgkmcnt(0)
	v_add_f32_e32 v112, v126, v112
	v_lshlrev_b32_e32 v113, 2, v113
	v_xor_b32_e32 v113, 0x80, v113
	v_mov_b32_e32 v113, v112
	s_nop 1
	v_permlane32_swap_b32_e32 v113, v112
	s_and_saveexec_b64 s[52:53], s[16:17]
	s_cbranch_execz .LBB0_1083
	s_waitcnt lgkmcnt(0)
	v_add_f32_e32 v114, v112, v113
	v_lshlrev_b64 v[112:113], 6, v[172:173]
	v_lshl_add_u64 v[112:113], s[42:43], 0, v[112:113]
	v_lshl_add_u64 v[112:113], s[50:51], 2, v[112:113]
	s_lshl_b32 s22, s61, 2
	v_lshl_add_u64 v[112:113], v[112:113], 0, s[22:23]
	global_store_dword v[112:113], v114, off

; __device__ __forceinline__ float sq4(f32x4 v) { return (v[0] * v[0] + v[1] * v[1]) + (v[2] * v[2] + v[3] * v[3]); }
; __device__ __forceinline__ u32x4 pack8(f32x4 a, f32x4 b) { u32x4 w; w.x = cvt_pk_bf16(a[0], a[1]); w.y = cvt_pk_bf16(a[2], a[3]); w.z = cvt_pk_bf16(b[0], b[1]); w.w = cvt_pk_bf16(b[2], b[3]); return w; }
;     __device__ __forceinline__ void operator()(const f32x4 (&acc)[2][2][4][2], const Unit& u, int wr, int wc, int fr, int fq) const {
;     ...
;         for (int ai = 0; ai < 2; ++ai) {
;             u32x4 bs[4][2];
; #pragma unroll
;             for (int m = 0; m < 4; ++m)
; #pragma unroll
;                 for (int bj = 0; bj < 2; ++bj) bs[m][bj] = *(const u32x4*)(xb + (size_t)(u.pm * BM + ai * HALF + wr * 64 + m * 16 + fr) * 1024 + col0 + 128 * bj);
; #pragma unroll
;             for (int m = 0; m < 4; ++m) {
;                 const int row = u.pm * BM + ai * HALF + wr * 64 + m * 16 + fr;
;                 float q = 0.f;
; #pragma unroll
;                 for (int bj = 0; bj < 2; ++bj) {
;                     const size_t off = (size_t)row * 1024 + col0 + 128 * bj; const u32x4 w = bs[m][bj];
;                     const f32x4 b0 = (f32x4){__builtin_bit_cast(float, w.x << 16), __builtin_bit_cast(float, w.x & 0xffff0000u), __builtin_bit_cast(float, w.y << 16), __builtin_bit_cast(float, w.y & 0xffff0000u)};
;                     const f32x4 b1 = (f32x4){__builtin_bit_cast(float, w.z << 16), __builtin_bit_cast(float, w.z & 0xffff0000u), __builtin_bit_cast(float, w.w << 16), __builtin_bit_cast(float, w.w & 0xffff0000u)};
;                     const f32x4 v0 = acc[ai][bj][m][0] + b0, v1 = acc[ai][bj][m][1] + b1;
;                     if (last) { __builtin_nontemporal_store(v0, (f32x4*)(out + off)); __builtin_nontemporal_store(v1, (f32x4*)(out + off + 4)); }
;                     else { q += sq4(v0) + sq4(v1); *(u32x4*)(xb + off) = pack8(v0, v1); }
;                 }
;                 if (!last) { q += shx(q, 16); q += shx(q, 32); if (fq == 0) ss[(size_t)row * 16 + u.pn * 4 + wc] = q; }
.LBB0_1089:
	s_or_b64 exec, exec, s[52:53]
	v_add_u32_e32 v100, 0x80, v172
	v_ashrrev_i32_e32 v101, 31, v100
	v_lshlrev_b64 v[110:111], 11, v[100:101]
	s_waitcnt lgkmcnt(0)
	v_lshl_add_u64 v[64:65], v[170:171], 0, v[110:111]
	s_nop 0
	s_nop 0
	v_add_u32_e32 v96, 0x90, v172
	v_ashrrev_i32_e32 v97, 31, v96
	v_add_u32_e32 v92, 0xa0, v172
	v_lshlrev_b64 v[98:99], 11, v[96:97]
	v_ashrrev_i32_e32 v93, 31, v92
	v_add_u32_e32 v88, 0xb0, v172
	v_lshl_add_u64 v[64:65], v[170:171], 0, v[98:99]
	v_lshlrev_b64 v[94:95], 11, v[92:93]
	v_ashrrev_i32_e32 v89, 31, v88
	s_nop 0
	s_nop 0
	v_lshl_add_u64 v[64:65], v[170:171], 0, v[94:95]
	v_lshlrev_b64 v[90:91], 11, v[88:89]
	s_nop 0
	s_nop 0
	v_lshl_add_u64 v[64:65], v[170:171], 0, v[90:91]
	s_nop 0
	s_nop 0
	s_nop 0
	s_waitcnt vmcnt(7)
	v_lshlrev_b32_e32 v112, 16, v212
	v_and_b32_e32 v113, 0xffff0000, v212
	v_lshlrev_b32_e32 v102, 16, v213
	v_and_b32_e32 v103, 0xffff0000, v213
	v_lshlrev_b32_e32 v114, 16, v214
	v_and_b32_e32 v115, 0xffff0000, v214
	v_lshlrev_b32_e32 v104, 16, v215
	v_and_b32_e32 v105, 0xffff0000, v215
	v_pk_add_f32 v[62:63], v[62:63], v[102:103]
	v_pk_add_f32 v[60:61], v[60:61], v[112:113]
	v_pk_add_f32 v[102:103], v[58:59], v[104:105]
	v_pk_add_f32 v[58:59], v[56:57], v[114:115]
	v_mul_f32_e32 v56, v61, v61
	v_mul_f32_e32 v57, v63, v63
	v_fmac_f32_e32 v56, v60, v60
	v_fmac_f32_e32 v57, v62, v62
	v_add_f32_e32 v56, v56, v57
	v_mul_f32_e32 v57, v59, v59
	v_mul_f32_e32 v104, v103, v103
	v_fmac_f32_e32 v57, v58, v58
	v_fmac_f32_e32 v104, v102, v102
	v_add_f32_e32 v57, v57, v104
	v_add_f32_e32 v104, v56, v57
	v_cvt_pk_bf16_f32 v56, v60, v61
	v_lshl_add_u64 v[60:61], s[26:27], 0, v[110:111]
	v_cvt_pk_bf16_f32 v57, v62, v63
	v_cvt_pk_bf16_f32 v58, v58, v59
	v_cvt_pk_bf16_f32 v59, v102, v103
	v_lshl_add_u64 v[60:61], v[168:169], 1, v[60:61]
	global_store_dwordx4 v[60:61], v[56:59], off
	s_waitcnt vmcnt(7)
	v_lshlrev_b32_e32 v62, 16, v218
	v_and_b32_e32 v63, 0xffff0000, v218
	v_lshlrev_b32_e32 v56, 16, v216
	v_and_b32_e32 v57, 0xffff0000, v216
	v_lshlrev_b32_e32 v58, 16, v217
	v_and_b32_e32 v59, 0xffff0000, v217
	v_lshlrev_b32_e32 v102, 16, v219
	v_and_b32_e32 v103, 0xffff0000, v219
	v_pk_add_f32 v[54:55], v[54:55], v[58:59]
	v_pk_add_f32 v[52:53], v[52:53], v[56:57]
	v_pk_add_f32 v[56:57], v[50:51], v[102:103]
	v_pk_add_f32 v[50:51], v[48:49], v[62:63]
	v_mul_f32_e32 v48, v53, v53
	v_mul_f32_e32 v49, v55, v55
	v_fmac_f32_e32 v48, v52, v52
	v_fmac_f32_e32 v49, v54, v54
	v_add_f32_e32 v48, v48, v49
	v_mul_f32_e32 v49, v51, v51
	v_mul_f32_e32 v58, v57, v57
	v_fmac_f32_e32 v49, v50, v50
	v_fmac_f32_e32 v58, v56, v56
	v_add_f32_e32 v49, v49, v58
	v_add_f32_e32 v48, v48, v49
	v_add_f32_e32 v58, v104, v48
	v_cvt_pk_bf16_f32 v48, v52, v53
	v_cvt_pk_bf16_f32 v49, v54, v55
	v_cvt_pk_bf16_f32 v50, v50, v51
	v_cvt_pk_bf16_f32 v51, v56, v57
	global_store_dwordx4 v[60:61], v[48:51], off offset:256
	s_nop 1
	v_mov_b32_e32 v48, v201
	v_mov_b32_e32 v49, v201
	v_lshlrev_b32_e32 v48, 2, v48
	v_xor_b32_e32 v48, 64, v48
	v_mov_b32_e32 v48, v58
	s_nop 1
	v_permlane16_swap_b32_e32 v48, v58
	s_waitcnt lgkmcnt(0)
	v_add_f32_e32 v48, v58, v48
	v_lshlrev_b32_e32 v49, 2, v49
	v_xor_b32_e32 v49, 0x80, v49
	v_mov_b32_e32 v49, v48
	s_nop 1
	v_permlane32_swap_b32_e32 v49, v48
	s_and_saveexec_b64 s[52:53], s[16:17]
	s_cbranch_execz .LBB0_1091
	s_waitcnt lgkmcnt(0)
	v_add_f32_e32 v50, v48, v49
	v_lshlrev_b64 v[48:49], 6, v[100:101]
	v_lshl_add_u64 v[48:49], s[42:43], 0, v[48:49]
	v_lshl_add_u64 v[48:49], s[50:51], 2, v[48:49]
	s_lshl_b32 s22, s61, 2
	v_lshl_add_u64 v[48:49], v[48:49], 0, s[22:23]
	global_store_dword v[48:49], v50, off
.LBB0_1091:
	s_or_b64 exec, exec, s[52:53]
	s_waitcnt vmcnt(7)
	v_lshlrev_b32_e32 v48, 16, v220
	s_waitcnt lgkmcnt(0)
	v_and_b32_e32 v49, 0xffff0000, v220
	v_lshlrev_b32_e32 v50, 16, v221
	v_and_b32_e32 v51, 0xffff0000, v221
	v_lshlrev_b32_e32 v52, 16, v222
	v_and_b32_e32 v53, 0xffff0000, v222
	v_lshlrev_b32_e32 v54, 16, v223
	v_and_b32_e32 v55, 0xffff0000, v223
	v_pk_add_f32 v[46:47], v[46:47], v[50:51]
	v_pk_add_f32 v[44:45], v[44:45], v[48:49]
	v_pk_add_f32 v[48:49], v[42:43], v[54:55]
	v_pk_add_f32 v[42:43], v[40:41], v[52:53]
	v_mul_f32_e32 v40, v45, v45
	v_mul_f32_e32 v41, v47, v47
	v_fmac_f32_e32 v40, v44, v44
	v_fmac_f32_e32 v41, v46, v46
	v_add_f32_e32 v40, v40, v41
	v_mul_f32_e32 v41, v43, v43
	v_mul_f32_e32 v50, v49, v49
	v_fmac_f32_e32 v41, v42, v42
	v_fmac_f32_e32 v50, v48, v48
	v_add_f32_e32 v41, v41, v50
	v_add_f32_e32 v50, v40, v41
	v_cvt_pk_bf16_f32 v40, v44, v45
	v_lshl_add_u64 v[44:45], s[26:27], 0, v[98:99]
	v_cvt_pk_bf16_f32 v41, v46, v47
	v_cvt_pk_bf16_f32 v42, v42, v43
	v_cvt_pk_bf16_f32 v43, v48, v49
	v_lshl_add_u64 v[44:45], v[168:169], 1, v[44:45]
	global_store_dwordx4 v[44:45], v[40:43], off
	s_waitcnt vmcnt(7)
	v_lshlrev_b32_e32 v46, 16, v226
	v_and_b32_e32 v47, 0xffff0000, v226
	v_lshlrev_b32_e32 v40, 16, v224
	v_and_b32_e32 v41, 0xffff0000, v224
	v_lshlrev_b32_e32 v42, 16, v225
	v_and_b32_e32 v43, 0xffff0000, v225
	v_lshlrev_b32_e32 v48, 16, v227
	v_and_b32_e32 v49, 0xffff0000, v227
	v_pk_add_f32 v[38:39], v[38:39], v[42:43]
	v_pk_add_f32 v[36:37], v[36:37], v[40:41]
	v_pk_add_f32 v[40:41], v[34:35], v[48:49]
	v_pk_add_f32 v[34:35], v[32:33], v[46:47]
	v_mul_f32_e32 v32, v37, v37
	v_mul_f32_e32 v33, v39, v39
	v_fmac_f32_e32 v32, v36, v36
	v_fmac_f32_e32 v33, v38, v38
	v_add_f32_e32 v32, v32, v33
	v_mul_f32_e32 v33, v35, v35
	v_mul_f32_e32 v42, v41, v41
	v_fmac_f32_e32 v33, v34, v34
	v_fmac_f32_e32 v42, v40, v40
	v_add_f32_e32 v33, v33, v42
	v_add_f32_e32 v32, v32, v33
	v_add_f32_e32 v42, v50, v32
	v_cvt_pk_bf16_f32 v32, v36, v37
	v_cvt_pk_bf16_f32 v33, v38, v39
	v_cvt_pk_bf16_f32 v34, v34, v35
	v_cvt_pk_bf16_f32 v35, v40, v41
	global_store_dwordx4 v[44:45], v[32:35], off offset:256
	s_nop 1
	v_mov_b32_e32 v32, v201
	v_mov_b32_e32 v33, v201
	v_lshlrev_b32_e32 v32, 2, v32
	v_xor_b32_e32 v32, 64, v32
	v_mov_b32_e32 v32, v42
	s_nop 1
	v_permlane16_swap_b32_e32 v32, v42
	s_waitcnt lgkmcnt(0)
	v_add_f32_e32 v32, v42, v32
	v_lshlrev_b32_e32 v33, 2, v33
	v_xor_b32_e32 v33, 0x80, v33
	v_mov_b32_e32 v33, v32
	s_nop 1
	v_permlane32_swap_b32_e32 v33, v32
	s_and_saveexec_b64 s[52:53], s[16:17]
	s_cbranch_execz .LBB0_1093
	s_waitcnt lgkmcnt(0)
	v_add_f32_e32 v34, v32, v33
	v_lshlrev_b64 v[32:33], 6, v[96:97]
	v_lshl_add_u64 v[32:33], s[42:43], 0, v[32:33]
	v_lshl_add_u64 v[32:33], s[50:51], 2, v[32:33]
	s_lshl_b32 s22, s61, 2
	v_lshl_add_u64 v[32:33], v[32:33], 0, s[22:23]
	global_store_dword v[32:33], v34, off
; __device__ __forceinline__ float sq4(f32x4 v) { return (v[0] * v[0] + v[1] * v[1]) + (v[2] * v[2] + v[3] * v[3]); }
; __device__ __forceinline__ u32x4 pack8(f32x4 a, f32x4 b) { u32x4 w; w.x = cvt_pk_bf16(a[0], a[1]); w.y = cvt_pk_bf16(a[2], a[3]); w.z = cvt_pk_bf16(b[0], b[1]); w.w = cvt_pk_bf16(b[2], b[3]); return w; }
;     __device__ __forceinline__ void operator()(const f32x4 (&acc)[2][2][4][2], const Unit& u, int wr, int wc, int fr, int fq) const {
;     ...
;         for (int ai = 0; ai < 2; ++ai) {
;             u32x4 bs[4][2];
; #pragma unroll
;             for (int m = 0; m < 4; ++m)
; #pragma unroll
;                 for (int bj = 0; bj < 2; ++bj) bs[m][bj] = *(const u32x4*)(xb + (size_t)(u.pm * BM + ai * HALF + wr * 64 + m * 16 + fr) * 1024 + col0 + 128 * bj);
; #pragma unroll
;             for (int m = 0; m < 4; ++m) {
;                 const int row = u.pm * BM + ai * HALF + wr * 64 + m * 16 + fr;
;                 float q = 0.f;
; #pragma unroll
;                 for (int bj = 0; bj < 2; ++bj) {
;                     const size_t off = (size_t)row * 1024 + col0 + 128 * bj; const u32x4 w = bs[m][bj];
;                     const f32x4 b0 = (f32x4){__builtin_bit_cast(float, w.x << 16), __builtin_bit_cast(float, w.x & 0xffff0000u), __builtin_bit_cast(float, w.y << 16), __builtin_bit_cast(float, w.y & 0xffff0000u)};
;                     const f32x4 b1 = (f32x4){__builtin_bit_cast(float, w.z << 16), __builtin_bit_cast(float, w.z & 0xffff0000u), __builtin_bit_cast(float, w.w << 16), __builtin_bit_cast(float, w.w & 0xffff0000u)};
;                     const f32x4 v0 = acc[ai][bj][m][0] + b0, v1 = acc[ai][bj][m][1] + b1;
;                     if (last) { __builtin_nontemporal_store(v0, (f32x4*)(out + off)); __builtin_nontemporal_store(v1, (f32x4*)(out + off + 4)); }
;                     else { q += sq4(v0) + sq4(v1); *(u32x4*)(xb + off) = pack8(v0, v1); }
;                 }
;                 if (!last) { q += shx(q, 16); q += shx(q, 32); if (fq == 0) ss[(size_t)row * 16 + u.pn * 4 + wc] = q; }
.LBB0_1093:
	s_or_b64 exec, exec, s[52:53]
	s_waitcnt vmcnt(7)
	v_lshlrev_b32_e32 v32, 16, v228
	s_waitcnt lgkmcnt(0)
	v_and_b32_e32 v33, 0xffff0000, v228
	v_lshlrev_b32_e32 v34, 16, v229
	v_and_b32_e32 v35, 0xffff0000, v229
	v_lshlrev_b32_e32 v36, 16, v230
	v_and_b32_e32 v37, 0xffff0000, v230
	v_lshlrev_b32_e32 v38, 16, v231
	v_and_b32_e32 v39, 0xffff0000, v231
	v_pk_add_f32 v[30:31], v[30:31], v[34:35]
	v_pk_add_f32 v[28:29], v[28:29], v[32:33]
	v_pk_add_f32 v[32:33], v[26:27], v[38:39]
	v_pk_add_f32 v[26:27], v[24:25], v[36:37]
	v_mul_f32_e32 v24, v29, v29
	v_mul_f32_e32 v25, v31, v31
	v_fmac_f32_e32 v24, v28, v28
	v_fmac_f32_e32 v25, v30, v30
	v_add_f32_e32 v24, v24, v25
	v_mul_f32_e32 v25, v27, v27
	v_mul_f32_e32 v34, v33, v33
	v_fmac_f32_e32 v25, v26, v26
	v_fmac_f32_e32 v34, v32, v32
	v_add_f32_e32 v25, v25, v34
	v_add_f32_e32 v34, v24, v25
	v_cvt_pk_bf16_f32 v24, v28, v29
	v_lshl_add_u64 v[28:29], s[26:27], 0, v[94:95]
	v_cvt_pk_bf16_f32 v25, v30, v31
	v_cvt_pk_bf16_f32 v26, v26, v27
	v_cvt_pk_bf16_f32 v27, v32, v33
	v_lshl_add_u64 v[28:29], v[168:169], 1, v[28:29]
	global_store_dwordx4 v[28:29], v[24:27], off
	s_waitcnt vmcnt(7)
	v_lshlrev_b32_e32 v30, 16, v234
	v_and_b32_e32 v31, 0xffff0000, v234
	v_lshlrev_b32_e32 v24, 16, v232
	v_and_b32_e32 v25, 0xffff0000, v232
	v_lshlrev_b32_e32 v26, 16, v233
	v_and_b32_e32 v27, 0xffff0000, v233
	v_lshlrev_b32_e32 v32, 16, v235
	v_and_b32_e32 v33, 0xffff0000, v235
	v_pk_add_f32 v[22:23], v[22:23], v[26:27]
	v_pk_add_f32 v[20:21], v[20:21], v[24:25]
	v_pk_add_f32 v[24:25], v[18:19], v[32:33]
	v_pk_add_f32 v[18:19], v[16:17], v[30:31]
	v_mul_f32_e32 v16, v21, v21
	v_mul_f32_e32 v17, v23, v23
	v_fmac_f32_e32 v16, v20, v20
	v_fmac_f32_e32 v17, v22, v22
	v_add_f32_e32 v16, v16, v17
	v_mul_f32_e32 v17, v19, v19
	v_mul_f32_e32 v26, v25, v25
	v_fmac_f32_e32 v17, v18, v18
	v_fmac_f32_e32 v26, v24, v24
	v_add_f32_e32 v17, v17, v26
	v_add_f32_e32 v16, v16, v17
	v_add_f32_e32 v26, v34, v16
	v_cvt_pk_bf16_f32 v16, v20, v21
	v_cvt_pk_bf16_f32 v17, v22, v23
	v_cvt_pk_bf16_f32 v18, v18, v19
	v_cvt_pk_bf16_f32 v19, v24, v25
	global_store_dwordx4 v[28:29], v[16:19], off offset:256
	s_nop 1
	v_mov_b32_e32 v16, v201
	v_mov_b32_e32 v17, v201
	v_lshlrev_b32_e32 v16, 2, v16
	v_xor_b32_e32 v16, 64, v16
	v_mov_b32_e32 v16, v26
	s_nop 1
	v_permlane16_swap_b32_e32 v16, v26
	s_waitcnt lgkmcnt(0)
	v_add_f32_e32 v16, v26, v16
	v_lshlrev_b32_e32 v17, 2, v17
	v_xor_b32_e32 v17, 0x80, v17
	v_mov_b32_e32 v17, v16
	s_nop 1
	v_permlane32_swap_b32_e32 v17, v16
	s_and_saveexec_b64 s[52:53], s[16:17]
	s_cbranch_execz .LBB0_1095
	s_waitcnt lgkmcnt(0)
	v_add_f32_e32 v18, v16, v17
	v_lshlrev_b64 v[16:17], 6, v[92:93]
	v_lshl_add_u64 v[16:17], s[42:43], 0, v[16:17]
	v_lshl_add_u64 v[16:17], s[50:51], 2, v[16:17]
	s_lshl_b32 s22, s61, 2
	v_lshl_add_u64 v[16:17], v[16:17], 0, s[22:23]
	global_store_dword v[16:17], v18, off
.LBB0_1095:
	s_or_b64 exec, exec, s[52:53]
	s_waitcnt vmcnt(7)
	v_lshlrev_b32_e32 v16, 16, v236
	s_waitcnt lgkmcnt(0)
	v_and_b32_e32 v17, 0xffff0000, v236
	v_lshlrev_b32_e32 v18, 16, v237
	v_and_b32_e32 v19, 0xffff0000, v237
	v_lshlrev_b32_e32 v20, 16, v238
	v_and_b32_e32 v21, 0xffff0000, v238
	v_lshlrev_b32_e32 v22, 16, v239
	v_and_b32_e32 v23, 0xffff0000, v239
	v_pk_add_f32 v[14:15], v[14:15], v[18:19]
	v_pk_add_f32 v[12:13], v[12:13], v[16:17]
	v_pk_add_f32 v[16:17], v[10:11], v[22:23]
	v_pk_add_f32 v[10:11], v[8:9], v[20:21]
	v_mul_f32_e32 v8, v13, v13
	v_mul_f32_e32 v9, v15, v15
	v_fmac_f32_e32 v8, v12, v12
	v_fmac_f32_e32 v9, v14, v14
	v_add_f32_e32 v8, v8, v9
	v_mul_f32_e32 v9, v11, v11
	v_mul_f32_e32 v18, v17, v17
	v_fmac_f32_e32 v9, v10, v10
	v_fmac_f32_e32 v18, v16, v16
	v_add_f32_e32 v9, v9, v18
	v_add_f32_e32 v18, v8, v9
	v_cvt_pk_bf16_f32 v8, v12, v13
	v_lshl_add_u64 v[12:13], s[26:27], 0, v[90:91]
	v_cvt_pk_bf16_f32 v9, v14, v15
	v_cvt_pk_bf16_f32 v10, v10, v11
	v_cvt_pk_bf16_f32 v11, v16, v17
	v_lshl_add_u64 v[12:13], v[168:169], 1, v[12:13]
	global_store_dwordx4 v[12:13], v[8:11], off
	s_waitcnt vmcnt(7)
	v_lshlrev_b32_e32 v14, 16, v242
	v_and_b32_e32 v15, 0xffff0000, v242
	v_lshlrev_b32_e32 v8, 16, v240
	v_and_b32_e32 v9, 0xffff0000, v240
	v_lshlrev_b32_e32 v10, 16, v241
	v_and_b32_e32 v11, 0xffff0000, v241
	v_lshlrev_b32_e32 v16, 16, v243
	v_and_b32_e32 v17, 0xffff0000, v243
	v_pk_add_f32 v[6:7], v[6:7], v[10:11]
	v_pk_add_f32 v[4:5], v[4:5], v[8:9]
	v_pk_add_f32 v[8:9], v[2:3], v[16:17]
	v_pk_add_f32 v[2:3], v[0:1], v[14:15]
	v_mul_f32_e32 v0, v5, v5
	v_mul_f32_e32 v1, v7, v7
	v_fmac_f32_e32 v0, v4, v4
	v_fmac_f32_e32 v1, v6, v6
	v_add_f32_e32 v0, v0, v1
	v_mul_f32_e32 v1, v3, v3
	v_mul_f32_e32 v10, v9, v9
	v_fmac_f32_e32 v1, v2, v2
	v_fmac_f32_e32 v10, v8, v8
	v_add_f32_e32 v1, v1, v10
	v_add_f32_e32 v0, v0, v1
	v_add_f32_e32 v10, v18, v0
	v_cvt_pk_bf16_f32 v0, v4, v5
	v_cvt_pk_bf16_f32 v1, v6, v7
	v_cvt_pk_bf16_f32 v2, v2, v3
	v_cvt_pk_bf16_f32 v3, v8, v9
	global_store_dwordx4 v[12:13], v[0:3], off offset:256
	s_nop 1
	v_mov_b32_e32 v0, v201
	v_mov_b32_e32 v1, v201
	v_lshlrev_b32_e32 v0, 2, v0
	v_xor_b32_e32 v0, 64, v0
	v_mov_b32_e32 v0, v10
	s_nop 1
	v_permlane16_swap_b32_e32 v0, v10
	s_waitcnt lgkmcnt(0)
	v_add_f32_e32 v0, v10, v0
	v_lshlrev_b32_e32 v1, 2, v1
	v_xor_b32_e32 v1, 0x80, v1
	v_mov_b32_e32 v1, v0
	s_nop 1
	v_permlane32_swap_b32_e32 v1, v0
	s_and_saveexec_b64 s[52:53], s[16:17]
	s_cbranch_execz .LBB0_1097
	s_waitcnt lgkmcnt(0)
	v_add_f32_e32 v2, v0, v1
	v_lshlrev_b64 v[0:1], 6, v[88:89]
	v_lshl_add_u64 v[0:1], s[42:43], 0, v[0:1]
	v_lshl_add_u64 v[0:1], s[50:51], 2, v[0:1]
	s_lshl_b32 s22, s61, 2
	v_lshl_add_u64 v[0:1], v[0:1], 0, s[22:23]
	global_store_dword v[0:1], v2, off

; __device__ __forceinline__ float sq4(f32x4 v) { return (v[0] * v[0] + v[1] * v[1]) + (v[2] * v[2] + v[3] * v[3]); }
; __device__ __forceinline__ u32x4 pack8(f32x4 a, f32x4 b) { u32x4 w; w.x = cvt_pk_bf16(a[0], a[1]); w.y = cvt_pk_bf16(a[2], a[3]); w.z = cvt_pk_bf16(b[0], b[1]); w.w = cvt_pk_bf16(b[2], b[3]); return w; }
;     __device__ __forceinline__ void operator()(const f32x4 (&acc)[2][2][4][2], const Unit& u, int wr, int wc, int fr, int fq) const {
;         const int col0 = u.pn * 256 + 32 * wc + 8 * fq;
; #pragma unroll
;         for (int ai = 0; ai < 2; ++ai) {
;             u32x4 bs[4][2];
; #pragma unroll
;             for (int m = 0; m < 4; ++m)
; #pragma unroll
;                 for (int bj = 0; bj < 2; ++bj) bs[m][bj] = *(const u32x4*)(xb + (size_t)(u.pm * BM + ai * HALF + wr * 64 + m * 16 + fr) * 1024 + col0 + 128 * bj);
; #pragma unroll
;             for (int m = 0; m < 4; ++m) {
;                 const int row = u.pm * BM + ai * HALF + wr * 64 + m * 16 + fr;
;                 float q = 0.f;
; #pragma unroll
;                 for (int bj = 0; bj < 2; ++bj) {
;                     const size_t off = (size_t)row * 1024 + col0 + 128 * bj; const u32x4 w = bs[m][bj];
;                     const f32x4 b0 = (f32x4){__builtin_bit_cast(float, w.x << 16), __builtin_bit_cast(float, w.x & 0xffff0000u), __builtin_bit_cast(float, w.y << 16), __builtin_bit_cast(float, w.y & 0xffff0000u)};
;                     const f32x4 b1 = (f32x4){__builtin_bit_cast(float, w.z << 16), __builtin_bit_cast(float, w.z & 0xffff0000u), __builtin_bit_cast(float, w.w << 16), __builtin_bit_cast(float, w.w & 0xffff0000u)};
;                     const f32x4 v0 = acc[ai][bj][m][0] + b0, v1 = acc[ai][bj][m][1] + b1;
;                     if (last) { __builtin_nontemporal_store(v0, (f32x4*)(out + off)); __builtin_nontemporal_store(v1, (f32x4*)(out + off + 4)); }
;                     else { q += sq4(v0) + sq4(v1); *(u32x4*)(xb + off) = pack8(v0, v1); }
;                 }
;                 if (!last) { q += shx(q, 16); q += shx(q, 32); if (fq == 0) ss[(size_t)row * 16 + u.pn * 4 + wc] = q; }
.LBB0_1507:
	v_lshl_or_b32 v168, s16, 8, v188
	v_lshl_add_u32 v172, s50, 8, v186
	v_ashrrev_i32_e32 v169, 31, v168
	v_lshlrev_b64 v[202:203], 1, v[168:169]
	v_ashrrev_i32_e32 v173, 31, v172
	v_lshl_add_u64 v[170:171], s[20:21], 0, v[202:203]
	v_lshlrev_b64 v[204:205], 11, v[172:173]
	v_lshl_add_u64 v[120:121], v[170:171], 0, v[204:205]
	global_load_dwordx4 v[192:195], v[120:121], off
	global_load_dwordx4 v[196:199], v[120:121], off offset:256
	v_or_b32_e32 v182, 16, v172
	v_ashrrev_i32_e32 v183, 31, v182
	v_or_b32_e32 v178, 32, v172
	v_lshlrev_b64 v[184:185], 11, v[182:183]
	v_ashrrev_i32_e32 v179, 31, v178
	v_or_b32_e32 v174, 48, v172
	v_lshl_add_u64 v[120:121], v[170:171], 0, v[184:185]
	v_lshlrev_b64 v[180:181], 11, v[178:179]
	v_ashrrev_i32_e32 v175, 31, v174
	global_load_dwordx4 v[148:151], v[120:121], off
	global_load_dwordx4 v[144:147], v[120:121], off offset:256
	v_lshl_add_u64 v[120:121], v[170:171], 0, v[180:181]
	v_lshlrev_b64 v[176:177], 11, v[174:175]
	global_load_dwordx4 v[140:143], v[120:121], off
	global_load_dwordx4 v[136:139], v[120:121], off offset:256
	v_lshl_add_u64 v[120:121], v[170:171], 0, v[176:177]
	global_load_dwordx4 v[132:135], v[120:121], off
	s_nop 0
	global_load_dwordx4 v[120:123], v[120:121], off offset:256
	v_add_u32_e32 v210, 0x80, v172
	v_ashrrev_i32_e32 v211, 31, v210
	v_lshlrev_b64 v[210:211], 11, v[210:211]
	v_lshl_add_u64 v[210:211], v[170:171], 0, v[210:211]
	global_load_dwordx4 v[212:215], v[210:211], off
	global_load_dwordx4 v[216:219], v[210:211], off offset:256
	v_add_u32_e32 v210, 0x90, v172
	v_ashrrev_i32_e32 v211, 31, v210
	v_lshlrev_b64 v[210:211], 11, v[210:211]
	v_lshl_add_u64 v[210:211], v[170:171], 0, v[210:211]
	global_load_dwordx4 v[220:223], v[210:211], off
	global_load_dwordx4 v[224:227], v[210:211], off offset:256
	v_add_u32_e32 v210, 0xa0, v172
	v_ashrrev_i32_e32 v211, 31, v210
	v_lshlrev_b64 v[210:211], 11, v[210:211]
	v_lshl_add_u64 v[210:211], v[170:171], 0, v[210:211]
	global_load_dwordx4 v[228:231], v[210:211], off
	global_load_dwordx4 v[232:235], v[210:211], off offset:256
	v_add_u32_e32 v210, 0xb0, v172
	v_ashrrev_i32_e32 v211, 31, v210
	v_lshlrev_b64 v[210:211], 11, v[210:211]
	v_lshl_add_u64 v[210:211], v[170:171], 0, v[210:211]
	global_load_dwordx4 v[236:239], v[210:211], off
	global_load_dwordx4 v[240:243], v[210:211], off offset:256
	s_lshl_b32 s50, s16, 2
	s_ashr_i32 s51, s50, 31
	s_waitcnt vmcnt(8)
	v_lshlrev_b32_e32 v206, 16, v192
	v_and_b32_e32 v207, 0xffff0000, v192
	v_lshlrev_b32_e32 v192, 16, v193
	v_and_b32_e32 v193, 0xffff0000, v193
	v_lshlrev_b32_e32 v208, 16, v194
	v_and_b32_e32 v209, 0xffff0000, v194
	v_lshlrev_b32_e32 v194, 16, v195
	v_and_b32_e32 v195, 0xffff0000, v195
	v_pk_add_f32 v[130:131], v[130:131], v[192:193]
	v_pk_add_f32 v[128:129], v[128:129], v[206:207]
	v_pk_add_f32 v[192:193], v[126:127], v[194:195]
	v_pk_add_f32 v[126:127], v[124:125], v[208:209]
	v_mul_f32_e32 v124, v129, v129
	v_mul_f32_e32 v125, v131, v131
	v_fmac_f32_e32 v124, v128, v128
	v_fmac_f32_e32 v125, v130, v130
	v_add_f32_e32 v124, v124, v125
	v_mul_f32_e32 v125, v127, v127
	v_mul_f32_e32 v194, v193, v193
	v_fmac_f32_e32 v125, v126, v126
	v_fmac_f32_e32 v194, v192, v192
	v_add_f32_e32 v125, v125, v194
	v_add_f32_e32 v194, v124, v125
	v_cvt_pk_bf16_f32 v124, v128, v129
	v_lshl_add_u64 v[128:129], s[20:21], 0, v[204:205]
	v_cvt_pk_bf16_f32 v125, v130, v131
	v_cvt_pk_bf16_f32 v126, v126, v127
	v_cvt_pk_bf16_f32 v127, v192, v193
	v_lshl_add_u64 v[128:129], v[128:129], 0, v[202:203]
	global_store_dwordx4 v[128:129], v[124:127], off
	v_lshlrev_b32_e32 v130, 16, v198
	v_and_b32_e32 v131, 0xffff0000, v198
	v_lshlrev_b32_e32 v124, 16, v196
	v_and_b32_e32 v125, 0xffff0000, v196
	v_lshlrev_b32_e32 v126, 16, v197
	v_and_b32_e32 v127, 0xffff0000, v197
	v_lshlrev_b32_e32 v192, 16, v199
	v_and_b32_e32 v193, 0xffff0000, v199
	v_pk_add_f32 v[118:119], v[118:119], v[126:127]
	v_pk_add_f32 v[116:117], v[116:117], v[124:125]
	v_pk_add_f32 v[124:125], v[114:115], v[192:193]
	v_pk_add_f32 v[114:115], v[112:113], v[130:131]
	v_mul_f32_e32 v112, v117, v117
	v_mul_f32_e32 v113, v119, v119
	v_fmac_f32_e32 v112, v116, v116
	v_fmac_f32_e32 v113, v118, v118
	v_add_f32_e32 v112, v112, v113
	v_mul_f32_e32 v113, v115, v115
	v_mul_f32_e32 v126, v125, v125
	v_fmac_f32_e32 v113, v114, v114
	v_fmac_f32_e32 v126, v124, v124
	v_add_f32_e32 v113, v113, v126
	v_add_f32_e32 v112, v112, v113
	v_add_f32_e32 v126, v194, v112
	v_cvt_pk_bf16_f32 v112, v116, v117
	v_cvt_pk_bf16_f32 v113, v118, v119
	v_cvt_pk_bf16_f32 v114, v114, v115
	v_cvt_pk_bf16_f32 v115, v124, v125
	global_store_dwordx4 v[128:129], v[112:115], off offset:256
	s_nop 1
	v_mov_b32_e32 v112, v201
	v_mov_b32_e32 v113, v201
	v_lshlrev_b32_e32 v112, 2, v112
	v_xor_b32_e32 v112, 64, v112
	v_mov_b32_e32 v112, v126
	s_nop 1
	v_permlane16_swap_b32_e32 v112, v126
	s_waitcnt lgkmcnt(0)
	v_add_f32_e32 v112, v126, v112
	v_lshlrev_b32_e32 v113, 2, v113
	v_xor_b32_e32 v113, 0x80, v113
	v_mov_b32_e32 v113, v112
	s_nop 1
	v_permlane32_swap_b32_e32 v113, v112
	s_and_saveexec_b64 s[52:53], s[8:9]
	s_cbranch_execz .LBB0_1509
	s_waitcnt lgkmcnt(0)
	v_add_f32_e32 v114, v112, v113
	v_lshlrev_b64 v[112:113], 6, v[172:173]
	v_lshl_add_u64 v[112:113], s[22:23], 0, v[112:113]
	v_lshl_add_u64 v[112:113], s[50:51], 2, v[112:113]
	s_lshl_b32 s16, s58, 2
	v_lshl_add_u64 v[112:113], v[112:113], 0, s[16:17]
	global_store_dword v[112:113], v114, off

; __device__ __forceinline__ float sq4(f32x4 v) { return (v[0] * v[0] + v[1] * v[1]) + (v[2] * v[2] + v[3] * v[3]); }
; __device__ __forceinline__ u32x4 pack8(f32x4 a, f32x4 b) { u32x4 w; w.x = cvt_pk_bf16(a[0], a[1]); w.y = cvt_pk_bf16(a[2], a[3]); w.z = cvt_pk_bf16(b[0], b[1]); w.w = cvt_pk_bf16(b[2], b[3]); return w; }
;     __device__ __forceinline__ void operator()(const f32x4 (&acc)[2][2][4][2], const Unit& u, int wr, int wc, int fr, int fq) const {
;     ...
;         for (int ai = 0; ai < 2; ++ai) {
;             u32x4 bs[4][2];
; #pragma unroll
;             for (int m = 0; m < 4; ++m)
; #pragma unroll
;                 for (int bj = 0; bj < 2; ++bj) bs[m][bj] = *(const u32x4*)(xb + (size_t)(u.pm * BM + ai * HALF + wr * 64 + m * 16 + fr) * 1024 + col0 + 128 * bj);
; #pragma unroll
;             for (int m = 0; m < 4; ++m) {
;                 const int row = u.pm * BM + ai * HALF + wr * 64 + m * 16 + fr;
;                 float q = 0.f;
; #pragma unroll
;                 for (int bj = 0; bj < 2; ++bj) {
;                     const size_t off = (size_t)row * 1024 + col0 + 128 * bj; const u32x4 w = bs[m][bj];
;                     const f32x4 b0 = (f32x4){__builtin_bit_cast(float, w.x << 16), __builtin_bit_cast(float, w.x & 0xffff0000u), __builtin_bit_cast(float, w.y << 16), __builtin_bit_cast(float, w.y & 0xffff0000u)};
;                     const f32x4 b1 = (f32x4){__builtin_bit_cast(float, w.z << 16), __builtin_bit_cast(float, w.z & 0xffff0000u), __builtin_bit_cast(float, w.w << 16), __builtin_bit_cast(float, w.w & 0xffff0000u)};
;                     const f32x4 v0 = acc[ai][bj][m][0] + b0, v1 = acc[ai][bj][m][1] + b1;
;                     if (last) { __builtin_nontemporal_store(v0, (f32x4*)(out + off)); __builtin_nontemporal_store(v1, (f32x4*)(out + off + 4)); }
;                     else { q += sq4(v0) + sq4(v1); *(u32x4*)(xb + off) = pack8(v0, v1); }
;                 }
;                 if (!last) { q += shx(q, 16); q += shx(q, 32); if (fq == 0) ss[(size_t)row * 16 + u.pn * 4 + wc] = q; }
.LBB0_1515:
	s_or_b64 exec, exec, s[52:53]
	v_add_u32_e32 v100, 0x80, v172
	v_ashrrev_i32_e32 v101, 31, v100
	v_lshlrev_b64 v[110:111], 11, v[100:101]
	s_waitcnt lgkmcnt(0)
	v_lshl_add_u64 v[64:65], v[170:171], 0, v[110:111]
	s_nop 0
	s_nop 0
	v_add_u32_e32 v96, 0x90, v172
	v_ashrrev_i32_e32 v97, 31, v96
	v_add_u32_e32 v92, 0xa0, v172
	v_lshlrev_b64 v[98:99], 11, v[96:97]
	v_ashrrev_i32_e32 v93, 31, v92
	v_add_u32_e32 v88, 0xb0, v172
	v_lshl_add_u64 v[64:65], v[170:171], 0, v[98:99]
	v_lshlrev_b64 v[94:95], 11, v[92:93]
	v_ashrrev_i32_e32 v89, 31, v88
	s_nop 0
	s_nop 0
	v_lshl_add_u64 v[64:65], v[170:171], 0, v[94:95]
	v_lshlrev_b64 v[90:91], 11, v[88:89]
	s_nop 0
	s_nop 0
	v_lshl_add_u64 v[64:65], v[170:171], 0, v[90:91]
	s_nop 0
	s_nop 0
	s_nop 0
	s_waitcnt vmcnt(7)
	v_lshlrev_b32_e32 v112, 16, v212
	v_and_b32_e32 v113, 0xffff0000, v212
	v_lshlrev_b32_e32 v102, 16, v213
	v_and_b32_e32 v103, 0xffff0000, v213
	v_lshlrev_b32_e32 v114, 16, v214
	v_and_b32_e32 v115, 0xffff0000, v214
	v_lshlrev_b32_e32 v104, 16, v215
	v_and_b32_e32 v105, 0xffff0000, v215
	v_pk_add_f32 v[62:63], v[62:63], v[102:103]
	v_pk_add_f32 v[60:61], v[60:61], v[112:113]
	v_pk_add_f32 v[102:103], v[58:59], v[104:105]
	v_pk_add_f32 v[58:59], v[56:57], v[114:115]
	v_mul_f32_e32 v56, v61, v61
	v_mul_f32_e32 v57, v63, v63
	v_fmac_f32_e32 v56, v60, v60
	v_fmac_f32_e32 v57, v62, v62
	v_add_f32_e32 v56, v56, v57
	v_mul_f32_e32 v57, v59, v59
	v_mul_f32_e32 v104, v103, v103
	v_fmac_f32_e32 v57, v58, v58
	v_fmac_f32_e32 v104, v102, v102
	v_add_f32_e32 v57, v57, v104
	v_add_f32_e32 v104, v56, v57
	v_cvt_pk_bf16_f32 v56, v60, v61
	v_lshl_add_u64 v[60:61], s[20:21], 0, v[110:111]
	v_cvt_pk_bf16_f32 v57, v62, v63
	v_cvt_pk_bf16_f32 v58, v58, v59
	v_cvt_pk_bf16_f32 v59, v102, v103
	v_lshl_add_u64 v[60:61], v[168:169], 1, v[60:61]
	global_store_dwordx4 v[60:61], v[56:59], off
	s_waitcnt vmcnt(7)
	v_lshlrev_b32_e32 v62, 16, v218
	v_and_b32_e32 v63, 0xffff0000, v218
	v_lshlrev_b32_e32 v56, 16, v216
	v_and_b32_e32 v57, 0xffff0000, v216
	v_lshlrev_b32_e32 v58, 16, v217
	v_and_b32_e32 v59, 0xffff0000, v217
	v_lshlrev_b32_e32 v102, 16, v219
	v_and_b32_e32 v103, 0xffff0000, v219
	v_pk_add_f32 v[54:55], v[54:55], v[58:59]
	v_pk_add_f32 v[52:53], v[52:53], v[56:57]
	v_pk_add_f32 v[56:57], v[50:51], v[102:103]
	v_pk_add_f32 v[50:51], v[48:49], v[62:63]
	v_mul_f32_e32 v48, v53, v53
	v_mul_f32_e32 v49, v55, v55
	v_fmac_f32_e32 v48, v52, v52
	v_fmac_f32_e32 v49, v54, v54
	v_add_f32_e32 v48, v48, v49
	v_mul_f32_e32 v49, v51, v51
	v_mul_f32_e32 v58, v57, v57
	v_fmac_f32_e32 v49, v50, v50
	v_fmac_f32_e32 v58, v56, v56
	v_add_f32_e32 v49, v49, v58
	v_add_f32_e32 v48, v48, v49
	v_add_f32_e32 v58, v104, v48
	v_cvt_pk_bf16_f32 v48, v52, v53
	v_cvt_pk_bf16_f32 v49, v54, v55
	v_cvt_pk_bf16_f32 v50, v50, v51
	v_cvt_pk_bf16_f32 v51, v56, v57
	global_store_dwordx4 v[60:61], v[48:51], off offset:256
	s_nop 1
	v_mov_b32_e32 v48, v201
	v_mov_b32_e32 v49, v201
	v_lshlrev_b32_e32 v48, 2, v48
	v_xor_b32_e32 v48, 64, v48
	v_mov_b32_e32 v48, v58
	s_nop 1
	v_permlane16_swap_b32_e32 v48, v58
	s_waitcnt lgkmcnt(0)
	v_add_f32_e32 v48, v58, v48
	v_lshlrev_b32_e32 v49, 2, v49
	v_xor_b32_e32 v49, 0x80, v49
	v_mov_b32_e32 v49, v48
	s_nop 1
	v_permlane32_swap_b32_e32 v49, v48
	s_and_saveexec_b64 s[52:53], s[8:9]
	s_cbranch_execz .LBB0_1517
	s_waitcnt lgkmcnt(0)
	v_add_f32_e32 v50, v48, v49
	v_lshlrev_b64 v[48:49], 6, v[100:101]
	v_lshl_add_u64 v[48:49], s[22:23], 0, v[48:49]
	v_lshl_add_u64 v[48:49], s[50:51], 2, v[48:49]
	s_lshl_b32 s16, s58, 2
	v_lshl_add_u64 v[48:49], v[48:49], 0, s[16:17]
	global_store_dword v[48:49], v50, off
.LBB0_1517:
	s_or_b64 exec, exec, s[52:53]
	s_waitcnt vmcnt(7)
	v_lshlrev_b32_e32 v48, 16, v220
	s_waitcnt lgkmcnt(0)
	v_and_b32_e32 v49, 0xffff0000, v220
	v_lshlrev_b32_e32 v50, 16, v221
	v_and_b32_e32 v51, 0xffff0000, v221
	v_lshlrev_b32_e32 v52, 16, v222
	v_and_b32_e32 v53, 0xffff0000, v222
	v_lshlrev_b32_e32 v54, 16, v223
	v_and_b32_e32 v55, 0xffff0000, v223
	v_pk_add_f32 v[46:47], v[46:47], v[50:51]
	v_pk_add_f32 v[44:45], v[44:45], v[48:49]
	v_pk_add_f32 v[48:49], v[42:43], v[54:55]
	v_pk_add_f32 v[42:43], v[40:41], v[52:53]
	v_mul_f32_e32 v40, v45, v45
	v_mul_f32_e32 v41, v47, v47
	v_fmac_f32_e32 v40, v44, v44
	v_fmac_f32_e32 v41, v46, v46
	v_add_f32_e32 v40, v40, v41
	v_mul_f32_e32 v41, v43, v43
	v_mul_f32_e32 v50, v49, v49
	v_fmac_f32_e32 v41, v42, v42
	v_fmac_f32_e32 v50, v48, v48
	v_add_f32_e32 v41, v41, v50
	v_add_f32_e32 v50, v40, v41
	v_cvt_pk_bf16_f32 v40, v44, v45
	v_lshl_add_u64 v[44:45], s[20:21], 0, v[98:99]
	v_cvt_pk_bf16_f32 v41, v46, v47
	v_cvt_pk_bf16_f32 v42, v42, v43
	v_cvt_pk_bf16_f32 v43, v48, v49
	v_lshl_add_u64 v[44:45], v[168:169], 1, v[44:45]
	global_store_dwordx4 v[44:45], v[40:43], off
	s_waitcnt vmcnt(7)
	v_lshlrev_b32_e32 v46, 16, v226
	v_and_b32_e32 v47, 0xffff0000, v226
	v_lshlrev_b32_e32 v40, 16, v224
	v_and_b32_e32 v41, 0xffff0000, v224
	v_lshlrev_b32_e32 v42, 16, v225
	v_and_b32_e32 v43, 0xffff0000, v225
	v_lshlrev_b32_e32 v48, 16, v227
	v_and_b32_e32 v49, 0xffff0000, v227
	v_pk_add_f32 v[38:39], v[38:39], v[42:43]
	v_pk_add_f32 v[36:37], v[36:37], v[40:41]
	v_pk_add_f32 v[40:41], v[34:35], v[48:49]
	v_pk_add_f32 v[34:35], v[32:33], v[46:47]
	v_mul_f32_e32 v32, v37, v37
	v_mul_f32_e32 v33, v39, v39
	v_fmac_f32_e32 v32, v36, v36
	v_fmac_f32_e32 v33, v38, v38
	v_add_f32_e32 v32, v32, v33
	v_mul_f32_e32 v33, v35, v35
	v_mul_f32_e32 v42, v41, v41
	v_fmac_f32_e32 v33, v34, v34
	v_fmac_f32_e32 v42, v40, v40
	v_add_f32_e32 v33, v33, v42
	v_add_f32_e32 v32, v32, v33
	v_add_f32_e32 v42, v50, v32
	v_cvt_pk_bf16_f32 v32, v36, v37
	v_cvt_pk_bf16_f32 v33, v38, v39
	v_cvt_pk_bf16_f32 v34, v34, v35
	v_cvt_pk_bf16_f32 v35, v40, v41
	global_store_dwordx4 v[44:45], v[32:35], off offset:256
	s_nop 1
	v_mov_b32_e32 v32, v201
	v_mov_b32_e32 v33, v201
	v_lshlrev_b32_e32 v32, 2, v32
	v_xor_b32_e32 v32, 64, v32
	v_mov_b32_e32 v32, v42
	s_nop 1
	v_permlane16_swap_b32_e32 v32, v42
	s_waitcnt lgkmcnt(0)
	v_add_f32_e32 v32, v42, v32
	v_lshlrev_b32_e32 v33, 2, v33
	v_xor_b32_e32 v33, 0x80, v33
	v_mov_b32_e32 v33, v32
	s_nop 1
	v_permlane32_swap_b32_e32 v33, v32
	s_and_saveexec_b64 s[52:53], s[8:9]
	s_cbranch_execz .LBB0_1519
	s_waitcnt lgkmcnt(0)
	v_add_f32_e32 v34, v32, v33
	v_lshlrev_b64 v[32:33], 6, v[96:97]
	v_lshl_add_u64 v[32:33], s[22:23], 0, v[32:33]
	v_lshl_add_u64 v[32:33], s[50:51], 2, v[32:33]
	s_lshl_b32 s16, s58, 2
	v_lshl_add_u64 v[32:33], v[32:33], 0, s[16:17]
	global_store_dword v[32:33], v34, off
; __device__ __forceinline__ float sq4(f32x4 v) { return (v[0] * v[0] + v[1] * v[1]) + (v[2] * v[2] + v[3] * v[3]); }
; __device__ __forceinline__ u32x4 pack8(f32x4 a, f32x4 b) { u32x4 w; w.x = cvt_pk_bf16(a[0], a[1]); w.y = cvt_pk_bf16(a[2], a[3]); w.z = cvt_pk_bf16(b[0], b[1]); w.w = cvt_pk_bf16(b[2], b[3]); return w; }
;     __device__ __forceinline__ void operator()(const f32x4 (&acc)[2][2][4][2], const Unit& u, int wr, int wc, int fr, int fq) const {
;     ...
;         for (int ai = 0; ai < 2; ++ai) {
;             u32x4 bs[4][2];
; #pragma unroll
;             for (int m = 0; m < 4; ++m)
; #pragma unroll
;                 for (int bj = 0; bj < 2; ++bj) bs[m][bj] = *(const u32x4*)(xb + (size_t)(u.pm * BM + ai * HALF + wr * 64 + m * 16 + fr) * 1024 + col0 + 128 * bj);
; #pragma unroll
;             for (int m = 0; m < 4; ++m) {
;                 const int row = u.pm * BM + ai * HALF + wr * 64 + m * 16 + fr;
;                 float q = 0.f;
; #pragma unroll
;                 for (int bj = 0; bj < 2; ++bj) {
;                     const size_t off = (size_t)row * 1024 + col0 + 128 * bj; const u32x4 w = bs[m][bj];
;                     const f32x4 b0 = (f32x4){__builtin_bit_cast(float, w.x << 16), __builtin_bit_cast(float, w.x & 0xffff0000u), __builtin_bit_cast(float, w.y << 16), __builtin_bit_cast(float, w.y & 0xffff0000u)};
;                     const f32x4 b1 = (f32x4){__builtin_bit_cast(float, w.z << 16), __builtin_bit_cast(float, w.z & 0xffff0000u), __builtin_bit_cast(float, w.w << 16), __builtin_bit_cast(float, w.w & 0xffff0000u)};
;                     const f32x4 v0 = acc[ai][bj][m][0] + b0, v1 = acc[ai][bj][m][1] + b1;
;                     if (last) { __builtin_nontemporal_store(v0, (f32x4*)(out + off)); __builtin_nontemporal_store(v1, (f32x4*)(out + off + 4)); }
;                     else { q += sq4(v0) + sq4(v1); *(u32x4*)(xb + off) = pack8(v0, v1); }
;                 }
;                 if (!last) { q += shx(q, 16); q += shx(q, 32); if (fq == 0) ss[(size_t)row * 16 + u.pn * 4 + wc] = q; }
.LBB0_1519:
	s_or_b64 exec, exec, s[52:53]
	s_waitcnt vmcnt(7)
	v_lshlrev_b32_e32 v32, 16, v228
	s_waitcnt lgkmcnt(0)
	v_and_b32_e32 v33, 0xffff0000, v228
	v_lshlrev_b32_e32 v34, 16, v229
	v_and_b32_e32 v35, 0xffff0000, v229
	v_lshlrev_b32_e32 v36, 16, v230
	v_and_b32_e32 v37, 0xffff0000, v230
	v_lshlrev_b32_e32 v38, 16, v231
	v_and_b32_e32 v39, 0xffff0000, v231
	v_pk_add_f32 v[30:31], v[30:31], v[34:35]
	v_pk_add_f32 v[28:29], v[28:29], v[32:33]
	v_pk_add_f32 v[32:33], v[26:27], v[38:39]
	v_pk_add_f32 v[26:27], v[24:25], v[36:37]
	v_mul_f32_e32 v24, v29, v29
	v_mul_f32_e32 v25, v31, v31
	v_fmac_f32_e32 v24, v28, v28
	v_fmac_f32_e32 v25, v30, v30
	v_add_f32_e32 v24, v24, v25
	v_mul_f32_e32 v25, v27, v27
	v_mul_f32_e32 v34, v33, v33
	v_fmac_f32_e32 v25, v26, v26
	v_fmac_f32_e32 v34, v32, v32
	v_add_f32_e32 v25, v25, v34
	v_add_f32_e32 v34, v24, v25
	v_cvt_pk_bf16_f32 v24, v28, v29
	v_lshl_add_u64 v[28:29], s[20:21], 0, v[94:95]
	v_cvt_pk_bf16_f32 v25, v30, v31
	v_cvt_pk_bf16_f32 v26, v26, v27
	v_cvt_pk_bf16_f32 v27, v32, v33
	v_lshl_add_u64 v[28:29], v[168:169], 1, v[28:29]
	global_store_dwordx4 v[28:29], v[24:27], off
	s_waitcnt vmcnt(7)
	v_lshlrev_b32_e32 v30, 16, v234
	v_and_b32_e32 v31, 0xffff0000, v234
	v_lshlrev_b32_e32 v24, 16, v232
	v_and_b32_e32 v25, 0xffff0000, v232
	v_lshlrev_b32_e32 v26, 16, v233
	v_and_b32_e32 v27, 0xffff0000, v233
	v_lshlrev_b32_e32 v32, 16, v235
	v_and_b32_e32 v33, 0xffff0000, v235
	v_pk_add_f32 v[22:23], v[22:23], v[26:27]
	v_pk_add_f32 v[20:21], v[20:21], v[24:25]
	v_pk_add_f32 v[24:25], v[18:19], v[32:33]
	v_pk_add_f32 v[18:19], v[16:17], v[30:31]
	v_mul_f32_e32 v16, v21, v21
	v_mul_f32_e32 v17, v23, v23
	v_fmac_f32_e32 v16, v20, v20
	v_fmac_f32_e32 v17, v22, v22
	v_add_f32_e32 v16, v16, v17
	v_mul_f32_e32 v17, v19, v19
	v_mul_f32_e32 v26, v25, v25
	v_fmac_f32_e32 v17, v18, v18
	v_fmac_f32_e32 v26, v24, v24
	v_add_f32_e32 v17, v17, v26
	v_add_f32_e32 v16, v16, v17
	v_add_f32_e32 v26, v34, v16
	v_cvt_pk_bf16_f32 v16, v20, v21
	v_cvt_pk_bf16_f32 v17, v22, v23
	v_cvt_pk_bf16_f32 v18, v18, v19
	v_cvt_pk_bf16_f32 v19, v24, v25
	global_store_dwordx4 v[28:29], v[16:19], off offset:256
	s_nop 1
	v_mov_b32_e32 v16, v201
	v_mov_b32_e32 v17, v201
	v_lshlrev_b32_e32 v16, 2, v16
	v_xor_b32_e32 v16, 64, v16
	v_mov_b32_e32 v16, v26
	s_nop 1
	v_permlane16_swap_b32_e32 v16, v26
	s_waitcnt lgkmcnt(0)
	v_add_f32_e32 v16, v26, v16
	v_lshlrev_b32_e32 v17, 2, v17
	v_xor_b32_e32 v17, 0x80, v17
	v_mov_b32_e32 v17, v16
	s_nop 1
	v_permlane32_swap_b32_e32 v17, v16
	s_and_saveexec_b64 s[52:53], s[8:9]
	s_cbranch_execz .LBB0_1521
	s_waitcnt lgkmcnt(0)
	v_add_f32_e32 v18, v16, v17
	v_lshlrev_b64 v[16:17], 6, v[92:93]
	v_lshl_add_u64 v[16:17], s[22:23], 0, v[16:17]
	v_lshl_add_u64 v[16:17], s[50:51], 2, v[16:17]
	s_lshl_b32 s16, s58, 2
	v_lshl_add_u64 v[16:17], v[16:17], 0, s[16:17]
	global_store_dword v[16:17], v18, off
.LBB0_1521:
	s_or_b64 exec, exec, s[52:53]
	s_waitcnt vmcnt(7)
	v_lshlrev_b32_e32 v16, 16, v236
	s_waitcnt lgkmcnt(0)
	v_and_b32_e32 v17, 0xffff0000, v236
	v_lshlrev_b32_e32 v18, 16, v237
	v_and_b32_e32 v19, 0xffff0000, v237
	v_lshlrev_b32_e32 v20, 16, v238
	v_and_b32_e32 v21, 0xffff0000, v238
	v_lshlrev_b32_e32 v22, 16, v239
	v_and_b32_e32 v23, 0xffff0000, v239
	v_pk_add_f32 v[14:15], v[14:15], v[18:19]
	v_pk_add_f32 v[12:13], v[12:13], v[16:17]
	v_pk_add_f32 v[16:17], v[10:11], v[22:23]
	v_pk_add_f32 v[10:11], v[8:9], v[20:21]
	v_mul_f32_e32 v8, v13, v13
	v_mul_f32_e32 v9, v15, v15
	v_fmac_f32_e32 v8, v12, v12
	v_fmac_f32_e32 v9, v14, v14
	v_add_f32_e32 v8, v8, v9
	v_mul_f32_e32 v9, v11, v11
	v_mul_f32_e32 v18, v17, v17
	v_fmac_f32_e32 v9, v10, v10
	v_fmac_f32_e32 v18, v16, v16
	v_add_f32_e32 v9, v9, v18
	v_add_f32_e32 v18, v8, v9
	v_cvt_pk_bf16_f32 v8, v12, v13
	v_lshl_add_u64 v[12:13], s[20:21], 0, v[90:91]
	v_cvt_pk_bf16_f32 v9, v14, v15
	v_cvt_pk_bf16_f32 v10, v10, v11
	v_cvt_pk_bf16_f32 v11, v16, v17
	v_lshl_add_u64 v[12:13], v[168:169], 1, v[12:13]
	global_store_dwordx4 v[12:13], v[8:11], off
	s_waitcnt vmcnt(7)
	v_lshlrev_b32_e32 v14, 16, v242
	v_and_b32_e32 v15, 0xffff0000, v242
	v_lshlrev_b32_e32 v8, 16, v240
	v_and_b32_e32 v9, 0xffff0000, v240
	v_lshlrev_b32_e32 v10, 16, v241
	v_and_b32_e32 v11, 0xffff0000, v241
	v_lshlrev_b32_e32 v16, 16, v243
	v_and_b32_e32 v17, 0xffff0000, v243
	v_pk_add_f32 v[6:7], v[6:7], v[10:11]
	v_pk_add_f32 v[4:5], v[4:5], v[8:9]
	v_pk_add_f32 v[8:9], v[2:3], v[16:17]
	v_pk_add_f32 v[2:3], v[0:1], v[14:15]
	v_mul_f32_e32 v0, v5, v5
	v_mul_f32_e32 v1, v7, v7
	v_fmac_f32_e32 v0, v4, v4
	v_fmac_f32_e32 v1, v6, v6
	v_add_f32_e32 v0, v0, v1
	v_mul_f32_e32 v1, v3, v3
	v_mul_f32_e32 v10, v9, v9
	v_fmac_f32_e32 v1, v2, v2
	v_fmac_f32_e32 v10, v8, v8
	v_add_f32_e32 v1, v1, v10
	v_add_f32_e32 v0, v0, v1
	v_add_f32_e32 v10, v18, v0
	v_cvt_pk_bf16_f32 v0, v4, v5
	v_cvt_pk_bf16_f32 v1, v6, v7
	v_cvt_pk_bf16_f32 v2, v2, v3
	v_cvt_pk_bf16_f32 v3, v8, v9
	global_store_dwordx4 v[12:13], v[0:3], off offset:256
	s_nop 1
	v_mov_b32_e32 v0, v201
	v_mov_b32_e32 v1, v201
	v_lshlrev_b32_e32 v0, 2, v0
	v_xor_b32_e32 v0, 64, v0
	v_mov_b32_e32 v0, v10
	s_nop 1
	v_permlane16_swap_b32_e32 v0, v10
	s_waitcnt lgkmcnt(0)
	v_add_f32_e32 v0, v10, v0
	v_lshlrev_b32_e32 v1, 2, v1
	v_xor_b32_e32 v1, 0x80, v1
	v_mov_b32_e32 v1, v0
	s_nop 1
	v_permlane32_swap_b32_e32 v1, v0
	s_and_saveexec_b64 s[52:53], s[8:9]
	s_cbranch_execz .LBB0_1523
	s_waitcnt lgkmcnt(0)
	v_add_f32_e32 v2, v0, v1
	v_lshlrev_b64 v[0:1], 6, v[88:89]
	v_lshl_add_u64 v[0:1], s[22:23], 0, v[0:1]
	v_lshl_add_u64 v[0:1], s[50:51], 2, v[0:1]
	s_lshl_b32 s16, s58, 2
	v_lshl_add_u64 v[0:1], v[0:1], 0, s[16:17]
	global_store_dword v[0:1], v2, off

; __device__ __forceinline__ float sq4(f32x4 v) { return (v[0] * v[0] + v[1] * v[1]) + (v[2] * v[2] + v[3] * v[3]); }
; __device__ __forceinline__ u32x4 pack8(f32x4 a, f32x4 b) { u32x4 w; w.x = cvt_pk_bf16(a[0], a[1]); w.y = cvt_pk_bf16(a[2], a[3]); w.z = cvt_pk_bf16(b[0], b[1]); w.w = cvt_pk_bf16(b[2], b[3]); return w; }
;     __device__ __forceinline__ void operator()(const f32x4 (&acc)[2][2][4][2], const Unit& u, int wr, int wc, int fr, int fq) const {
;         const int col0 = u.pn * 256 + 32 * wc + 8 * fq;
; #pragma unroll
;         for (int ai = 0; ai < 2; ++ai) {
;             u32x4 bs[4][2];
; #pragma unroll
;             for (int m = 0; m < 4; ++m)
; #pragma unroll
;                 for (int bj = 0; bj < 2; ++bj) bs[m][bj] = *(const u32x4*)(xb + (size_t)(u.pm * BM + ai * HALF + wr * 64 + m * 16 + fr) * 1024 + col0 + 128 * bj);
; #pragma unroll
;             for (int m = 0; m < 4; ++m) {
;                 const int row = u.pm * BM + ai * HALF + wr * 64 + m * 16 + fr;
;                 float q = 0.f;
; #pragma unroll
;                 for (int bj = 0; bj < 2; ++bj) {
;                     const size_t off = (size_t)row * 1024 + col0 + 128 * bj; const u32x4 w = bs[m][bj];
;                     const f32x4 b0 = (f32x4){__builtin_bit_cast(float, w.x << 16), __builtin_bit_cast(float, w.x & 0xffff0000u), __builtin_bit_cast(float, w.y << 16), __builtin_bit_cast(float, w.y & 0xffff0000u)};
;                     const f32x4 b1 = (f32x4){__builtin_bit_cast(float, w.z << 16), __builtin_bit_cast(float, w.z & 0xffff0000u), __builtin_bit_cast(float, w.w << 16), __builtin_bit_cast(float, w.w & 0xffff0000u)};
;                     const f32x4 v0 = acc[ai][bj][m][0] + b0, v1 = acc[ai][bj][m][1] + b1;
;                     if (last) { __builtin_nontemporal_store(v0, (f32x4*)(out + off)); __builtin_nontemporal_store(v1, (f32x4*)(out + off + 4)); }
;                     else { q += sq4(v0) + sq4(v1); *(u32x4*)(xb + off) = pack8(v0, v1); }
;                 }
;                 if (!last) { q += shx(q, 16); q += shx(q, 32); if (fq == 0) ss[(size_t)row * 16 + u.pn * 4 + wc] = q; }
.LBB0_1673:
	v_lshl_or_b32 v168, s18, 8, v188
	v_lshl_add_u32 v172, s65, 8, v186
	v_ashrrev_i32_e32 v169, 31, v168
	v_lshlrev_b64 v[202:203], 1, v[168:169]
	v_ashrrev_i32_e32 v173, 31, v172
	v_lshl_add_u64 v[170:171], s[22:23], 0, v[202:203]
	v_lshlrev_b64 v[204:205], 11, v[172:173]
	v_lshl_add_u64 v[120:121], v[170:171], 0, v[204:205]
	global_load_dwordx4 v[192:195], v[120:121], off
	global_load_dwordx4 v[196:199], v[120:121], off offset:256
	v_or_b32_e32 v182, 16, v172
	v_ashrrev_i32_e32 v183, 31, v182
	v_or_b32_e32 v178, 32, v172
	v_lshlrev_b64 v[184:185], 11, v[182:183]
	v_ashrrev_i32_e32 v179, 31, v178
	v_or_b32_e32 v174, 48, v172
	v_lshl_add_u64 v[120:121], v[170:171], 0, v[184:185]
	v_lshlrev_b64 v[180:181], 11, v[178:179]
	v_ashrrev_i32_e32 v175, 31, v174
	global_load_dwordx4 v[148:151], v[120:121], off
	global_load_dwordx4 v[144:147], v[120:121], off offset:256
	v_lshl_add_u64 v[120:121], v[170:171], 0, v[180:181]
	v_lshlrev_b64 v[176:177], 11, v[174:175]
	global_load_dwordx4 v[140:143], v[120:121], off
	global_load_dwordx4 v[136:139], v[120:121], off offset:256
	v_lshl_add_u64 v[120:121], v[170:171], 0, v[176:177]
	global_load_dwordx4 v[132:135], v[120:121], off
	s_nop 0
	global_load_dwordx4 v[120:123], v[120:121], off offset:256
	v_add_u32_e32 v210, 0x80, v172
	v_ashrrev_i32_e32 v211, 31, v210
	v_lshlrev_b64 v[210:211], 11, v[210:211]
	v_lshl_add_u64 v[210:211], v[170:171], 0, v[210:211]
	global_load_dwordx4 v[212:215], v[210:211], off
	global_load_dwordx4 v[216:219], v[210:211], off offset:256
	v_add_u32_e32 v210, 0x90, v172
	v_ashrrev_i32_e32 v211, 31, v210
	v_lshlrev_b64 v[210:211], 11, v[210:211]
	v_lshl_add_u64 v[210:211], v[170:171], 0, v[210:211]
	global_load_dwordx4 v[220:223], v[210:211], off
	global_load_dwordx4 v[224:227], v[210:211], off offset:256
	v_add_u32_e32 v210, 0xa0, v172
	v_ashrrev_i32_e32 v211, 31, v210
	v_lshlrev_b64 v[210:211], 11, v[210:211]
	v_lshl_add_u64 v[210:211], v[170:171], 0, v[210:211]
	global_load_dwordx4 v[228:231], v[210:211], off
	global_load_dwordx4 v[232:235], v[210:211], off offset:256
	v_add_u32_e32 v210, 0xb0, v172
	v_ashrrev_i32_e32 v211, 31, v210
	v_lshlrev_b64 v[210:211], 11, v[210:211]
	v_lshl_add_u64 v[210:211], v[170:171], 0, v[210:211]
	global_load_dwordx4 v[236:239], v[210:211], off
	global_load_dwordx4 v[240:243], v[210:211], off offset:256
	s_lshl_b32 s46, s18, 2
	s_ashr_i32 s47, s46, 31
	s_waitcnt vmcnt(8)
	v_lshlrev_b32_e32 v206, 16, v192
	v_and_b32_e32 v207, 0xffff0000, v192
	v_lshlrev_b32_e32 v192, 16, v193
	v_and_b32_e32 v193, 0xffff0000, v193
	v_lshlrev_b32_e32 v208, 16, v194
	v_and_b32_e32 v209, 0xffff0000, v194
	v_lshlrev_b32_e32 v194, 16, v195
	v_and_b32_e32 v195, 0xffff0000, v195
	v_pk_add_f32 v[130:131], v[130:131], v[192:193]
	v_pk_add_f32 v[128:129], v[128:129], v[206:207]
	v_pk_add_f32 v[192:193], v[126:127], v[194:195]
	v_pk_add_f32 v[126:127], v[124:125], v[208:209]
	v_mul_f32_e32 v124, v129, v129
	v_mul_f32_e32 v125, v131, v131
	v_fmac_f32_e32 v124, v128, v128
	v_fmac_f32_e32 v125, v130, v130
	v_add_f32_e32 v124, v124, v125
	v_mul_f32_e32 v125, v127, v127
	v_mul_f32_e32 v194, v193, v193
	v_fmac_f32_e32 v125, v126, v126
	v_fmac_f32_e32 v194, v192, v192
	v_add_f32_e32 v125, v125, v194
	v_add_f32_e32 v194, v124, v125
	v_cvt_pk_bf16_f32 v124, v128, v129
	v_lshl_add_u64 v[128:129], s[22:23], 0, v[204:205]
	v_cvt_pk_bf16_f32 v125, v130, v131
	v_cvt_pk_bf16_f32 v126, v126, v127
	v_cvt_pk_bf16_f32 v127, v192, v193
	v_lshl_add_u64 v[128:129], v[128:129], 0, v[202:203]
	global_store_dwordx4 v[128:129], v[124:127], off
	v_lshlrev_b32_e32 v130, 16, v198
	v_and_b32_e32 v131, 0xffff0000, v198
	v_lshlrev_b32_e32 v124, 16, v196
	v_and_b32_e32 v125, 0xffff0000, v196
	v_lshlrev_b32_e32 v126, 16, v197
	v_and_b32_e32 v127, 0xffff0000, v197
	v_lshlrev_b32_e32 v192, 16, v199
	v_and_b32_e32 v193, 0xffff0000, v199
	v_pk_add_f32 v[118:119], v[118:119], v[126:127]
	v_pk_add_f32 v[116:117], v[116:117], v[124:125]
	v_pk_add_f32 v[124:125], v[114:115], v[192:193]
	v_pk_add_f32 v[114:115], v[112:113], v[130:131]
	v_mul_f32_e32 v112, v117, v117
	v_mul_f32_e32 v113, v119, v119
	v_fmac_f32_e32 v112, v116, v116
	v_fmac_f32_e32 v113, v118, v118
	v_add_f32_e32 v112, v112, v113
	v_mul_f32_e32 v113, v115, v115
	v_mul_f32_e32 v126, v125, v125
	v_fmac_f32_e32 v113, v114, v114
	v_fmac_f32_e32 v126, v124, v124
	v_add_f32_e32 v113, v113, v126
	v_add_f32_e32 v112, v112, v113
	v_add_f32_e32 v126, v194, v112
	v_cvt_pk_bf16_f32 v112, v116, v117
	v_cvt_pk_bf16_f32 v113, v118, v119
	v_cvt_pk_bf16_f32 v114, v114, v115
	v_cvt_pk_bf16_f32 v115, v124, v125
	global_store_dwordx4 v[128:129], v[112:115], off offset:256
	s_nop 1
	v_mov_b32_e32 v112, v201
	v_mov_b32_e32 v113, v201
	v_lshlrev_b32_e32 v112, 2, v112
	v_xor_b32_e32 v112, 64, v112
	v_mov_b32_e32 v112, v126
	s_nop 1
	v_permlane16_swap_b32_e32 v112, v126
	s_waitcnt lgkmcnt(0)
	v_add_f32_e32 v112, v126, v112
	v_lshlrev_b32_e32 v113, 2, v113
	v_xor_b32_e32 v113, 0x80, v113
	v_mov_b32_e32 v113, v112
	s_nop 1
	v_permlane32_swap_b32_e32 v113, v112
	s_and_saveexec_b64 s[48:49], s[8:9]
	s_cbranch_execz .LBB0_1675
	s_waitcnt lgkmcnt(0)
	v_add_f32_e32 v114, v112, v113
	v_lshlrev_b64 v[112:113], 6, v[172:173]
	v_lshl_add_u64 v[112:113], s[24:25], 0, v[112:113]
	v_lshl_add_u64 v[112:113], s[46:47], 2, v[112:113]
	s_lshl_b32 s18, s54, 2
	v_lshl_add_u64 v[112:113], v[112:113], 0, s[18:19]
	global_store_dword v[112:113], v114, off

; __device__ __forceinline__ float sq4(f32x4 v) { return (v[0] * v[0] + v[1] * v[1]) + (v[2] * v[2] + v[3] * v[3]); }
; __device__ __forceinline__ u32x4 pack8(f32x4 a, f32x4 b) { u32x4 w; w.x = cvt_pk_bf16(a[0], a[1]); w.y = cvt_pk_bf16(a[2], a[3]); w.z = cvt_pk_bf16(b[0], b[1]); w.w = cvt_pk_bf16(b[2], b[3]); return w; }
;     __device__ __forceinline__ void operator()(const f32x4 (&acc)[2][2][4][2], const Unit& u, int wr, int wc, int fr, int fq) const {
;     ...
;         for (int ai = 0; ai < 2; ++ai) {
;             u32x4 bs[4][2];
; #pragma unroll
;             for (int m = 0; m < 4; ++m)
; #pragma unroll
;                 for (int bj = 0; bj < 2; ++bj) bs[m][bj] = *(const u32x4*)(xb + (size_t)(u.pm * BM + ai * HALF + wr * 64 + m * 16 + fr) * 1024 + col0 + 128 * bj);
; #pragma unroll
;             for (int m = 0; m < 4; ++m) {
;                 const int row = u.pm * BM + ai * HALF + wr * 64 + m * 16 + fr;
;                 float q = 0.f;
; #pragma unroll
;                 for (int bj = 0; bj < 2; ++bj) {
;                     const size_t off = (size_t)row * 1024 + col0 + 128 * bj; const u32x4 w = bs[m][bj];
;                     const f32x4 b0 = (f32x4){__builtin_bit_cast(float, w.x << 16), __builtin_bit_cast(float, w.x & 0xffff0000u), __builtin_bit_cast(float, w.y << 16), __builtin_bit_cast(float, w.y & 0xffff0000u)};
;                     const f32x4 b1 = (f32x4){__builtin_bit_cast(float, w.z << 16), __builtin_bit_cast(float, w.z & 0xffff0000u), __builtin_bit_cast(float, w.w << 16), __builtin_bit_cast(float, w.w & 0xffff0000u)};
;                     const f32x4 v0 = acc[ai][bj][m][0] + b0, v1 = acc[ai][bj][m][1] + b1;
;                     if (last) { __builtin_nontemporal_store(v0, (f32x4*)(out + off)); __builtin_nontemporal_store(v1, (f32x4*)(out + off + 4)); }
;                     else { q += sq4(v0) + sq4(v1); *(u32x4*)(xb + off) = pack8(v0, v1); }
;                 }
;                 if (!last) { q += shx(q, 16); q += shx(q, 32); if (fq == 0) ss[(size_t)row * 16 + u.pn * 4 + wc] = q; }
.LBB0_1681:
	s_or_b64 exec, exec, s[48:49]
	v_add_u32_e32 v100, 0x80, v172
	v_ashrrev_i32_e32 v101, 31, v100
	v_lshlrev_b64 v[110:111], 11, v[100:101]
	s_waitcnt lgkmcnt(0)
	v_lshl_add_u64 v[64:65], v[170:171], 0, v[110:111]
	s_nop 0
	s_nop 0
	v_add_u32_e32 v96, 0x90, v172
	v_ashrrev_i32_e32 v97, 31, v96
	v_add_u32_e32 v92, 0xa0, v172
	v_lshlrev_b64 v[98:99], 11, v[96:97]
	v_ashrrev_i32_e32 v93, 31, v92
	v_add_u32_e32 v88, 0xb0, v172
	v_lshl_add_u64 v[64:65], v[170:171], 0, v[98:99]
	v_lshlrev_b64 v[94:95], 11, v[92:93]
	v_ashrrev_i32_e32 v89, 31, v88
	s_nop 0
	s_nop 0
	v_lshl_add_u64 v[64:65], v[170:171], 0, v[94:95]
	v_lshlrev_b64 v[90:91], 11, v[88:89]
	s_nop 0
	s_nop 0
	v_lshl_add_u64 v[64:65], v[170:171], 0, v[90:91]
	s_nop 0
	s_nop 0
	s_nop 0
	s_waitcnt vmcnt(7)
	v_lshlrev_b32_e32 v112, 16, v212
	v_and_b32_e32 v113, 0xffff0000, v212
	v_lshlrev_b32_e32 v102, 16, v213
	v_and_b32_e32 v103, 0xffff0000, v213
	v_lshlrev_b32_e32 v114, 16, v214
	v_and_b32_e32 v115, 0xffff0000, v214
	v_lshlrev_b32_e32 v104, 16, v215
	v_and_b32_e32 v105, 0xffff0000, v215
	v_pk_add_f32 v[62:63], v[62:63], v[102:103]
	v_pk_add_f32 v[60:61], v[60:61], v[112:113]
	v_pk_add_f32 v[102:103], v[58:59], v[104:105]
	v_pk_add_f32 v[58:59], v[56:57], v[114:115]
	v_mul_f32_e32 v56, v61, v61
	v_mul_f32_e32 v57, v63, v63
	v_fmac_f32_e32 v56, v60, v60
	v_fmac_f32_e32 v57, v62, v62
	v_add_f32_e32 v56, v56, v57
	v_mul_f32_e32 v57, v59, v59
	v_mul_f32_e32 v104, v103, v103
	v_fmac_f32_e32 v57, v58, v58
	v_fmac_f32_e32 v104, v102, v102
	v_add_f32_e32 v57, v57, v104
	v_add_f32_e32 v104, v56, v57
	v_cvt_pk_bf16_f32 v56, v60, v61
	v_lshl_add_u64 v[60:61], s[22:23], 0, v[110:111]
	v_cvt_pk_bf16_f32 v57, v62, v63
	v_cvt_pk_bf16_f32 v58, v58, v59
	v_cvt_pk_bf16_f32 v59, v102, v103
	v_lshl_add_u64 v[60:61], v[168:169], 1, v[60:61]
	global_store_dwordx4 v[60:61], v[56:59], off
	s_waitcnt vmcnt(7)
	v_lshlrev_b32_e32 v62, 16, v218
	v_and_b32_e32 v63, 0xffff0000, v218
	v_lshlrev_b32_e32 v56, 16, v216
	v_and_b32_e32 v57, 0xffff0000, v216
	v_lshlrev_b32_e32 v58, 16, v217
	v_and_b32_e32 v59, 0xffff0000, v217
	v_lshlrev_b32_e32 v102, 16, v219
	v_and_b32_e32 v103, 0xffff0000, v219
	v_pk_add_f32 v[54:55], v[54:55], v[58:59]
	v_pk_add_f32 v[52:53], v[52:53], v[56:57]
	v_pk_add_f32 v[56:57], v[50:51], v[102:103]
	v_pk_add_f32 v[50:51], v[48:49], v[62:63]
	v_mul_f32_e32 v48, v53, v53
	v_mul_f32_e32 v49, v55, v55
	v_fmac_f32_e32 v48, v52, v52
	v_fmac_f32_e32 v49, v54, v54
	v_add_f32_e32 v48, v48, v49
	v_mul_f32_e32 v49, v51, v51
	v_mul_f32_e32 v58, v57, v57
	v_fmac_f32_e32 v49, v50, v50
	v_fmac_f32_e32 v58, v56, v56
	v_add_f32_e32 v49, v49, v58
	v_add_f32_e32 v48, v48, v49
	v_add_f32_e32 v58, v104, v48
	v_cvt_pk_bf16_f32 v48, v52, v53
	v_cvt_pk_bf16_f32 v49, v54, v55
	v_cvt_pk_bf16_f32 v50, v50, v51
	v_cvt_pk_bf16_f32 v51, v56, v57
	global_store_dwordx4 v[60:61], v[48:51], off offset:256
	s_nop 1
	v_mov_b32_e32 v48, v201
	v_mov_b32_e32 v49, v201
	v_lshlrev_b32_e32 v48, 2, v48
	v_xor_b32_e32 v48, 64, v48
	v_mov_b32_e32 v48, v58
	s_nop 1
	v_permlane16_swap_b32_e32 v48, v58
	s_waitcnt lgkmcnt(0)
	v_add_f32_e32 v48, v58, v48
	v_lshlrev_b32_e32 v49, 2, v49
	v_xor_b32_e32 v49, 0x80, v49
	v_mov_b32_e32 v49, v48
	s_nop 1
	v_permlane32_swap_b32_e32 v49, v48
	s_and_saveexec_b64 s[48:49], s[8:9]
	s_cbranch_execz .LBB0_1683
	s_waitcnt lgkmcnt(0)
	v_add_f32_e32 v50, v48, v49
	v_lshlrev_b64 v[48:49], 6, v[100:101]
	v_lshl_add_u64 v[48:49], s[24:25], 0, v[48:49]
	v_lshl_add_u64 v[48:49], s[46:47], 2, v[48:49]
	s_lshl_b32 s18, s54, 2
	v_lshl_add_u64 v[48:49], v[48:49], 0, s[18:19]
	global_store_dword v[48:49], v50, off
.LBB0_1683:
	s_or_b64 exec, exec, s[48:49]
	s_waitcnt vmcnt(7)
	v_lshlrev_b32_e32 v48, 16, v220
	s_waitcnt lgkmcnt(0)
	v_and_b32_e32 v49, 0xffff0000, v220
	v_lshlrev_b32_e32 v50, 16, v221
	v_and_b32_e32 v51, 0xffff0000, v221
	v_lshlrev_b32_e32 v52, 16, v222
	v_and_b32_e32 v53, 0xffff0000, v222
	v_lshlrev_b32_e32 v54, 16, v223
	v_and_b32_e32 v55, 0xffff0000, v223
	v_pk_add_f32 v[46:47], v[46:47], v[50:51]
	v_pk_add_f32 v[44:45], v[44:45], v[48:49]
	v_pk_add_f32 v[48:49], v[42:43], v[54:55]
	v_pk_add_f32 v[42:43], v[40:41], v[52:53]
	v_mul_f32_e32 v40, v45, v45
	v_mul_f32_e32 v41, v47, v47
	v_fmac_f32_e32 v40, v44, v44
	v_fmac_f32_e32 v41, v46, v46
	v_add_f32_e32 v40, v40, v41
	v_mul_f32_e32 v41, v43, v43
	v_mul_f32_e32 v50, v49, v49
	v_fmac_f32_e32 v41, v42, v42
	v_fmac_f32_e32 v50, v48, v48
	v_add_f32_e32 v41, v41, v50
	v_add_f32_e32 v50, v40, v41
	v_cvt_pk_bf16_f32 v40, v44, v45
	v_lshl_add_u64 v[44:45], s[22:23], 0, v[98:99]
	v_cvt_pk_bf16_f32 v41, v46, v47
	v_cvt_pk_bf16_f32 v42, v42, v43
	v_cvt_pk_bf16_f32 v43, v48, v49
	v_lshl_add_u64 v[44:45], v[168:169], 1, v[44:45]
	global_store_dwordx4 v[44:45], v[40:43], off
	s_waitcnt vmcnt(7)
	v_lshlrev_b32_e32 v46, 16, v226
	v_and_b32_e32 v47, 0xffff0000, v226
	v_lshlrev_b32_e32 v40, 16, v224
	v_and_b32_e32 v41, 0xffff0000, v224
	v_lshlrev_b32_e32 v42, 16, v225
	v_and_b32_e32 v43, 0xffff0000, v225
	v_lshlrev_b32_e32 v48, 16, v227
	v_and_b32_e32 v49, 0xffff0000, v227
	v_pk_add_f32 v[38:39], v[38:39], v[42:43]
	v_pk_add_f32 v[36:37], v[36:37], v[40:41]
	v_pk_add_f32 v[40:41], v[34:35], v[48:49]
	v_pk_add_f32 v[34:35], v[32:33], v[46:47]
	v_mul_f32_e32 v32, v37, v37
	v_mul_f32_e32 v33, v39, v39
	v_fmac_f32_e32 v32, v36, v36
	v_fmac_f32_e32 v33, v38, v38
	v_add_f32_e32 v32, v32, v33
	v_mul_f32_e32 v33, v35, v35
	v_mul_f32_e32 v42, v41, v41
	v_fmac_f32_e32 v33, v34, v34
	v_fmac_f32_e32 v42, v40, v40
	v_add_f32_e32 v33, v33, v42
	v_add_f32_e32 v32, v32, v33
	v_add_f32_e32 v42, v50, v32
	v_cvt_pk_bf16_f32 v32, v36, v37
	v_cvt_pk_bf16_f32 v33, v38, v39
	v_cvt_pk_bf16_f32 v34, v34, v35
	v_cvt_pk_bf16_f32 v35, v40, v41
	global_store_dwordx4 v[44:45], v[32:35], off offset:256
	s_nop 1
	v_mov_b32_e32 v32, v201
	v_mov_b32_e32 v33, v201
	v_lshlrev_b32_e32 v32, 2, v32
	v_xor_b32_e32 v32, 64, v32
	v_mov_b32_e32 v32, v42
	s_nop 1
	v_permlane16_swap_b32_e32 v32, v42
	s_waitcnt lgkmcnt(0)
	v_add_f32_e32 v32, v42, v32
	v_lshlrev_b32_e32 v33, 2, v33
	v_xor_b32_e32 v33, 0x80, v33
	v_mov_b32_e32 v33, v32
	s_nop 1
	v_permlane32_swap_b32_e32 v33, v32
	s_and_saveexec_b64 s[48:49], s[8:9]
	s_cbranch_execz .LBB0_1685
	s_waitcnt lgkmcnt(0)
	v_add_f32_e32 v34, v32, v33
	v_lshlrev_b64 v[32:33], 6, v[96:97]
	v_lshl_add_u64 v[32:33], s[24:25], 0, v[32:33]
	v_lshl_add_u64 v[32:33], s[46:47], 2, v[32:33]
	s_lshl_b32 s18, s54, 2
	v_lshl_add_u64 v[32:33], v[32:33], 0, s[18:19]
	global_store_dword v[32:33], v34, off
; __device__ __forceinline__ float sq4(f32x4 v) { return (v[0] * v[0] + v[1] * v[1]) + (v[2] * v[2] + v[3] * v[3]); }
; __device__ __forceinline__ u32x4 pack8(f32x4 a, f32x4 b) { u32x4 w; w.x = cvt_pk_bf16(a[0], a[1]); w.y = cvt_pk_bf16(a[2], a[3]); w.z = cvt_pk_bf16(b[0], b[1]); w.w = cvt_pk_bf16(b[2], b[3]); return w; }
;     __device__ __forceinline__ void operator()(const f32x4 (&acc)[2][2][4][2], const Unit& u, int wr, int wc, int fr, int fq) const {
;     ...
;         for (int ai = 0; ai < 2; ++ai) {
;             u32x4 bs[4][2];
; #pragma unroll
;             for (int m = 0; m < 4; ++m)
; #pragma unroll
;                 for (int bj = 0; bj < 2; ++bj) bs[m][bj] = *(const u32x4*)(xb + (size_t)(u.pm * BM + ai * HALF + wr * 64 + m * 16 + fr) * 1024 + col0 + 128 * bj);
; #pragma unroll
;             for (int m = 0; m < 4; ++m) {
;                 const int row = u.pm * BM + ai * HALF + wr * 64 + m * 16 + fr;
;                 float q = 0.f;
; #pragma unroll
;                 for (int bj = 0; bj < 2; ++bj) {
;                     const size_t off = (size_t)row * 1024 + col0 + 128 * bj; const u32x4 w = bs[m][bj];
;                     const f32x4 b0 = (f32x4){__builtin_bit_cast(float, w.x << 16), __builtin_bit_cast(float, w.x & 0xffff0000u), __builtin_bit_cast(float, w.y << 16), __builtin_bit_cast(float, w.y & 0xffff0000u)};
;                     const f32x4 b1 = (f32x4){__builtin_bit_cast(float, w.z << 16), __builtin_bit_cast(float, w.z & 0xffff0000u), __builtin_bit_cast(float, w.w << 16), __builtin_bit_cast(float, w.w & 0xffff0000u)};
;                     const f32x4 v0 = acc[ai][bj][m][0] + b0, v1 = acc[ai][bj][m][1] + b1;
;                     if (last) { __builtin_nontemporal_store(v0, (f32x4*)(out + off)); __builtin_nontemporal_store(v1, (f32x4*)(out + off + 4)); }
;                     else { q += sq4(v0) + sq4(v1); *(u32x4*)(xb + off) = pack8(v0, v1); }
;                 }
;                 if (!last) { q += shx(q, 16); q += shx(q, 32); if (fq == 0) ss[(size_t)row * 16 + u.pn * 4 + wc] = q; }
.LBB0_1685:
	s_or_b64 exec, exec, s[48:49]
	s_waitcnt vmcnt(7)
	v_lshlrev_b32_e32 v32, 16, v228
	s_waitcnt lgkmcnt(0)
	v_and_b32_e32 v33, 0xffff0000, v228
	v_lshlrev_b32_e32 v34, 16, v229
	v_and_b32_e32 v35, 0xffff0000, v229
	v_lshlrev_b32_e32 v36, 16, v230
	v_and_b32_e32 v37, 0xffff0000, v230
	v_lshlrev_b32_e32 v38, 16, v231
	v_and_b32_e32 v39, 0xffff0000, v231
	v_pk_add_f32 v[30:31], v[30:31], v[34:35]
	v_pk_add_f32 v[28:29], v[28:29], v[32:33]
	v_pk_add_f32 v[32:33], v[26:27], v[38:39]
	v_pk_add_f32 v[26:27], v[24:25], v[36:37]
	v_mul_f32_e32 v24, v29, v29
	v_mul_f32_e32 v25, v31, v31
	v_fmac_f32_e32 v24, v28, v28
	v_fmac_f32_e32 v25, v30, v30
	v_add_f32_e32 v24, v24, v25
	v_mul_f32_e32 v25, v27, v27
	v_mul_f32_e32 v34, v33, v33
	v_fmac_f32_e32 v25, v26, v26
	v_fmac_f32_e32 v34, v32, v32
	v_add_f32_e32 v25, v25, v34
	v_add_f32_e32 v34, v24, v25
	v_cvt_pk_bf16_f32 v24, v28, v29
	v_lshl_add_u64 v[28:29], s[22:23], 0, v[94:95]
	v_cvt_pk_bf16_f32 v25, v30, v31
	v_cvt_pk_bf16_f32 v26, v26, v27
	v_cvt_pk_bf16_f32 v27, v32, v33
	v_lshl_add_u64 v[28:29], v[168:169], 1, v[28:29]
	global_store_dwordx4 v[28:29], v[24:27], off
	s_waitcnt vmcnt(7)
	v_lshlrev_b32_e32 v30, 16, v234
	v_and_b32_e32 v31, 0xffff0000, v234
	v_lshlrev_b32_e32 v24, 16, v232
	v_and_b32_e32 v25, 0xffff0000, v232
	v_lshlrev_b32_e32 v26, 16, v233
	v_and_b32_e32 v27, 0xffff0000, v233
	v_lshlrev_b32_e32 v32, 16, v235
	v_and_b32_e32 v33, 0xffff0000, v235
	v_pk_add_f32 v[22:23], v[22:23], v[26:27]
	v_pk_add_f32 v[20:21], v[20:21], v[24:25]
	v_pk_add_f32 v[24:25], v[18:19], v[32:33]
	v_pk_add_f32 v[18:19], v[16:17], v[30:31]
	v_mul_f32_e32 v16, v21, v21
	v_mul_f32_e32 v17, v23, v23
	v_fmac_f32_e32 v16, v20, v20
	v_fmac_f32_e32 v17, v22, v22
	v_add_f32_e32 v16, v16, v17
	v_mul_f32_e32 v17, v19, v19
	v_mul_f32_e32 v26, v25, v25
	v_fmac_f32_e32 v17, v18, v18
	v_fmac_f32_e32 v26, v24, v24
	v_add_f32_e32 v17, v17, v26
	v_add_f32_e32 v16, v16, v17
	v_add_f32_e32 v26, v34, v16
	v_cvt_pk_bf16_f32 v16, v20, v21
	v_cvt_pk_bf16_f32 v17, v22, v23
	v_cvt_pk_bf16_f32 v18, v18, v19
	v_cvt_pk_bf16_f32 v19, v24, v25
	global_store_dwordx4 v[28:29], v[16:19], off offset:256
	s_nop 1
	v_mov_b32_e32 v16, v201
	v_mov_b32_e32 v17, v201
	v_lshlrev_b32_e32 v16, 2, v16
	v_xor_b32_e32 v16, 64, v16
	v_mov_b32_e32 v16, v26
	s_nop 1
	v_permlane16_swap_b32_e32 v16, v26
	s_waitcnt lgkmcnt(0)
	v_add_f32_e32 v16, v26, v16
	v_lshlrev_b32_e32 v17, 2, v17
	v_xor_b32_e32 v17, 0x80, v17
	v_mov_b32_e32 v17, v16
	s_nop 1
	v_permlane32_swap_b32_e32 v17, v16
	s_and_saveexec_b64 s[48:49], s[8:9]
	s_cbranch_execz .LBB0_1687
	s_waitcnt lgkmcnt(0)
	v_add_f32_e32 v18, v16, v17
	v_lshlrev_b64 v[16:17], 6, v[92:93]
	v_lshl_add_u64 v[16:17], s[24:25], 0, v[16:17]
	v_lshl_add_u64 v[16:17], s[46:47], 2, v[16:17]
	s_lshl_b32 s18, s54, 2
	v_lshl_add_u64 v[16:17], v[16:17], 0, s[18:19]
	global_store_dword v[16:17], v18, off
.LBB0_1687:
	s_or_b64 exec, exec, s[48:49]
	s_waitcnt vmcnt(7)
	v_lshlrev_b32_e32 v16, 16, v236
	s_waitcnt lgkmcnt(0)
	v_and_b32_e32 v17, 0xffff0000, v236
	v_lshlrev_b32_e32 v18, 16, v237
	v_and_b32_e32 v19, 0xffff0000, v237
	v_lshlrev_b32_e32 v20, 16, v238
	v_and_b32_e32 v21, 0xffff0000, v238
	v_lshlrev_b32_e32 v22, 16, v239
	v_and_b32_e32 v23, 0xffff0000, v239
	v_pk_add_f32 v[14:15], v[14:15], v[18:19]
	v_pk_add_f32 v[12:13], v[12:13], v[16:17]
	v_pk_add_f32 v[16:17], v[10:11], v[22:23]
	v_pk_add_f32 v[10:11], v[8:9], v[20:21]
	v_mul_f32_e32 v8, v13, v13
	v_mul_f32_e32 v9, v15, v15
	v_fmac_f32_e32 v8, v12, v12
	v_fmac_f32_e32 v9, v14, v14
	v_add_f32_e32 v8, v8, v9
	v_mul_f32_e32 v9, v11, v11
	v_mul_f32_e32 v18, v17, v17
	v_fmac_f32_e32 v9, v10, v10
	v_fmac_f32_e32 v18, v16, v16
	v_add_f32_e32 v9, v9, v18
	v_add_f32_e32 v18, v8, v9
	v_cvt_pk_bf16_f32 v8, v12, v13
	v_lshl_add_u64 v[12:13], s[22:23], 0, v[90:91]
	v_cvt_pk_bf16_f32 v9, v14, v15
	v_cvt_pk_bf16_f32 v10, v10, v11
	v_cvt_pk_bf16_f32 v11, v16, v17
	v_lshl_add_u64 v[12:13], v[168:169], 1, v[12:13]
	global_store_dwordx4 v[12:13], v[8:11], off
	s_waitcnt vmcnt(7)
	v_lshlrev_b32_e32 v14, 16, v242
	v_and_b32_e32 v15, 0xffff0000, v242
	v_lshlrev_b32_e32 v8, 16, v240
	v_and_b32_e32 v9, 0xffff0000, v240
	v_lshlrev_b32_e32 v10, 16, v241
	v_and_b32_e32 v11, 0xffff0000, v241
	v_lshlrev_b32_e32 v16, 16, v243
	v_and_b32_e32 v17, 0xffff0000, v243
	v_pk_add_f32 v[6:7], v[6:7], v[10:11]
	v_pk_add_f32 v[4:5], v[4:5], v[8:9]
	v_pk_add_f32 v[8:9], v[2:3], v[16:17]
	v_pk_add_f32 v[2:3], v[0:1], v[14:15]
	v_mul_f32_e32 v0, v5, v5
	v_mul_f32_e32 v1, v7, v7
	v_fmac_f32_e32 v0, v4, v4
	v_fmac_f32_e32 v1, v6, v6
	v_add_f32_e32 v0, v0, v1
	v_mul_f32_e32 v1, v3, v3
	v_mul_f32_e32 v10, v9, v9
	v_fmac_f32_e32 v1, v2, v2
	v_fmac_f32_e32 v10, v8, v8
	v_add_f32_e32 v1, v1, v10
	v_add_f32_e32 v0, v0, v1
	v_add_f32_e32 v10, v18, v0
	v_cvt_pk_bf16_f32 v0, v4, v5
	v_cvt_pk_bf16_f32 v1, v6, v7
	v_cvt_pk_bf16_f32 v2, v2, v3
	v_cvt_pk_bf16_f32 v3, v8, v9
	global_store_dwordx4 v[12:13], v[0:3], off offset:256
	s_nop 1
	v_mov_b32_e32 v0, v201
	v_mov_b32_e32 v1, v201
	v_lshlrev_b32_e32 v0, 2, v0
	v_xor_b32_e32 v0, 64, v0
	v_mov_b32_e32 v0, v10
	s_nop 1
	v_permlane16_swap_b32_e32 v0, v10
	s_waitcnt lgkmcnt(0)
	v_add_f32_e32 v0, v10, v0
	v_lshlrev_b32_e32 v1, 2, v1
	v_xor_b32_e32 v1, 0x80, v1
	v_mov_b32_e32 v1, v0
	s_nop 1
	v_permlane32_swap_b32_e32 v1, v0
	s_and_saveexec_b64 s[48:49], s[8:9]
	s_cbranch_execz .LBB0_1689
	s_waitcnt lgkmcnt(0)
	v_add_f32_e32 v2, v0, v1
	v_lshlrev_b64 v[0:1], 6, v[88:89]
	v_lshl_add_u64 v[0:1], s[24:25], 0, v[0:1]
	v_lshl_add_u64 v[0:1], s[46:47], 2, v[0:1]
	s_lshl_b32 s18, s54, 2
	v_lshl_add_u64 v[0:1], v[0:1], 0, s[18:19]
	global_store_dword v[0:1], v2, off

; __device__ __forceinline__ float sq4(f32x4 v) { return (v[0] * v[0] + v[1] * v[1]) + (v[2] * v[2] + v[3] * v[3]); }
; __device__ __forceinline__ u32x4 pack8(f32x4 a, f32x4 b) { u32x4 w; w.x = cvt_pk_bf16(a[0], a[1]); w.y = cvt_pk_bf16(a[2], a[3]); w.z = cvt_pk_bf16(b[0], b[1]); w.w = cvt_pk_bf16(b[2], b[3]); return w; }
;     __device__ __forceinline__ void operator()(const f32x4 (&acc)[2][2][4][2], const Unit& u, int wr, int wc, int fr, int fq) const {
;         const int col0 = u.pn * 256 + 32 * wc + 8 * fq;
; #pragma unroll
;         for (int ai = 0; ai < 2; ++ai) {
;             u32x4 bs[4][2];
; #pragma unroll
;             for (int m = 0; m < 4; ++m)
; #pragma unroll
;                 for (int bj = 0; bj < 2; ++bj) bs[m][bj] = *(const u32x4*)(xb + (size_t)(u.pm * BM + ai * HALF + wr * 64 + m * 16 + fr) * 1024 + col0 + 128 * bj);
; #pragma unroll
;             for (int m = 0; m < 4; ++m) {
;                 const int row = u.pm * BM + ai * HALF + wr * 64 + m * 16 + fr;
;                 float q = 0.f;
; #pragma unroll
;                 for (int bj = 0; bj < 2; ++bj) {
;                     const size_t off = (size_t)row * 1024 + col0 + 128 * bj; const u32x4 w = bs[m][bj];
;                     const f32x4 b0 = (f32x4){__builtin_bit_cast(float, w.x << 16), __builtin_bit_cast(float, w.x & 0xffff0000u), __builtin_bit_cast(float, w.y << 16), __builtin_bit_cast(float, w.y & 0xffff0000u)};
;                     const f32x4 b1 = (f32x4){__builtin_bit_cast(float, w.z << 16), __builtin_bit_cast(float, w.z & 0xffff0000u), __builtin_bit_cast(float, w.w << 16), __builtin_bit_cast(float, w.w & 0xffff0000u)};
;                     const f32x4 v0 = acc[ai][bj][m][0] + b0, v1 = acc[ai][bj][m][1] + b1;
;                     if (last) { __builtin_nontemporal_store(v0, (f32x4*)(out + off)); __builtin_nontemporal_store(v1, (f32x4*)(out + off + 4)); }
;                     else { q += sq4(v0) + sq4(v1); *(u32x4*)(xb + off) = pack8(v0, v1); }
;                 }
;                 if (!last) { q += shx(q, 16); q += shx(q, 32); if (fq == 0) ss[(size_t)row * 16 + u.pn * 4 + wc] = q; }
.LBB0_1959:
	v_lshl_or_b32 v168, s10, 8, v188
	v_lshl_add_u32 v172, s38, 8, v186
	v_ashrrev_i32_e32 v169, 31, v168
	v_lshlrev_b64 v[202:203], 1, v[168:169]
	v_ashrrev_i32_e32 v173, 31, v172
	v_lshl_add_u64 v[170:171], s[16:17], 0, v[202:203]
	v_lshlrev_b64 v[204:205], 11, v[172:173]
	v_lshl_add_u64 v[128:129], v[170:171], 0, v[204:205]
	global_load_dwordx4 v[192:195], v[128:129], off
	global_load_dwordx4 v[196:199], v[128:129], off offset:256
	v_or_b32_e32 v182, 16, v172
	v_or_b32_e32 v178, 32, v172
	v_or_b32_e32 v174, 48, v172
	v_ashrrev_i32_e32 v183, 31, v182
	v_ashrrev_i32_e32 v179, 31, v178
	v_ashrrev_i32_e32 v175, 31, v174
	v_lshlrev_b64 v[184:185], 11, v[182:183]
	v_lshlrev_b64 v[180:181], 11, v[178:179]
	v_lshlrev_b64 v[176:177], 11, v[174:175]
	v_lshl_add_u64 v[128:129], v[170:171], 0, v[184:185]
	v_lshl_add_u64 v[130:131], v[170:171], 0, v[180:181]
	v_lshl_add_u64 v[206:207], v[170:171], 0, v[176:177]
	global_load_dwordx4 v[148:151], v[128:129], off
	global_load_dwordx4 v[144:147], v[128:129], off offset:256
	global_load_dwordx4 v[140:143], v[130:131], off
	global_load_dwordx4 v[136:139], v[130:131], off offset:256
	global_load_dwordx4 v[132:135], v[206:207], off
	s_nop 0
	global_load_dwordx4 v[128:131], v[206:207], off offset:256
	v_add_u32_e32 v244, 0x80, v172
	v_ashrrev_i32_e32 v245, 31, v244
	v_lshlrev_b64 v[244:245], 11, v[244:245]
	v_lshl_add_u64 v[244:245], v[170:171], 0, v[244:245]
	global_load_dwordx4 v[212:215], v[244:245], off
	global_load_dwordx4 v[216:219], v[244:245], off offset:256
	v_add_u32_e32 v244, 0x90, v172
	v_ashrrev_i32_e32 v245, 31, v244
	v_lshlrev_b64 v[244:245], 11, v[244:245]
	v_lshl_add_u64 v[244:245], v[170:171], 0, v[244:245]
	global_load_dwordx4 v[220:223], v[244:245], off
	global_load_dwordx4 v[224:227], v[244:245], off offset:256
	v_add_u32_e32 v244, 0xa0, v172
	v_ashrrev_i32_e32 v245, 31, v244
	v_lshlrev_b64 v[244:245], 11, v[244:245]
	v_lshl_add_u64 v[244:245], v[170:171], 0, v[244:245]
	global_load_dwordx4 v[228:231], v[244:245], off
	global_load_dwordx4 v[232:235], v[244:245], off offset:256
	v_add_u32_e32 v244, 0xb0, v172
	v_ashrrev_i32_e32 v245, 31, v244
	v_lshlrev_b64 v[244:245], 11, v[244:245]
	v_lshl_add_u64 v[244:245], v[170:171], 0, v[244:245]
	global_load_dwordx4 v[236:239], v[244:245], off
	global_load_dwordx4 v[240:243], v[244:245], off offset:256
	v_lshl_add_u64 v[204:205], s[16:17], 0, v[204:205]
	v_lshl_add_u64 v[202:203], v[204:205], 0, v[202:203]
	v_mov_b32_e32 v200, v201
	s_lshl_b32 s38, s10, 2
	s_ashr_i32 s39, s38, 31
	s_waitcnt vmcnt(8)
	v_lshlrev_b32_e32 v204, 16, v192
	v_and_b32_e32 v205, 0xffff0000, v192
	v_lshlrev_b32_e32 v192, 16, v193
	v_and_b32_e32 v193, 0xffff0000, v193
	v_lshlrev_b32_e32 v206, 16, v194
	v_and_b32_e32 v207, 0xffff0000, v194
	v_lshlrev_b32_e32 v194, 16, v195
	v_and_b32_e32 v195, 0xffff0000, v195
	v_lshlrev_b32_e32 v208, 16, v196
	v_and_b32_e32 v209, 0xffff0000, v196
	v_lshlrev_b32_e32 v196, 16, v197
	v_and_b32_e32 v197, 0xffff0000, v197
	v_lshlrev_b32_e32 v210, 16, v198
	v_and_b32_e32 v211, 0xffff0000, v198
	v_lshlrev_b32_e32 v198, 16, v199
	v_and_b32_e32 v199, 0xffff0000, v199
	v_pk_add_f32 v[126:127], v[126:127], v[192:193]
	v_pk_add_f32 v[124:125], v[124:125], v[204:205]
	v_pk_add_f32 v[122:123], v[122:123], v[194:195]
	v_pk_add_f32 v[120:121], v[120:121], v[206:207]
	v_pk_add_f32 v[118:119], v[118:119], v[196:197]
	v_pk_add_f32 v[116:117], v[116:117], v[208:209]
	v_pk_add_f32 v[192:193], v[114:115], v[198:199]
	v_pk_add_f32 v[194:195], v[112:113], v[210:211]
	v_mul_f32_e32 v196, v125, v125
	v_mul_f32_e32 v197, v127, v127
	v_mul_f32_e32 v198, v121, v121
	v_mul_f32_e32 v199, v123, v123
	v_cvt_pk_bf16_f32 v112, v124, v125
	v_cvt_pk_bf16_f32 v113, v126, v127
	v_cvt_pk_bf16_f32 v114, v120, v121
	v_cvt_pk_bf16_f32 v115, v122, v123
	v_mul_f32_e32 v121, v117, v117
	v_mul_f32_e32 v123, v119, v119
	v_mul_f32_e32 v125, v195, v195
	v_mul_f32_e32 v127, v193, v193
	v_fmac_f32_e32 v196, v124, v124
	v_fmac_f32_e32 v197, v126, v126
	v_fmac_f32_e32 v198, v120, v120
	v_fmac_f32_e32 v199, v122, v122
	v_fmac_f32_e32 v121, v116, v116
	v_fmac_f32_e32 v123, v118, v118
	v_fmac_f32_e32 v125, v194, v194
	v_fmac_f32_e32 v127, v192, v192
	global_store_dwordx4 v[202:203], v[112:115], off
	s_nop 1
	v_cvt_pk_bf16_f32 v112, v116, v117
	v_cvt_pk_bf16_f32 v113, v118, v119
	v_cvt_pk_bf16_f32 v114, v194, v195
	v_add_f32_e32 v116, v196, v197
	v_add_f32_e32 v117, v198, v199
	v_add_f32_e32 v118, v121, v123
	v_add_f32_e32 v119, v125, v127
	v_cvt_pk_bf16_f32 v115, v192, v193
	global_store_dwordx4 v[202:203], v[112:115], off offset:256
	s_nop 1
	v_add_f32_e32 v112, v116, v117
	v_add_f32_e32 v113, v118, v119
	v_lshlrev_b32_e32 v114, 2, v200
	v_add_f32_e32 v112, v112, v113
	v_xor_b32_e32 v113, 64, v114
	v_mov_b32_e32 v113, v112
	s_nop 1
	v_permlane16_swap_b32_e32 v113, v112
	v_mov_b32_e32 v114, v201
	s_waitcnt lgkmcnt(0)
	v_add_f32_e32 v112, v112, v113
	v_lshlrev_b32_e32 v114, 2, v114
	v_xor_b32_e32 v113, 0x80, v114
	v_mov_b32_e32 v113, v112
	s_nop 1
	v_permlane32_swap_b32_e32 v113, v112
	s_and_saveexec_b64 s[40:41], s[6:7]
	s_cbranch_execz .LBB0_1961
	s_waitcnt lgkmcnt(0)
	v_add_f32_e32 v114, v112, v113
	v_lshlrev_b64 v[112:113], 6, v[172:173]
	v_lshl_add_u64 v[112:113], s[18:19], 0, v[112:113]
	v_lshl_add_u64 v[112:113], s[38:39], 2, v[112:113]
	s_lshl_b32 s10, s33, 2
	v_lshl_add_u64 v[112:113], v[112:113], 0, s[10:11]
	global_store_dword v[112:113], v114, off

; __device__ __forceinline__ float sq4(f32x4 v) { return (v[0] * v[0] + v[1] * v[1]) + (v[2] * v[2] + v[3] * v[3]); }
; __device__ __forceinline__ u32x4 pack8(f32x4 a, f32x4 b) { u32x4 w; w.x = cvt_pk_bf16(a[0], a[1]); w.y = cvt_pk_bf16(a[2], a[3]); w.z = cvt_pk_bf16(b[0], b[1]); w.w = cvt_pk_bf16(b[2], b[3]); return w; }
;     __device__ __forceinline__ void operator()(const f32x4 (&acc)[2][2][4][2], const Unit& u, int wr, int wc, int fr, int fq) const {
;     ...
;         for (int ai = 0; ai < 2; ++ai) {
;             u32x4 bs[4][2];
; #pragma unroll
;             for (int m = 0; m < 4; ++m)
; #pragma unroll
;                 for (int bj = 0; bj < 2; ++bj) bs[m][bj] = *(const u32x4*)(xb + (size_t)(u.pm * BM + ai * HALF + wr * 64 + m * 16 + fr) * 1024 + col0 + 128 * bj);
; #pragma unroll
;             for (int m = 0; m < 4; ++m) {
;                 const int row = u.pm * BM + ai * HALF + wr * 64 + m * 16 + fr;
;                 float q = 0.f;
; #pragma unroll
;                 for (int bj = 0; bj < 2; ++bj) {
;                     const size_t off = (size_t)row * 1024 + col0 + 128 * bj; const u32x4 w = bs[m][bj];
;                     const f32x4 b0 = (f32x4){__builtin_bit_cast(float, w.x << 16), __builtin_bit_cast(float, w.x & 0xffff0000u), __builtin_bit_cast(float, w.y << 16), __builtin_bit_cast(float, w.y & 0xffff0000u)};
;                     const f32x4 b1 = (f32x4){__builtin_bit_cast(float, w.z << 16), __builtin_bit_cast(float, w.z & 0xffff0000u), __builtin_bit_cast(float, w.w << 16), __builtin_bit_cast(float, w.w & 0xffff0000u)};
;                     const f32x4 v0 = acc[ai][bj][m][0] + b0, v1 = acc[ai][bj][m][1] + b1;
;                     if (last) { __builtin_nontemporal_store(v0, (f32x4*)(out + off)); __builtin_nontemporal_store(v1, (f32x4*)(out + off + 4)); }
;                     else { q += sq4(v0) + sq4(v1); *(u32x4*)(xb + off) = pack8(v0, v1); }
;                 }
;                 if (!last) { q += shx(q, 16); q += shx(q, 32); if (fq == 0) ss[(size_t)row * 16 + u.pn * 4 + wc] = q; }
.LBB0_1967:
	s_or_b64 exec, exec, s[40:41]
	v_add_u32_e32 v100, 0x80, v172
	v_ashrrev_i32_e32 v101, 31, v100
	v_lshlrev_b64 v[110:111], 11, v[100:101]
	s_waitcnt lgkmcnt(0)
	v_lshl_add_u64 v[64:65], v[170:171], 0, v[110:111]
	s_nop 0
	s_nop 0
	v_add_u32_e32 v96, 0x90, v172
	v_add_u32_e32 v92, 0xa0, v172
	v_add_u32_e32 v88, 0xb0, v172
	v_ashrrev_i32_e32 v97, 31, v96
	v_ashrrev_i32_e32 v93, 31, v92
	v_ashrrev_i32_e32 v89, 31, v88
	v_lshlrev_b64 v[98:99], 11, v[96:97]
	v_lshlrev_b64 v[94:95], 11, v[92:93]
	v_lshlrev_b64 v[90:91], 11, v[88:89]
	v_lshl_add_u64 v[64:65], v[170:171], 0, v[98:99]
	v_lshl_add_u64 v[66:67], v[170:171], 0, v[94:95]
	v_lshl_add_u64 v[112:113], v[170:171], 0, v[90:91]
	s_nop 0
	s_nop 0
	s_nop 0
	s_nop 0
	s_nop 0
	s_nop 0
	s_nop 0
	v_lshl_add_u64 v[110:111], s[16:17], 0, v[110:111]
	v_lshl_add_u64 v[110:111], v[168:169], 1, v[110:111]
	v_mov_b32_e32 v120, v201
	s_waitcnt vmcnt(7)
	v_lshlrev_b32_e32 v112, 16, v212
	v_and_b32_e32 v113, 0xffff0000, v212
	v_lshlrev_b32_e32 v102, 16, v213
	v_and_b32_e32 v103, 0xffff0000, v213
	v_lshlrev_b32_e32 v114, 16, v214
	v_and_b32_e32 v115, 0xffff0000, v214
	v_lshlrev_b32_e32 v104, 16, v215
	v_and_b32_e32 v105, 0xffff0000, v215
	s_waitcnt vmcnt(6)
	v_lshlrev_b32_e32 v116, 16, v216
	v_and_b32_e32 v117, 0xffff0000, v216
	v_lshlrev_b32_e32 v106, 16, v217
	v_and_b32_e32 v107, 0xffff0000, v217
	v_lshlrev_b32_e32 v118, 16, v218
	v_and_b32_e32 v119, 0xffff0000, v218
	v_lshlrev_b32_e32 v108, 16, v219
	v_and_b32_e32 v109, 0xffff0000, v219
	v_pk_add_f32 v[62:63], v[62:63], v[102:103]
	v_pk_add_f32 v[60:61], v[60:61], v[112:113]
	v_pk_add_f32 v[58:59], v[58:59], v[104:105]
	v_pk_add_f32 v[56:57], v[56:57], v[114:115]
	v_pk_add_f32 v[54:55], v[54:55], v[106:107]
	v_pk_add_f32 v[52:53], v[52:53], v[116:117]
	v_pk_add_f32 v[102:103], v[50:51], v[108:109]
	v_pk_add_f32 v[104:105], v[48:49], v[118:119]
	v_mul_f32_e32 v106, v61, v61
	v_mul_f32_e32 v107, v63, v63
	v_mul_f32_e32 v108, v57, v57
	v_mul_f32_e32 v109, v59, v59
	v_cvt_pk_bf16_f32 v48, v60, v61
	v_cvt_pk_bf16_f32 v49, v62, v63
	v_cvt_pk_bf16_f32 v50, v56, v57
	v_cvt_pk_bf16_f32 v51, v58, v59
	v_mul_f32_e32 v57, v53, v53
	v_mul_f32_e32 v59, v55, v55
	v_mul_f32_e32 v61, v105, v105
	v_mul_f32_e32 v63, v103, v103
	v_fmac_f32_e32 v106, v60, v60
	v_fmac_f32_e32 v107, v62, v62
	v_fmac_f32_e32 v108, v56, v56
	v_fmac_f32_e32 v109, v58, v58
	v_fmac_f32_e32 v57, v52, v52
	v_fmac_f32_e32 v59, v54, v54
	v_fmac_f32_e32 v61, v104, v104
	v_fmac_f32_e32 v63, v102, v102
	global_store_dwordx4 v[110:111], v[48:51], off
	s_nop 1
	v_cvt_pk_bf16_f32 v48, v52, v53
	v_cvt_pk_bf16_f32 v49, v54, v55
	v_cvt_pk_bf16_f32 v50, v104, v105
	v_add_f32_e32 v52, v106, v107
	v_add_f32_e32 v53, v108, v109
	v_add_f32_e32 v54, v57, v59
	v_add_f32_e32 v55, v61, v63
	v_cvt_pk_bf16_f32 v51, v102, v103
	global_store_dwordx4 v[110:111], v[48:51], off offset:256
	s_nop 1
	v_add_f32_e32 v48, v52, v53
	v_add_f32_e32 v49, v54, v55
	v_lshlrev_b32_e32 v50, 2, v120
	v_add_f32_e32 v48, v48, v49
	v_xor_b32_e32 v49, 64, v50
	v_mov_b32_e32 v49, v48
	s_nop 1
	v_permlane16_swap_b32_e32 v49, v48
	v_mov_b32_e32 v50, v201
	s_waitcnt lgkmcnt(0)
	v_add_f32_e32 v48, v48, v49
	v_lshlrev_b32_e32 v50, 2, v50
	v_xor_b32_e32 v49, 0x80, v50
	v_mov_b32_e32 v49, v48
	s_nop 1
	v_permlane32_swap_b32_e32 v49, v48
	s_and_saveexec_b64 s[40:41], s[6:7]
	s_cbranch_execz .LBB0_1969
	s_waitcnt lgkmcnt(0)
	v_add_f32_e32 v50, v48, v49
	v_lshlrev_b64 v[48:49], 6, v[100:101]
	v_lshl_add_u64 v[48:49], s[18:19], 0, v[48:49]
	v_lshl_add_u64 v[48:49], s[38:39], 2, v[48:49]
	s_lshl_b32 s10, s33, 2
	v_lshl_add_u64 v[48:49], v[48:49], 0, s[10:11]
	global_store_dword v[48:49], v50, off
.LBB0_1969:
	s_or_b64 exec, exec, s[40:41]
	s_waitcnt vmcnt(7)
	v_lshlrev_b32_e32 v48, 16, v220
	s_waitcnt lgkmcnt(0)
	v_and_b32_e32 v49, 0xffff0000, v220
	v_lshlrev_b32_e32 v50, 16, v221
	v_and_b32_e32 v51, 0xffff0000, v221
	v_lshlrev_b32_e32 v52, 16, v222
	v_and_b32_e32 v53, 0xffff0000, v222
	v_lshlrev_b32_e32 v54, 16, v223
	v_and_b32_e32 v55, 0xffff0000, v223
	v_pk_add_f32 v[46:47], v[46:47], v[50:51]
	v_pk_add_f32 v[44:45], v[44:45], v[48:49]
	v_pk_add_f32 v[48:49], v[42:43], v[54:55]
	v_pk_add_f32 v[42:43], v[40:41], v[52:53]
	v_mul_f32_e32 v40, v45, v45
	v_mul_f32_e32 v41, v47, v47
	v_fmac_f32_e32 v40, v44, v44
	v_fmac_f32_e32 v41, v46, v46
	v_add_f32_e32 v40, v40, v41
	v_mul_f32_e32 v41, v43, v43
	v_mul_f32_e32 v50, v49, v49
	v_fmac_f32_e32 v41, v42, v42
	v_fmac_f32_e32 v50, v48, v48
	v_add_f32_e32 v41, v41, v50
	v_add_f32_e32 v50, v40, v41
	v_cvt_pk_bf16_f32 v40, v44, v45
	v_lshl_add_u64 v[44:45], s[16:17], 0, v[98:99]
	v_cvt_pk_bf16_f32 v41, v46, v47
	v_cvt_pk_bf16_f32 v42, v42, v43
	v_cvt_pk_bf16_f32 v43, v48, v49
	v_lshl_add_u64 v[44:45], v[168:169], 1, v[44:45]
	global_store_dwordx4 v[44:45], v[40:43], off
	s_waitcnt vmcnt(7)
	v_lshlrev_b32_e32 v46, 16, v226
	v_and_b32_e32 v47, 0xffff0000, v226
	v_lshlrev_b32_e32 v40, 16, v224
	v_and_b32_e32 v41, 0xffff0000, v224
	v_lshlrev_b32_e32 v42, 16, v225
	v_and_b32_e32 v43, 0xffff0000, v225
	v_lshlrev_b32_e32 v48, 16, v227
	v_and_b32_e32 v49, 0xffff0000, v227
	v_pk_add_f32 v[38:39], v[38:39], v[42:43]
	v_pk_add_f32 v[36:37], v[36:37], v[40:41]
	v_pk_add_f32 v[40:41], v[34:35], v[48:49]
	v_pk_add_f32 v[34:35], v[32:33], v[46:47]
	v_mul_f32_e32 v32, v37, v37
	v_mul_f32_e32 v33, v39, v39
	v_fmac_f32_e32 v32, v36, v36
	v_fmac_f32_e32 v33, v38, v38
	v_add_f32_e32 v32, v32, v33
	v_mul_f32_e32 v33, v35, v35
	v_mul_f32_e32 v42, v41, v41
	v_fmac_f32_e32 v33, v34, v34
	v_fmac_f32_e32 v42, v40, v40
	v_add_f32_e32 v33, v33, v42
	v_add_f32_e32 v32, v32, v33
	v_add_f32_e32 v42, v50, v32
	v_cvt_pk_bf16_f32 v32, v36, v37
	v_cvt_pk_bf16_f32 v33, v38, v39
	v_cvt_pk_bf16_f32 v34, v34, v35
	v_cvt_pk_bf16_f32 v35, v40, v41
	global_store_dwordx4 v[44:45], v[32:35], off offset:256
	s_nop 1
	v_mov_b32_e32 v32, v201
	v_mov_b32_e32 v33, v201
	v_lshlrev_b32_e32 v32, 2, v32
	v_xor_b32_e32 v32, 64, v32
	v_mov_b32_e32 v32, v42
	s_nop 1
	v_permlane16_swap_b32_e32 v32, v42
	s_waitcnt lgkmcnt(0)
	v_add_f32_e32 v32, v42, v32
	v_lshlrev_b32_e32 v33, 2, v33
	v_xor_b32_e32 v33, 0x80, v33
	v_mov_b32_e32 v33, v32
	s_nop 1
	v_permlane32_swap_b32_e32 v33, v32
	s_and_saveexec_b64 s[40:41], s[6:7]
	s_cbranch_execz .LBB0_1971
	s_waitcnt lgkmcnt(0)
	v_add_f32_e32 v34, v32, v33
	v_lshlrev_b64 v[32:33], 6, v[96:97]
	v_lshl_add_u64 v[32:33], s[18:19], 0, v[32:33]
	v_lshl_add_u64 v[32:33], s[38:39], 2, v[32:33]
	s_lshl_b32 s10, s33, 2
	v_lshl_add_u64 v[32:33], v[32:33], 0, s[10:11]
	global_store_dword v[32:33], v34, off
; __device__ __forceinline__ float sq4(f32x4 v) { return (v[0] * v[0] + v[1] * v[1]) + (v[2] * v[2] + v[3] * v[3]); }
; __device__ __forceinline__ u32x4 pack8(f32x4 a, f32x4 b) { u32x4 w; w.x = cvt_pk_bf16(a[0], a[1]); w.y = cvt_pk_bf16(a[2], a[3]); w.z = cvt_pk_bf16(b[0], b[1]); w.w = cvt_pk_bf16(b[2], b[3]); return w; }
;     __device__ __forceinline__ void operator()(const f32x4 (&acc)[2][2][4][2], const Unit& u, int wr, int wc, int fr, int fq) const {
;     ...
;         for (int ai = 0; ai < 2; ++ai) {
;             u32x4 bs[4][2];
; #pragma unroll
;             for (int m = 0; m < 4; ++m)
; #pragma unroll
;                 for (int bj = 0; bj < 2; ++bj) bs[m][bj] = *(const u32x4*)(xb + (size_t)(u.pm * BM + ai * HALF + wr * 64 + m * 16 + fr) * 1024 + col0 + 128 * bj);
; #pragma unroll
;             for (int m = 0; m < 4; ++m) {
;                 const int row = u.pm * BM + ai * HALF + wr * 64 + m * 16 + fr;
;                 float q = 0.f;
; #pragma unroll
;                 for (int bj = 0; bj < 2; ++bj) {
;                     const size_t off = (size_t)row * 1024 + col0 + 128 * bj; const u32x4 w = bs[m][bj];
;                     const f32x4 b0 = (f32x4){__builtin_bit_cast(float, w.x << 16), __builtin_bit_cast(float, w.x & 0xffff0000u), __builtin_bit_cast(float, w.y << 16), __builtin_bit_cast(float, w.y & 0xffff0000u)};
;                     const f32x4 b1 = (f32x4){__builtin_bit_cast(float, w.z << 16), __builtin_bit_cast(float, w.z & 0xffff0000u), __builtin_bit_cast(float, w.w << 16), __builtin_bit_cast(float, w.w & 0xffff0000u)};
;                     const f32x4 v0 = acc[ai][bj][m][0] + b0, v1 = acc[ai][bj][m][1] + b1;
;                     if (last) { __builtin_nontemporal_store(v0, (f32x4*)(out + off)); __builtin_nontemporal_store(v1, (f32x4*)(out + off + 4)); }
;                     else { q += sq4(v0) + sq4(v1); *(u32x4*)(xb + off) = pack8(v0, v1); }
;                 }
;                 if (!last) { q += shx(q, 16); q += shx(q, 32); if (fq == 0) ss[(size_t)row * 16 + u.pn * 4 + wc] = q; }
.LBB0_1971:
	s_or_b64 exec, exec, s[40:41]
	s_waitcnt vmcnt(7)
	v_lshlrev_b32_e32 v32, 16, v228
	s_waitcnt lgkmcnt(0)
	v_and_b32_e32 v33, 0xffff0000, v228
	v_lshlrev_b32_e32 v34, 16, v229
	v_and_b32_e32 v35, 0xffff0000, v229
	v_lshlrev_b32_e32 v36, 16, v230
	v_and_b32_e32 v37, 0xffff0000, v230
	v_lshlrev_b32_e32 v38, 16, v231
	v_and_b32_e32 v39, 0xffff0000, v231
	v_pk_add_f32 v[30:31], v[30:31], v[34:35]
	v_pk_add_f32 v[28:29], v[28:29], v[32:33]
	v_pk_add_f32 v[32:33], v[26:27], v[38:39]
	v_pk_add_f32 v[26:27], v[24:25], v[36:37]
	v_mul_f32_e32 v24, v29, v29
	v_mul_f32_e32 v25, v31, v31
	v_fmac_f32_e32 v24, v28, v28
	v_fmac_f32_e32 v25, v30, v30
	v_add_f32_e32 v24, v24, v25
	v_mul_f32_e32 v25, v27, v27
	v_mul_f32_e32 v34, v33, v33
	v_fmac_f32_e32 v25, v26, v26
	v_fmac_f32_e32 v34, v32, v32
	v_add_f32_e32 v25, v25, v34
	v_add_f32_e32 v34, v24, v25
	v_cvt_pk_bf16_f32 v24, v28, v29
	v_lshl_add_u64 v[28:29], s[16:17], 0, v[94:95]
	v_cvt_pk_bf16_f32 v25, v30, v31
	v_cvt_pk_bf16_f32 v26, v26, v27
	v_cvt_pk_bf16_f32 v27, v32, v33
	v_lshl_add_u64 v[28:29], v[168:169], 1, v[28:29]
	global_store_dwordx4 v[28:29], v[24:27], off
	s_waitcnt vmcnt(7)
	v_lshlrev_b32_e32 v30, 16, v234
	v_and_b32_e32 v31, 0xffff0000, v234
	v_lshlrev_b32_e32 v24, 16, v232
	v_and_b32_e32 v25, 0xffff0000, v232
	v_lshlrev_b32_e32 v26, 16, v233
	v_and_b32_e32 v27, 0xffff0000, v233
	v_lshlrev_b32_e32 v32, 16, v235
	v_and_b32_e32 v33, 0xffff0000, v235
	v_pk_add_f32 v[22:23], v[22:23], v[26:27]
	v_pk_add_f32 v[20:21], v[20:21], v[24:25]
	v_pk_add_f32 v[24:25], v[18:19], v[32:33]
	v_pk_add_f32 v[18:19], v[16:17], v[30:31]
	v_mul_f32_e32 v16, v21, v21
	v_mul_f32_e32 v17, v23, v23
	v_fmac_f32_e32 v16, v20, v20
	v_fmac_f32_e32 v17, v22, v22
	v_add_f32_e32 v16, v16, v17
	v_mul_f32_e32 v17, v19, v19
	v_mul_f32_e32 v26, v25, v25
	v_fmac_f32_e32 v17, v18, v18
	v_fmac_f32_e32 v26, v24, v24
	v_add_f32_e32 v17, v17, v26
	v_add_f32_e32 v16, v16, v17
	v_add_f32_e32 v26, v34, v16
	v_cvt_pk_bf16_f32 v16, v20, v21
	v_cvt_pk_bf16_f32 v17, v22, v23
	v_cvt_pk_bf16_f32 v18, v18, v19
	v_cvt_pk_bf16_f32 v19, v24, v25
	global_store_dwordx4 v[28:29], v[16:19], off offset:256
	s_nop 1
	v_mov_b32_e32 v16, v201
	v_mov_b32_e32 v17, v201
	v_lshlrev_b32_e32 v16, 2, v16
	v_xor_b32_e32 v16, 64, v16
	v_mov_b32_e32 v16, v26
	s_nop 1
	v_permlane16_swap_b32_e32 v16, v26
	s_waitcnt lgkmcnt(0)
	v_add_f32_e32 v16, v26, v16
	v_lshlrev_b32_e32 v17, 2, v17
	v_xor_b32_e32 v17, 0x80, v17
	v_mov_b32_e32 v17, v16
	s_nop 1
	v_permlane32_swap_b32_e32 v17, v16
	s_and_saveexec_b64 s[40:41], s[6:7]
	s_cbranch_execz .LBB0_1973
	s_waitcnt lgkmcnt(0)
	v_add_f32_e32 v18, v16, v17
	v_lshlrev_b64 v[16:17], 6, v[92:93]
	v_lshl_add_u64 v[16:17], s[18:19], 0, v[16:17]
	v_lshl_add_u64 v[16:17], s[38:39], 2, v[16:17]
	s_lshl_b32 s10, s33, 2
	v_lshl_add_u64 v[16:17], v[16:17], 0, s[10:11]
	global_store_dword v[16:17], v18, off
.LBB0_1973:
	s_or_b64 exec, exec, s[40:41]
	s_waitcnt vmcnt(7)
	v_lshlrev_b32_e32 v16, 16, v236
	s_waitcnt lgkmcnt(0)
	v_and_b32_e32 v17, 0xffff0000, v236
	v_lshlrev_b32_e32 v18, 16, v237
	v_and_b32_e32 v19, 0xffff0000, v237
	v_lshlrev_b32_e32 v20, 16, v238
	v_and_b32_e32 v21, 0xffff0000, v238
	v_lshlrev_b32_e32 v22, 16, v239
	v_and_b32_e32 v23, 0xffff0000, v239
	v_pk_add_f32 v[14:15], v[14:15], v[18:19]
	v_pk_add_f32 v[12:13], v[12:13], v[16:17]
	v_pk_add_f32 v[16:17], v[10:11], v[22:23]
	v_pk_add_f32 v[10:11], v[8:9], v[20:21]
	v_mul_f32_e32 v8, v13, v13
	v_mul_f32_e32 v9, v15, v15
	v_fmac_f32_e32 v8, v12, v12
	v_fmac_f32_e32 v9, v14, v14
	v_add_f32_e32 v8, v8, v9
	v_mul_f32_e32 v9, v11, v11
	v_mul_f32_e32 v18, v17, v17
	v_fmac_f32_e32 v9, v10, v10
	v_fmac_f32_e32 v18, v16, v16
	v_add_f32_e32 v9, v9, v18
	v_add_f32_e32 v18, v8, v9
	v_cvt_pk_bf16_f32 v8, v12, v13
	v_lshl_add_u64 v[12:13], s[16:17], 0, v[90:91]
	v_cvt_pk_bf16_f32 v9, v14, v15
	v_cvt_pk_bf16_f32 v10, v10, v11
	v_cvt_pk_bf16_f32 v11, v16, v17
	v_lshl_add_u64 v[12:13], v[168:169], 1, v[12:13]
	global_store_dwordx4 v[12:13], v[8:11], off
	s_waitcnt vmcnt(7)
	v_lshlrev_b32_e32 v14, 16, v242
	v_and_b32_e32 v15, 0xffff0000, v242
	v_lshlrev_b32_e32 v8, 16, v240
	v_and_b32_e32 v9, 0xffff0000, v240
	v_lshlrev_b32_e32 v10, 16, v241
	v_and_b32_e32 v11, 0xffff0000, v241
	v_lshlrev_b32_e32 v16, 16, v243
	v_and_b32_e32 v17, 0xffff0000, v243
	v_pk_add_f32 v[6:7], v[6:7], v[10:11]
	v_pk_add_f32 v[4:5], v[4:5], v[8:9]
	v_pk_add_f32 v[8:9], v[2:3], v[16:17]
	v_pk_add_f32 v[2:3], v[0:1], v[14:15]
	v_mul_f32_e32 v0, v5, v5
	v_mul_f32_e32 v1, v7, v7
	v_fmac_f32_e32 v0, v4, v4
	v_fmac_f32_e32 v1, v6, v6
	v_add_f32_e32 v0, v0, v1
	v_mul_f32_e32 v1, v3, v3
	v_mul_f32_e32 v10, v9, v9
	v_fmac_f32_e32 v1, v2, v2
	v_fmac_f32_e32 v10, v8, v8
	v_add_f32_e32 v1, v1, v10
	v_add_f32_e32 v0, v0, v1
	v_add_f32_e32 v10, v18, v0
	v_cvt_pk_bf16_f32 v0, v4, v5
	v_cvt_pk_bf16_f32 v1, v6, v7
	v_cvt_pk_bf16_f32 v2, v2, v3
	v_cvt_pk_bf16_f32 v3, v8, v9
	global_store_dwordx4 v[12:13], v[0:3], off offset:256
	s_nop 1
	v_mov_b32_e32 v0, v201
	v_mov_b32_e32 v1, v201
	v_lshlrev_b32_e32 v0, 2, v0
	v_xor_b32_e32 v0, 64, v0
	v_mov_b32_e32 v0, v10
	s_nop 1
	v_permlane16_swap_b32_e32 v0, v10
	s_waitcnt lgkmcnt(0)
	v_add_f32_e32 v0, v10, v0
	v_lshlrev_b32_e32 v1, 2, v1
	v_xor_b32_e32 v1, 0x80, v1
	v_mov_b32_e32 v1, v0
	s_nop 1
	v_permlane32_swap_b32_e32 v1, v0
	s_and_saveexec_b64 s[40:41], s[6:7]
	s_cbranch_execz .LBB0_1975
	s_waitcnt lgkmcnt(0)
	v_add_f32_e32 v2, v0, v1
	v_lshlrev_b64 v[0:1], 6, v[88:89]
	v_lshl_add_u64 v[0:1], s[18:19], 0, v[0:1]
	v_lshl_add_u64 v[0:1], s[38:39], 2, v[0:1]
	s_lshl_b32 s10, s33, 2
	v_lshl_add_u64 v[0:1], v[0:1], 0, s[10:11]
	global_store_dword v[0:1], v2, off
